# K-loops: dropped the setprio 0/1 flip between the two MFMA groups of a block and the satisfied lgkmcnt(0) after the barrier
# speedup vs baseline: 1.0010x; 1.0010x over previous
; #define PG8_STAGE(bufoff, gbase, voff) do { _Pragma("unroll") for (int _i = 0; _i < 2; ++_i) \
;         __builtin_amdgcn_global_load_lds((const unsigned*)((const char*)(gbase) + (voff)[_i]), (PG8_LAS unsigned*)(lds + (bufoff) + ldsw + _i * 8192), 16, 0, 0); } while (0)
; #define PG8_LDA(dst, b, h) do { _Pragma("unroll") for (int m = 0; m < 4; ++m) _Pragma("unroll") for (int k = 0; k < 2; ++k) dst[m][k] = *(const PG8_LAS bf16x8*)(lds + PG8_SA(b, h) + aoff + m * 2048 + k * 1024); } while (0)
; #define PG8_LDB(dst, b, h) do { _Pragma("unroll") for (int n = 0; n < 2; ++n) _Pragma("unroll") for (int k = 0; k < 2; ++k) dst[n][k] = *(const PG8_LAS bf16x8*)(lds + PG8_SB(b, h) + boff + n * 2048 + k * 1024); } while (0)
; #define PG8_MMA(ai, bj, At, Bt) do { __builtin_amdgcn_s_setprio(1); _Pragma("unroll") for (int m = 0; m < 4; ++m) _Pragma("unroll") for (int n = 0; n < 2; ++n) _Pragma("unroll") for (int k = 0; k < 2; ++k) \
;         acc[ai][bj][m][n] = __builtin_amdgcn_mfma_f32_16x16x32_bf16(Bt[n][k], At[m][k], acc[ai][bj][m][n], 0, 0, 0); __builtin_amdgcn_s_setprio(0); } while (0)
; #define PG8_WAIT_V(n) asm volatile("s_waitcnt vmcnt(" #n ")" ::: "memory")
; #define PG8_BAR __builtin_amdgcn_s_barrier()
; template <class Epi, class Sched, bool ALIGN_EPI = false, bool SP2 = false>
; __device__ __forceinline__ void gemm_phase(PG8_LAS unsigned char* lds, const Gemm g, const Sched& S, const Epi& E) {
;     ...
;         for (int t = 0; t < nt; t += 2) {
;             const bool last = (t == nt - 2);
;             const char* a1 = cA + (size_t)(t + 1) * kstep;
;             const char* a2 = last ? nA : cA + (size_t)(t + 2) * kstep; const char* b2 = last ? nB : cB + (size_t)(t + 2) * kstep;
;             const char* a3 = a2 + kstep; const char* b3 = b2 + kstep;
;             if (last && has_next) S.a_ready(nxt);
;             if constexpr (SP2) {
;             PG8_LDB(B0, 0, 0); PG8_LDB(B1, 0, 1); PG8_SCHED; PG8_LDA(At, 0, 0); PG8_STAGE(PG8_SA(1, 1), a1 + hstep, voffA);
;             PG8_WAIT_V(8); PG8_WAIT_L(0); PG8_BAR; PG8_MMA(0, 0, At, B0); PG8_MMA(0, 1, At, B1); PG8_BAR; PG8_SCHED;
;             PG8_LDA(At, 0, 1); PG8_STAGE(PG8_SB(0, 0), b2, voffB); PG8_STAGE(PG8_SB(0, 1), b2 + hstep, voffB); PG8_STAGE(PG8_SA(0, 0), a2, voffA);
;             PG8_WAIT_V(8); PG8_WAIT_L(0); PG8_BAR; PG8_MMA(1, 0, At, B0); PG8_MMA(1, 1, At, B1); PG8_BAR; PG8_SCHED;
.LBB0_264:
	ds_read_b128 v[148:151], v168
	ds_read_b128 v[152:155], v168 offset:1024
	ds_read_b128 v[156:159], v168 offset:2048
	ds_read_b128 v[160:163], v168 offset:3072
	ds_read_b128 v[174:177], v169
	ds_read_b128 v[178:181], v169 offset:1024
	ds_read_b128 v[182:185], v169 offset:2048
	ds_read_b128 v[186:189], v169 offset:3072
	s_add_i32 s71, s42, 2
	s_add_u32 s72, s40, 0x80
	s_addc_u32 s43, s41, 0
	s_cmp_eq_u32 s63, s42
	s_cselect_b32 s42, s8, s72
	s_cselect_b32 s43, s9, s43
	s_cselect_b32 s73, s37, s38
	s_cselect_b32 s72, s36, s33
	v_lshl_add_u64 v[164:165], s[40:41], 0, v[140:141]
	s_add_i32 m0, s56, 0xc000
	ds_read_b128 v[194:197], v170
	ds_read_b128 v[198:201], v170 offset:1024
	ds_read_b128 v[202:205], v170 offset:2048
	ds_read_b128 v[206:209], v170 offset:3072
	ds_read_b128 v[210:213], v170 offset:4096
	ds_read_b128 v[214:217], v170 offset:5120
	ds_read_b128 v[218:221], v170 offset:6144
	ds_read_b128 v[222:225], v170 offset:7168
	global_load_lds_dwordx4 v[164:165], off
	v_lshl_add_u64 v[164:165], s[40:41], 0, v[142:143]
	s_add_i32 m0, s56, 0xe000
	s_nop 0
	global_load_lds_dwordx4 v[164:165], off
	s_waitcnt vmcnt(8)
	s_waitcnt lgkmcnt(0)
	s_barrier
	s_setprio 1
	v_mfma_f32_16x16x32_bf16 v[120:123], v[148:151], v[194:197], v[120:123]
	v_mfma_f32_16x16x32_bf16 v[116:119], v[156:159], v[194:197], v[116:119]
	v_mfma_f32_16x16x32_bf16 v[108:111], v[148:151], v[202:205], v[108:111]
	v_mfma_f32_16x16x32_bf16 v[100:103], v[156:159], v[202:205], v[100:103]
	v_mfma_f32_16x16x32_bf16 v[92:95], v[148:151], v[210:213], v[92:95]
	v_mfma_f32_16x16x32_bf16 v[84:87], v[156:159], v[210:213], v[84:87]
	v_mfma_f32_16x16x32_bf16 v[76:79], v[148:151], v[218:221], v[76:79]
	v_mfma_f32_16x16x32_bf16 v[68:71], v[156:159], v[218:221], v[68:71]
	v_mfma_f32_16x16x32_bf16 v[120:123], v[152:155], v[198:201], v[120:123]
	v_mfma_f32_16x16x32_bf16 v[116:119], v[160:163], v[198:201], v[116:119]
	v_mfma_f32_16x16x32_bf16 v[108:111], v[152:155], v[206:209], v[108:111]
	v_mfma_f32_16x16x32_bf16 v[100:103], v[160:163], v[206:209], v[100:103]
	v_mfma_f32_16x16x32_bf16 v[92:95], v[152:155], v[214:217], v[92:95]
	v_mfma_f32_16x16x32_bf16 v[84:87], v[160:163], v[214:217], v[84:87]
	v_mfma_f32_16x16x32_bf16 v[76:79], v[152:155], v[222:225], v[76:79]
	v_mfma_f32_16x16x32_bf16 v[68:71], v[160:163], v[222:225], v[68:71]
	v_mfma_f32_16x16x32_bf16 v[124:127], v[174:177], v[194:197], v[124:127]
	v_mfma_f32_16x16x32_bf16 v[112:115], v[182:185], v[194:197], v[112:115]
	v_mfma_f32_16x16x32_bf16 v[104:107], v[174:177], v[202:205], v[104:107]
	v_mfma_f32_16x16x32_bf16 v[96:99], v[182:185], v[202:205], v[96:99]
	v_mfma_f32_16x16x32_bf16 v[88:91], v[174:177], v[210:213], v[88:91]
	v_mfma_f32_16x16x32_bf16 v[80:83], v[182:185], v[210:213], v[80:83]
	v_mfma_f32_16x16x32_bf16 v[72:75], v[174:177], v[218:221], v[72:75]
	v_mfma_f32_16x16x32_bf16 v[64:67], v[182:185], v[218:221], v[64:67]
	v_mfma_f32_16x16x32_bf16 v[124:127], v[178:181], v[198:201], v[124:127]
	v_mfma_f32_16x16x32_bf16 v[112:115], v[186:189], v[198:201], v[112:115]
	v_mfma_f32_16x16x32_bf16 v[104:107], v[178:181], v[206:209], v[104:107]
	v_mfma_f32_16x16x32_bf16 v[96:99], v[186:189], v[206:209], v[96:99]
	v_mfma_f32_16x16x32_bf16 v[88:91], v[178:181], v[214:217], v[88:91]
	v_mfma_f32_16x16x32_bf16 v[80:83], v[186:189], v[214:217], v[80:83]
	v_mfma_f32_16x16x32_bf16 v[72:75], v[178:181], v[222:225], v[72:75]
	v_mfma_f32_16x16x32_bf16 v[64:67], v[186:189], v[222:225], v[64:67]
	s_setprio 0
	s_barrier
	s_add_i32 s74, s66, s3
	v_lshl_add_u64 v[164:165], s[72:73], 0, v[134:135]
	s_mov_b32 m0, s74
	ds_read_b128 v[194:197], v170 offset:16384
	ds_read_b128 v[198:201], v170 offset:17408
	ds_read_b128 v[202:205], v170 offset:18432
	ds_read_b128 v[206:209], v170 offset:19456
	ds_read_b128 v[210:213], v170 offset:20480
	ds_read_b128 v[214:217], v170 offset:21504
	ds_read_b128 v[218:221], v170 offset:22528
	ds_read_b128 v[222:225], v170 offset:23552
	global_load_lds_dwordx4 v[164:165], off
	s_add_i32 m0, s74, 0x2000
	v_lshl_add_u64 v[190:191], s[72:73], 0, v[130:131]
	s_add_u32 s72, s72, s12
	s_addc_u32 s73, s73, s13
	s_add_i32 s74, s67, s3
	global_load_lds_dwordx4 v[190:191], off
	v_lshl_add_u64 v[226:227], s[72:73], 0, v[134:135]
	s_mov_b32 m0, s74
	v_lshl_add_u64 v[228:229], s[72:73], 0, v[130:131]
	global_load_lds_dwordx4 v[226:227], off
	s_add_i32 m0, s74, 0x2000
	v_lshl_add_u64 v[230:231], s[42:43], 0, v[136:137]
	global_load_lds_dwordx4 v[228:229], off
	s_mov_b32 m0, s56
	v_lshl_add_u64 v[232:233], s[42:43], 0, v[132:133]
	global_load_lds_dwordx4 v[230:231], off
	s_mov_b32 m0, s57
	s_nop 0
	global_load_lds_dwordx4 v[232:233], off
	s_cmp_lg_u32 s71, 2
	s_cbranch_scc1 .Lss_p1_skip
	s_lshl_b32 s84, s4, 14
	s_mov_b32 s85, 0
	s_add_i32 m0, s56, 0x20000
	v_lshl_add_u64 v[238:239], v[236:237], 0, s[84:85]
	s_add_u32 s84, s84, 0x2000
	global_load_lds_dwordx4 v[238:239], off
	s_add_i32 m0, s56, 0x22000
	v_lshl_add_u64 v[238:239], v[236:237], 0, s[84:85]
	global_load_lds_dwordx4 v[238:239], off
; #define PG8_STAGE(bufoff, gbase, voff) do { _Pragma("unroll") for (int _i = 0; _i < 2; ++_i) \
;         __builtin_amdgcn_global_load_lds((const unsigned*)((const char*)(gbase) + (voff)[_i]), (PG8_LAS unsigned*)(lds + (bufoff) + ldsw + _i * 8192), 16, 0, 0); } while (0)
; #define PG8_LDA(dst, b, h) do { _Pragma("unroll") for (int m = 0; m < 4; ++m) _Pragma("unroll") for (int k = 0; k < 2; ++k) dst[m][k] = *(const PG8_LAS bf16x8*)(lds + PG8_SA(b, h) + aoff + m * 2048 + k * 1024); } while (0)
; #define PG8_LDB(dst, b, h) do { _Pragma("unroll") for (int n = 0; n < 2; ++n) _Pragma("unroll") for (int k = 0; k < 2; ++k) dst[n][k] = *(const PG8_LAS bf16x8*)(lds + PG8_SB(b, h) + boff + n * 2048 + k * 1024); } while (0)
; #define PG8_MMA(ai, bj, At, Bt) do { __builtin_amdgcn_s_setprio(1); _Pragma("unroll") for (int m = 0; m < 4; ++m) _Pragma("unroll") for (int n = 0; n < 2; ++n) _Pragma("unroll") for (int k = 0; k < 2; ++k) \
;         acc[ai][bj][m][n] = __builtin_amdgcn_mfma_f32_16x16x32_bf16(Bt[n][k], At[m][k], acc[ai][bj][m][n], 0, 0, 0); __builtin_amdgcn_s_setprio(0); } while (0)
; #define PG8_WAIT_V(n) asm volatile("s_waitcnt vmcnt(" #n ")" ::: "memory")
; #define PG8_WAIT_L(n) asm volatile("s_waitcnt lgkmcnt(" #n ")" ::: "memory")
; #define PG8_BAR __builtin_amdgcn_s_barrier()
; #define PG8_SCHED __builtin_amdgcn_sched_barrier(0)
; template <class Epi, class Sched, bool ALIGN_EPI = false, bool SP2 = false>
; __device__ __forceinline__ void gemm_phase(PG8_LAS unsigned char* lds, const Gemm g, const Sched& S, const Epi& E) {
;     ...
;             PG8_LDB(B0, 0, 0); PG8_LDB(B1, 0, 1); PG8_SCHED; PG8_LDA(At, 0, 0); PG8_STAGE(PG8_SA(1, 1), a1 + hstep, voffA);
;             PG8_WAIT_V(8); PG8_WAIT_L(0); PG8_BAR; PG8_MMA(0, 0, At, B0); PG8_MMA(0, 1, At, B1); PG8_BAR; PG8_SCHED;
;             PG8_LDA(At, 0, 1); PG8_STAGE(PG8_SB(0, 0), b2, voffB); PG8_STAGE(PG8_SB(0, 1), b2 + hstep, voffB); PG8_STAGE(PG8_SA(0, 0), a2, voffA);
;             PG8_WAIT_V(8); PG8_WAIT_L(0); PG8_BAR; PG8_MMA(1, 0, At, B0); PG8_MMA(1, 1, At, B1); PG8_BAR; PG8_SCHED;
;             PG8_LDB(B0, 1, 0); PG8_LDB(B1, 1, 1); PG8_SCHED; PG8_LDA(At, 1, 0); PG8_STAGE(PG8_SA(0, 1), a2 + hstep, voffA);
;             PG8_WAIT_V(8); PG8_WAIT_L(0); PG8_BAR; PG8_MMA(0, 0, At, B0); PG8_MMA(0, 1, At, B1); PG8_BAR; PG8_SCHED;
.Lss_p1_skip:
	s_waitcnt vmcnt(8)
	s_waitcnt lgkmcnt(0)
	s_barrier
	s_setprio 1
	v_mfma_f32_16x16x32_bf16 v[60:63], v[148:151], v[194:197], v[60:63]
	v_mfma_f32_16x16x32_bf16 v[52:55], v[156:159], v[194:197], v[52:55]
	v_mfma_f32_16x16x32_bf16 v[44:47], v[148:151], v[202:205], v[44:47]
	v_mfma_f32_16x16x32_bf16 v[36:39], v[156:159], v[202:205], v[36:39]
	v_mfma_f32_16x16x32_bf16 v[28:31], v[148:151], v[210:213], v[28:31]
	v_mfma_f32_16x16x32_bf16 v[20:23], v[156:159], v[210:213], v[20:23]
	v_mfma_f32_16x16x32_bf16 v[12:15], v[148:151], v[218:221], v[12:15]
	v_mfma_f32_16x16x32_bf16 v[4:7], v[156:159], v[218:221], v[4:7]
	v_mfma_f32_16x16x32_bf16 v[60:63], v[152:155], v[198:201], v[60:63]
	v_mfma_f32_16x16x32_bf16 v[52:55], v[160:163], v[198:201], v[52:55]
	v_mfma_f32_16x16x32_bf16 v[44:47], v[152:155], v[206:209], v[44:47]
	v_mfma_f32_16x16x32_bf16 v[36:39], v[160:163], v[206:209], v[36:39]
	v_mfma_f32_16x16x32_bf16 v[28:31], v[152:155], v[214:217], v[28:31]
	v_mfma_f32_16x16x32_bf16 v[20:23], v[160:163], v[214:217], v[20:23]
	v_mfma_f32_16x16x32_bf16 v[12:15], v[152:155], v[222:225], v[12:15]
	v_mfma_f32_16x16x32_bf16 v[4:7], v[160:163], v[222:225], v[4:7]
	v_mfma_f32_16x16x32_bf16 v[56:59], v[174:177], v[194:197], v[56:59]
	v_mfma_f32_16x16x32_bf16 v[48:51], v[182:185], v[194:197], v[48:51]
	v_mfma_f32_16x16x32_bf16 v[40:43], v[174:177], v[202:205], v[40:43]
	v_mfma_f32_16x16x32_bf16 v[32:35], v[182:185], v[202:205], v[32:35]
	v_mfma_f32_16x16x32_bf16 v[24:27], v[174:177], v[210:213], v[24:27]
	v_mfma_f32_16x16x32_bf16 v[16:19], v[182:185], v[210:213], v[16:19]
	v_mfma_f32_16x16x32_bf16 v[8:11], v[174:177], v[218:221], v[8:11]
	v_mfma_f32_16x16x32_bf16 v[0:3], v[182:185], v[218:221], v[0:3]
	v_mfma_f32_16x16x32_bf16 v[56:59], v[178:181], v[198:201], v[56:59]
	v_mfma_f32_16x16x32_bf16 v[48:51], v[186:189], v[198:201], v[48:51]
	v_mfma_f32_16x16x32_bf16 v[40:43], v[178:181], v[206:209], v[40:43]
	v_mfma_f32_16x16x32_bf16 v[32:35], v[186:189], v[206:209], v[32:35]
	v_mfma_f32_16x16x32_bf16 v[24:27], v[178:181], v[214:217], v[24:27]
	v_mfma_f32_16x16x32_bf16 v[16:19], v[186:189], v[214:217], v[16:19]
	v_mfma_f32_16x16x32_bf16 v[8:11], v[178:181], v[222:225], v[8:11]
	v_mfma_f32_16x16x32_bf16 v[0:3], v[186:189], v[222:225], v[0:3]
	s_setprio 0
	s_barrier
	s_add_i32 s72, 0, 0x18000
	v_add_u32_e32 v128, s72, v166
	s_add_i32 s73, 0, 0x1c000
	ds_read_b128 v[148:151], v128
	ds_read_b128 v[152:155], v128 offset:1024
	ds_read_b128 v[156:159], v128 offset:2048
	ds_read_b128 v[160:163], v128 offset:3072
	v_add_u32_e32 v128, s73, v166
	ds_read_b128 v[174:177], v128
	ds_read_b128 v[178:181], v128 offset:1024
	ds_read_b128 v[182:185], v128 offset:2048
	ds_read_b128 v[186:189], v128 offset:3072
	s_add_u32 s42, s42, s12
	s_addc_u32 s43, s43, s13
	s_mov_b32 m0, s58
	v_lshl_add_u64 v[234:235], s[42:43], 0, v[136:137]
	ds_read_b128 v[194:197], v170 offset:32768
	ds_read_b128 v[198:201], v170 offset:33792
	ds_read_b128 v[202:205], v170 offset:34816
	ds_read_b128 v[206:209], v170 offset:35840
	ds_read_b128 v[210:213], v170 offset:36864
	ds_read_b128 v[214:217], v170 offset:37888
	ds_read_b128 v[218:221], v170 offset:38912
	ds_read_b128 v[222:225], v170 offset:39936
	global_load_lds_dwordx4 v[234:235], off
	v_lshl_add_u64 v[234:235], s[42:43], 0, v[132:133]
	s_mov_b32 m0, s59
	s_nop 0
	global_load_lds_dwordx4 v[234:235], off
	s_waitcnt vmcnt(8)
	s_waitcnt lgkmcnt(0)
	s_barrier
	s_setprio 1
	v_mfma_f32_16x16x32_bf16 v[120:123], v[148:151], v[194:197], v[120:123]
	v_mfma_f32_16x16x32_bf16 v[116:119], v[156:159], v[194:197], v[116:119]
	v_mfma_f32_16x16x32_bf16 v[108:111], v[148:151], v[202:205], v[108:111]
	v_mfma_f32_16x16x32_bf16 v[100:103], v[156:159], v[202:205], v[100:103]
	v_mfma_f32_16x16x32_bf16 v[92:95], v[148:151], v[210:213], v[92:95]
	v_mfma_f32_16x16x32_bf16 v[84:87], v[156:159], v[210:213], v[84:87]
	v_mfma_f32_16x16x32_bf16 v[76:79], v[148:151], v[218:221], v[76:79]
	v_mfma_f32_16x16x32_bf16 v[68:71], v[156:159], v[218:221], v[68:71]
	v_mfma_f32_16x16x32_bf16 v[120:123], v[152:155], v[198:201], v[120:123]
	v_mfma_f32_16x16x32_bf16 v[116:119], v[160:163], v[198:201], v[116:119]
	v_mfma_f32_16x16x32_bf16 v[108:111], v[152:155], v[206:209], v[108:111]
	v_mfma_f32_16x16x32_bf16 v[100:103], v[160:163], v[206:209], v[100:103]
	v_mfma_f32_16x16x32_bf16 v[92:95], v[152:155], v[214:217], v[92:95]
	v_mfma_f32_16x16x32_bf16 v[84:87], v[160:163], v[214:217], v[84:87]
	v_mfma_f32_16x16x32_bf16 v[76:79], v[152:155], v[222:225], v[76:79]
	v_mfma_f32_16x16x32_bf16 v[68:71], v[160:163], v[222:225], v[68:71]
	v_mfma_f32_16x16x32_bf16 v[124:127], v[174:177], v[194:197], v[124:127]
	v_mfma_f32_16x16x32_bf16 v[112:115], v[182:185], v[194:197], v[112:115]
	v_mfma_f32_16x16x32_bf16 v[104:107], v[174:177], v[202:205], v[104:107]
	v_mfma_f32_16x16x32_bf16 v[96:99], v[182:185], v[202:205], v[96:99]
	v_mfma_f32_16x16x32_bf16 v[88:91], v[174:177], v[210:213], v[88:91]
	v_mfma_f32_16x16x32_bf16 v[80:83], v[182:185], v[210:213], v[80:83]
	v_mfma_f32_16x16x32_bf16 v[72:75], v[174:177], v[218:221], v[72:75]
	v_mfma_f32_16x16x32_bf16 v[64:67], v[182:185], v[218:221], v[64:67]
	v_mfma_f32_16x16x32_bf16 v[124:127], v[178:181], v[198:201], v[124:127]
	v_mfma_f32_16x16x32_bf16 v[112:115], v[186:189], v[198:201], v[112:115]
	v_mfma_f32_16x16x32_bf16 v[104:107], v[178:181], v[206:209], v[104:107]
	v_mfma_f32_16x16x32_bf16 v[96:99], v[186:189], v[206:209], v[96:99]
	v_mfma_f32_16x16x32_bf16 v[88:91], v[178:181], v[214:217], v[88:91]
	v_mfma_f32_16x16x32_bf16 v[80:83], v[186:189], v[214:217], v[80:83]
	v_mfma_f32_16x16x32_bf16 v[72:75], v[178:181], v[222:225], v[72:75]
	v_mfma_f32_16x16x32_bf16 v[64:67], v[186:189], v[222:225], v[64:67]
	s_setprio 0
	s_barrier
; #define PG8_STAGE(bufoff, gbase, voff) do { _Pragma("unroll") for (int _i = 0; _i < 2; ++_i) \
;         __builtin_amdgcn_global_load_lds((const unsigned*)((const char*)(gbase) + (voff)[_i]), (PG8_LAS unsigned*)(lds + (bufoff) + ldsw + _i * 8192), 16, 0, 0); } while (0)
; #define PG8_LDA(dst, b, h) do { _Pragma("unroll") for (int m = 0; m < 4; ++m) _Pragma("unroll") for (int k = 0; k < 2; ++k) dst[m][k] = *(const PG8_LAS bf16x8*)(lds + PG8_SA(b, h) + aoff + m * 2048 + k * 1024); } while (0)
; #define PG8_LDB(dst, b, h) do { _Pragma("unroll") for (int n = 0; n < 2; ++n) _Pragma("unroll") for (int k = 0; k < 2; ++k) dst[n][k] = *(const PG8_LAS bf16x8*)(lds + PG8_SB(b, h) + boff + n * 2048 + k * 1024); } while (0)
; #define PG8_MMA(ai, bj, At, Bt) do { __builtin_amdgcn_s_setprio(1); _Pragma("unroll") for (int m = 0; m < 4; ++m) _Pragma("unroll") for (int n = 0; n < 2; ++n) _Pragma("unroll") for (int k = 0; k < 2; ++k) \
;         acc[ai][bj][m][n] = __builtin_amdgcn_mfma_f32_16x16x32_bf16(Bt[n][k], At[m][k], acc[ai][bj][m][n], 0, 0, 0); __builtin_amdgcn_s_setprio(0); } while (0)
; #define PG8_WAIT_V(n) asm volatile("s_waitcnt vmcnt(" #n ")" ::: "memory")
; #define PG8_WAIT_L(n) asm volatile("s_waitcnt lgkmcnt(" #n ")" ::: "memory")
; #define PG8_BAR __builtin_amdgcn_s_barrier()
; #define PG8_SCHED __builtin_amdgcn_sched_barrier(0)
; template <class Epi, class Sched, bool ALIGN_EPI = false, bool SP2 = false>
; __device__ __forceinline__ void gemm_phase(PG8_LAS unsigned char* lds, const Gemm g, const Sched& S, const Epi& E) {
;     ...
;             PG8_LDB(B0, 1, 0); PG8_LDB(B1, 1, 1); PG8_SCHED; PG8_LDA(At, 1, 0); PG8_STAGE(PG8_SA(0, 1), a2 + hstep, voffA);
;             PG8_WAIT_V(8); PG8_WAIT_L(0); PG8_BAR; PG8_MMA(0, 0, At, B0); PG8_MMA(0, 1, At, B1); PG8_BAR; PG8_SCHED;
;             PG8_LDA(At, 1, 1); PG8_STAGE(PG8_SB(1, 0), b3, voffB); PG8_STAGE(PG8_SB(1, 1), b3 + hstep, voffB); PG8_STAGE(PG8_SA(1, 0), a3, voffA);
;             PG8_WAIT_V(8); PG8_WAIT_L(0); PG8_BAR; PG8_MMA(1, 0, At, B0); PG8_MMA(1, 1, At, B1); PG8_BAR; PG8_SCHED;
	s_add_i32 s42, s72, s3
	v_lshl_add_u64 v[164:165], v[164:165], 0, s[18:19]
	s_mov_b32 m0, s42
	ds_read_b128 v[194:197], v170 offset:49152
	ds_read_b128 v[198:201], v170 offset:50176
	ds_read_b128 v[202:205], v170 offset:51200
	ds_read_b128 v[206:209], v170 offset:52224
	ds_read_b128 v[210:213], v170 offset:53248
	ds_read_b128 v[214:217], v170 offset:54272
	ds_read_b128 v[218:221], v170 offset:55296
	ds_read_b128 v[222:225], v170 offset:56320
	global_load_lds_dwordx4 v[164:165], off
	v_lshl_add_u64 v[164:165], v[190:191], 0, s[18:19]
	s_add_i32 m0, s42, 0x2000
	s_add_i32 s42, s73, s3
	global_load_lds_dwordx4 v[164:165], off
	v_lshl_add_u64 v[164:165], v[226:227], 0, s[18:19]
	s_mov_b32 m0, s42
	s_nop 0
	global_load_lds_dwordx4 v[164:165], off
	v_lshl_add_u64 v[164:165], v[228:229], 0, s[18:19]
	s_add_i32 m0, s42, 0x2000
	s_nop 0
	global_load_lds_dwordx4 v[164:165], off
	v_lshl_add_u64 v[164:165], v[230:231], 0, s[18:19]
	s_mov_b32 m0, s48
	s_nop 0
	global_load_lds_dwordx4 v[164:165], off
	v_lshl_add_u64 v[164:165], v[232:233], 0, s[18:19]
	s_mov_b32 m0, s61
	s_nop 0
	global_load_lds_dwordx4 v[164:165], off
	s_waitcnt vmcnt(8)
	s_waitcnt lgkmcnt(0)
	s_barrier
	s_setprio 1
	v_mfma_f32_16x16x32_bf16 v[60:63], v[148:151], v[194:197], v[60:63]
	v_mfma_f32_16x16x32_bf16 v[52:55], v[156:159], v[194:197], v[52:55]
	v_mfma_f32_16x16x32_bf16 v[44:47], v[148:151], v[202:205], v[44:47]
	v_mfma_f32_16x16x32_bf16 v[36:39], v[156:159], v[202:205], v[36:39]
	v_mfma_f32_16x16x32_bf16 v[28:31], v[148:151], v[210:213], v[28:31]
	v_mfma_f32_16x16x32_bf16 v[20:23], v[156:159], v[210:213], v[20:23]
	v_mfma_f32_16x16x32_bf16 v[12:15], v[148:151], v[218:221], v[12:15]
	v_mfma_f32_16x16x32_bf16 v[4:7], v[156:159], v[218:221], v[4:7]
	v_mfma_f32_16x16x32_bf16 v[60:63], v[152:155], v[198:201], v[60:63]
	v_mfma_f32_16x16x32_bf16 v[52:55], v[160:163], v[198:201], v[52:55]
	v_mfma_f32_16x16x32_bf16 v[44:47], v[152:155], v[206:209], v[44:47]
	v_mfma_f32_16x16x32_bf16 v[36:39], v[160:163], v[206:209], v[36:39]
	v_mfma_f32_16x16x32_bf16 v[28:31], v[152:155], v[214:217], v[28:31]
	v_mfma_f32_16x16x32_bf16 v[20:23], v[160:163], v[214:217], v[20:23]
	v_mfma_f32_16x16x32_bf16 v[12:15], v[152:155], v[222:225], v[12:15]
	v_mfma_f32_16x16x32_bf16 v[4:7], v[160:163], v[222:225], v[4:7]
	v_mfma_f32_16x16x32_bf16 v[56:59], v[174:177], v[194:197], v[56:59]
	v_mfma_f32_16x16x32_bf16 v[48:51], v[182:185], v[194:197], v[48:51]
	v_mfma_f32_16x16x32_bf16 v[40:43], v[174:177], v[202:205], v[40:43]
	v_mfma_f32_16x16x32_bf16 v[32:35], v[182:185], v[202:205], v[32:35]
	v_mfma_f32_16x16x32_bf16 v[24:27], v[174:177], v[210:213], v[24:27]
	v_mfma_f32_16x16x32_bf16 v[16:19], v[182:185], v[210:213], v[16:19]
	v_mfma_f32_16x16x32_bf16 v[8:11], v[174:177], v[218:221], v[8:11]
	v_mfma_f32_16x16x32_bf16 v[0:3], v[182:185], v[218:221], v[0:3]
	v_mfma_f32_16x16x32_bf16 v[56:59], v[178:181], v[198:201], v[56:59]
	v_mfma_f32_16x16x32_bf16 v[48:51], v[186:189], v[198:201], v[48:51]
	v_mfma_f32_16x16x32_bf16 v[40:43], v[178:181], v[206:209], v[40:43]
	v_mfma_f32_16x16x32_bf16 v[32:35], v[186:189], v[206:209], v[32:35]
	v_mfma_f32_16x16x32_bf16 v[24:27], v[178:181], v[214:217], v[24:27]
	v_mfma_f32_16x16x32_bf16 v[16:19], v[186:189], v[214:217], v[16:19]
	v_mfma_f32_16x16x32_bf16 v[8:11], v[178:181], v[222:225], v[8:11]
	v_mfma_f32_16x16x32_bf16 v[0:3], v[186:189], v[222:225], v[0:3]
	s_setprio 0
	s_barrier
	s_add_u32 s40, s40, 0x100
	s_addc_u32 s41, s41, 0
	s_add_u32 s33, s33, 0x100
	s_addc_u32 s38, s38, 0
	s_cmp_ge_i32 s71, s62
	s_mov_b32 s42, s71
	s_cbranch_scc0 .LBB0_264

; #define PG8_STAGE(bufoff, gbase, voff) do { _Pragma("unroll") for (int _i = 0; _i < 2; ++_i) \
;         __builtin_amdgcn_global_load_lds((const unsigned*)((const char*)(gbase) + (voff)[_i]), (PG8_LAS unsigned*)(lds + (bufoff) + ldsw + _i * 8192), 16, 0, 0); } while (0)
; #define PG8_LDA(dst, b, h) do { _Pragma("unroll") for (int m = 0; m < 4; ++m) _Pragma("unroll") for (int k = 0; k < 2; ++k) dst[m][k] = *(const PG8_LAS bf16x8*)(lds + PG8_SA(b, h) + aoff + m * 2048 + k * 1024); } while (0)
; #define PG8_LDB(dst, b, h) do { _Pragma("unroll") for (int n = 0; n < 2; ++n) _Pragma("unroll") for (int k = 0; k < 2; ++k) dst[n][k] = *(const PG8_LAS bf16x8*)(lds + PG8_SB(b, h) + boff + n * 2048 + k * 1024); } while (0)
; #define PG8_MMA(ai, bj, At, Bt) do { __builtin_amdgcn_s_setprio(1); _Pragma("unroll") for (int m = 0; m < 4; ++m) _Pragma("unroll") for (int n = 0; n < 2; ++n) _Pragma("unroll") for (int k = 0; k < 2; ++k) \
;         acc[ai][bj][m][n] = __builtin_amdgcn_mfma_f32_16x16x32_bf16(Bt[n][k], At[m][k], acc[ai][bj][m][n], 0, 0, 0); __builtin_amdgcn_s_setprio(0); } while (0)
; template <class Epi, class Sched, bool ALIGN_EPI = false, bool SP2 = false>
; __device__ __forceinline__ void gemm_phase(PG8_LAS unsigned char* lds, const Gemm g, const Sched& S, const Epi& E) {
;     ...
;         for (int t = 0; t < nt; t += 2) {
;             const bool last = (t == nt - 2);
;             const char* a1 = cA + (size_t)(t + 1) * kstep;
;             const char* a2 = last ? nA : cA + (size_t)(t + 2) * kstep; const char* b2 = last ? nB : cB + (size_t)(t + 2) * kstep;
;             const char* a3 = a2 + kstep; const char* b3 = b2 + kstep;
;             if (last && has_next) S.a_ready(nxt);
;             if constexpr (SP2) {
;             PG8_LDB(B0, 0, 0); PG8_LDB(B1, 0, 1); PG8_SCHED; PG8_LDA(At, 0, 0); PG8_STAGE(PG8_SA(1, 1), a1 + hstep, voffA);
;             PG8_WAIT_V(8); PG8_WAIT_L(0); PG8_BAR; PG8_MMA(0, 0, At, B0); PG8_MMA(0, 1, At, B1); PG8_BAR; PG8_SCHED;
;             PG8_LDA(At, 0, 1); PG8_STAGE(PG8_SB(0, 0), b2, voffB); PG8_STAGE(PG8_SB(0, 1), b2 + hstep, voffB); PG8_STAGE(PG8_SA(0, 0), a2, voffA);
;             PG8_WAIT_V(8); PG8_WAIT_L(0); PG8_BAR; PG8_MMA(1, 0, At, B0); PG8_MMA(1, 1, At, B1); PG8_BAR; PG8_SCHED;
;             PG8_LDB(B0, 1, 0); PG8_LDB(B1, 1, 1); PG8_SCHED; PG8_LDA(At, 1, 0); PG8_STAGE(PG8_SA(0, 1), a2 + hstep, voffA);
.LBB0_284:
	ds_read_b128 v[150:153], v144
	ds_read_b128 v[154:157], v144 offset:1024
	ds_read_b128 v[158:161], v144 offset:2048
	ds_read_b128 v[162:165], v144 offset:3072
	ds_read_b128 v[166:169], v145
	ds_read_b128 v[170:173], v145 offset:1024
	ds_read_b128 v[174:177], v145 offset:2048
	ds_read_b128 v[178:181], v145 offset:3072
	s_add_i32 s90, s62, 2
	s_add_u32 s91, s60, 0x80
	s_addc_u32 s63, s61, 0
	s_cmp_eq_u32 s74, s62
	s_cselect_b32 s62, s56, s91
	s_cselect_b32 s63, s57, s63
	s_cselect_b32 s93, s59, s89
	s_cselect_b32 s92, s58, s33
	s_mov_b32 m0, s75
	v_lshl_add_u64 v[190:191], s[60:61], 0, v[140:141]
	ds_read_b128 v[182:185], v146
	ds_read_b128 v[186:189], v146 offset:1024
	ds_read_b128 v[194:197], v146 offset:2048
	ds_read_b128 v[198:201], v146 offset:3072
	ds_read_b128 v[202:205], v146 offset:4096
	ds_read_b128 v[206:209], v146 offset:5120
	ds_read_b128 v[210:213], v146 offset:6144
	ds_read_b128 v[214:217], v146 offset:7168
	global_load_lds_dwordx4 v[190:191], off
	v_lshl_add_u64 v[190:191], s[60:61], 0, v[142:143]
	s_mov_b32 m0, s76
	s_nop 0
	global_load_lds_dwordx4 v[190:191], off
	s_waitcnt vmcnt(8)
	s_waitcnt lgkmcnt(0)
	s_barrier
	s_setprio 1
	v_mfma_f32_16x16x32_bf16 v[124:127], v[150:153], v[182:185], v[124:127]
	v_mfma_f32_16x16x32_bf16 v[120:123], v[158:161], v[182:185], v[120:123]
	v_mfma_f32_16x16x32_bf16 v[108:111], v[150:153], v[194:197], v[108:111]
	v_mfma_f32_16x16x32_bf16 v[104:107], v[158:161], v[194:197], v[104:107]
	v_mfma_f32_16x16x32_bf16 v[92:95], v[150:153], v[202:205], v[92:95]
	v_mfma_f32_16x16x32_bf16 v[88:91], v[158:161], v[202:205], v[88:91]
	v_mfma_f32_16x16x32_bf16 v[76:79], v[150:153], v[210:213], v[76:79]
	v_mfma_f32_16x16x32_bf16 v[72:75], v[158:161], v[210:213], v[72:75]
	v_mfma_f32_16x16x32_bf16 v[124:127], v[154:157], v[186:189], v[124:127]
	v_mfma_f32_16x16x32_bf16 v[120:123], v[162:165], v[186:189], v[120:123]
	v_mfma_f32_16x16x32_bf16 v[108:111], v[154:157], v[198:201], v[108:111]
	v_mfma_f32_16x16x32_bf16 v[104:107], v[162:165], v[198:201], v[104:107]
	v_mfma_f32_16x16x32_bf16 v[92:95], v[154:157], v[206:209], v[92:95]
	v_mfma_f32_16x16x32_bf16 v[88:91], v[162:165], v[206:209], v[88:91]
	v_mfma_f32_16x16x32_bf16 v[76:79], v[154:157], v[214:217], v[76:79]
	v_mfma_f32_16x16x32_bf16 v[72:75], v[162:165], v[214:217], v[72:75]
	v_mfma_f32_16x16x32_bf16 v[116:119], v[166:169], v[182:185], v[116:119]
	v_mfma_f32_16x16x32_bf16 v[112:115], v[174:177], v[182:185], v[112:115]
	v_mfma_f32_16x16x32_bf16 v[100:103], v[166:169], v[194:197], v[100:103]
	v_mfma_f32_16x16x32_bf16 v[96:99], v[174:177], v[194:197], v[96:99]
	v_mfma_f32_16x16x32_bf16 v[84:87], v[166:169], v[202:205], v[84:87]
	v_mfma_f32_16x16x32_bf16 v[80:83], v[174:177], v[202:205], v[80:83]
	v_mfma_f32_16x16x32_bf16 v[68:71], v[166:169], v[210:213], v[68:71]
	v_mfma_f32_16x16x32_bf16 v[64:67], v[174:177], v[210:213], v[64:67]
	v_mfma_f32_16x16x32_bf16 v[116:119], v[170:173], v[186:189], v[116:119]
	v_mfma_f32_16x16x32_bf16 v[112:115], v[178:181], v[186:189], v[112:115]
	v_mfma_f32_16x16x32_bf16 v[100:103], v[170:173], v[198:201], v[100:103]
	v_mfma_f32_16x16x32_bf16 v[96:99], v[178:181], v[198:201], v[96:99]
	v_mfma_f32_16x16x32_bf16 v[84:87], v[170:173], v[206:209], v[84:87]
	v_mfma_f32_16x16x32_bf16 v[80:83], v[178:181], v[206:209], v[80:83]
	v_mfma_f32_16x16x32_bf16 v[68:71], v[170:173], v[214:217], v[68:71]
	v_mfma_f32_16x16x32_bf16 v[64:67], v[178:181], v[214:217], v[64:67]
	s_setprio 0
	s_barrier
	s_mov_b32 m0, s77
	v_lshl_add_u64 v[190:191], s[92:93], 0, v[134:135]
	v_lshl_add_u64 v[218:219], s[92:93], 0, v[130:131]
	s_add_u32 s92, s92, s12
	ds_read_b128 v[182:185], v146 offset:16384
	ds_read_b128 v[186:189], v146 offset:17408
	ds_read_b128 v[194:197], v146 offset:18432
	ds_read_b128 v[198:201], v146 offset:19456
	ds_read_b128 v[202:205], v146 offset:20480
	ds_read_b128 v[206:209], v146 offset:21504
	ds_read_b128 v[210:213], v146 offset:22528
	ds_read_b128 v[214:217], v146 offset:23552
	global_load_lds_dwordx4 v[190:191], off
	s_mov_b32 m0, s78
	s_addc_u32 s93, s93, s13
	global_load_lds_dwordx4 v[218:219], off
	v_lshl_add_u64 v[220:221], s[92:93], 0, v[134:135]
	s_mov_b32 m0, s79
	v_lshl_add_u64 v[222:223], s[92:93], 0, v[130:131]
	global_load_lds_dwordx4 v[220:221], off
	s_mov_b32 m0, s80
	v_lshl_add_u64 v[224:225], s[62:63], 0, v[136:137]
	global_load_lds_dwordx4 v[222:223], off
	s_mov_b32 m0, s4
	v_lshl_add_u64 v[226:227], s[62:63], 0, v[132:133]
	global_load_lds_dwordx4 v[224:225], off
	s_mov_b32 m0, s5
	s_nop 0
	global_load_lds_dwordx4 v[226:227], off
	s_waitcnt vmcnt(8)
	s_waitcnt lgkmcnt(0)
	s_barrier
; #define PG8_STAGE(bufoff, gbase, voff) do { _Pragma("unroll") for (int _i = 0; _i < 2; ++_i) \
;         __builtin_amdgcn_global_load_lds((const unsigned*)((const char*)(gbase) + (voff)[_i]), (PG8_LAS unsigned*)(lds + (bufoff) + ldsw + _i * 8192), 16, 0, 0); } while (0)
; #define PG8_LDA(dst, b, h) do { _Pragma("unroll") for (int m = 0; m < 4; ++m) _Pragma("unroll") for (int k = 0; k < 2; ++k) dst[m][k] = *(const PG8_LAS bf16x8*)(lds + PG8_SA(b, h) + aoff + m * 2048 + k * 1024); } while (0)
; #define PG8_LDB(dst, b, h) do { _Pragma("unroll") for (int n = 0; n < 2; ++n) _Pragma("unroll") for (int k = 0; k < 2; ++k) dst[n][k] = *(const PG8_LAS bf16x8*)(lds + PG8_SB(b, h) + boff + n * 2048 + k * 1024); } while (0)
; #define PG8_MMA(ai, bj, At, Bt) do { __builtin_amdgcn_s_setprio(1); _Pragma("unroll") for (int m = 0; m < 4; ++m) _Pragma("unroll") for (int n = 0; n < 2; ++n) _Pragma("unroll") for (int k = 0; k < 2; ++k) \
;         acc[ai][bj][m][n] = __builtin_amdgcn_mfma_f32_16x16x32_bf16(Bt[n][k], At[m][k], acc[ai][bj][m][n], 0, 0, 0); __builtin_amdgcn_s_setprio(0); } while (0)
; #define PG8_WAIT_V(n) asm volatile("s_waitcnt vmcnt(" #n ")" ::: "memory")
; #define PG8_WAIT_L(n) asm volatile("s_waitcnt lgkmcnt(" #n ")" ::: "memory")
; #define PG8_BAR __builtin_amdgcn_s_barrier()
; #define PG8_SCHED __builtin_amdgcn_sched_barrier(0)
; template <class Epi, class Sched, bool ALIGN_EPI = false, bool SP2 = false>
; __device__ __forceinline__ void gemm_phase(PG8_LAS unsigned char* lds, const Gemm g, const Sched& S, const Epi& E) {
;     ...
;             PG8_WAIT_V(8); PG8_WAIT_L(0); PG8_BAR; PG8_MMA(1, 0, At, B0); PG8_MMA(1, 1, At, B1); PG8_BAR; PG8_SCHED;
;             PG8_LDB(B0, 1, 0); PG8_LDB(B1, 1, 1); PG8_SCHED; PG8_LDA(At, 1, 0); PG8_STAGE(PG8_SA(0, 1), a2 + hstep, voffA);
;             PG8_WAIT_V(8); PG8_WAIT_L(0); PG8_BAR; PG8_MMA(0, 0, At, B0); PG8_MMA(0, 1, At, B1); PG8_BAR; PG8_SCHED;
;             PG8_LDA(At, 1, 1); PG8_STAGE(PG8_SB(1, 0), b3, voffB); PG8_STAGE(PG8_SB(1, 1), b3 + hstep, voffB); PG8_STAGE(PG8_SA(1, 0), a3, voffA);
	s_setprio 1
	v_mfma_f32_16x16x32_bf16 v[60:63], v[150:153], v[182:185], v[60:63]
	v_mfma_f32_16x16x32_bf16 v[56:59], v[158:161], v[182:185], v[56:59]
	v_mfma_f32_16x16x32_bf16 v[44:47], v[150:153], v[194:197], v[44:47]
	v_mfma_f32_16x16x32_bf16 v[40:43], v[158:161], v[194:197], v[40:43]
	v_mfma_f32_16x16x32_bf16 v[28:31], v[150:153], v[202:205], v[28:31]
	v_mfma_f32_16x16x32_bf16 v[24:27], v[158:161], v[202:205], v[24:27]
	v_mfma_f32_16x16x32_bf16 v[12:15], v[150:153], v[210:213], v[12:15]
	v_mfma_f32_16x16x32_bf16 v[8:11], v[158:161], v[210:213], v[8:11]
	v_mfma_f32_16x16x32_bf16 v[60:63], v[154:157], v[186:189], v[60:63]
	v_mfma_f32_16x16x32_bf16 v[56:59], v[162:165], v[186:189], v[56:59]
	v_mfma_f32_16x16x32_bf16 v[44:47], v[154:157], v[198:201], v[44:47]
	v_mfma_f32_16x16x32_bf16 v[40:43], v[162:165], v[198:201], v[40:43]
	v_mfma_f32_16x16x32_bf16 v[28:31], v[154:157], v[206:209], v[28:31]
	v_mfma_f32_16x16x32_bf16 v[24:27], v[162:165], v[206:209], v[24:27]
	v_mfma_f32_16x16x32_bf16 v[12:15], v[154:157], v[214:217], v[12:15]
	v_mfma_f32_16x16x32_bf16 v[8:11], v[162:165], v[214:217], v[8:11]
	v_mfma_f32_16x16x32_bf16 v[52:55], v[166:169], v[182:185], v[52:55]
	v_mfma_f32_16x16x32_bf16 v[48:51], v[174:177], v[182:185], v[48:51]
	v_mfma_f32_16x16x32_bf16 v[36:39], v[166:169], v[194:197], v[36:39]
	v_mfma_f32_16x16x32_bf16 v[32:35], v[174:177], v[194:197], v[32:35]
	v_mfma_f32_16x16x32_bf16 v[20:23], v[166:169], v[202:205], v[20:23]
	v_mfma_f32_16x16x32_bf16 v[16:19], v[174:177], v[202:205], v[16:19]
	v_mfma_f32_16x16x32_bf16 v[4:7], v[166:169], v[210:213], v[4:7]
	v_mfma_f32_16x16x32_bf16 v[0:3], v[174:177], v[210:213], v[0:3]
	v_mfma_f32_16x16x32_bf16 v[52:55], v[170:173], v[186:189], v[52:55]
	v_mfma_f32_16x16x32_bf16 v[48:51], v[178:181], v[186:189], v[48:51]
	v_mfma_f32_16x16x32_bf16 v[36:39], v[170:173], v[198:201], v[36:39]
	v_mfma_f32_16x16x32_bf16 v[32:35], v[178:181], v[198:201], v[32:35]
	v_mfma_f32_16x16x32_bf16 v[20:23], v[170:173], v[206:209], v[20:23]
	v_mfma_f32_16x16x32_bf16 v[16:19], v[178:181], v[206:209], v[16:19]
	v_mfma_f32_16x16x32_bf16 v[4:7], v[170:173], v[214:217], v[4:7]
	v_mfma_f32_16x16x32_bf16 v[0:3], v[178:181], v[214:217], v[0:3]
	s_setprio 0
	s_barrier
	ds_read_b128 v[150:153], v147
	ds_read_b128 v[154:157], v147 offset:1024
	ds_read_b128 v[158:161], v147 offset:2048
	ds_read_b128 v[162:165], v147 offset:3072
	ds_read_b128 v[166:169], v148
	ds_read_b128 v[170:173], v148 offset:1024
	ds_read_b128 v[174:177], v148 offset:2048
	ds_read_b128 v[178:181], v148 offset:3072
	s_add_u32 s62, s62, s12
	s_addc_u32 s63, s63, s13
	s_mov_b32 m0, s65
	v_lshl_add_u64 v[228:229], s[62:63], 0, v[136:137]
	ds_read_b128 v[182:185], v146 offset:32768
	ds_read_b128 v[186:189], v146 offset:33792
	ds_read_b128 v[194:197], v146 offset:34816
	ds_read_b128 v[198:201], v146 offset:35840
	ds_read_b128 v[202:205], v146 offset:36864
	ds_read_b128 v[206:209], v146 offset:37888
	ds_read_b128 v[210:213], v146 offset:38912
	ds_read_b128 v[214:217], v146 offset:39936
	global_load_lds_dwordx4 v[228:229], off
	v_lshl_add_u64 v[228:229], s[62:63], 0, v[132:133]
	s_mov_b32 m0, s66
	s_nop 0
	global_load_lds_dwordx4 v[228:229], off
	s_waitcnt vmcnt(8)
	s_waitcnt lgkmcnt(0)
	s_barrier
	s_setprio 1
	v_mfma_f32_16x16x32_bf16 v[124:127], v[150:153], v[182:185], v[124:127]
	v_mfma_f32_16x16x32_bf16 v[120:123], v[158:161], v[182:185], v[120:123]
	v_mfma_f32_16x16x32_bf16 v[108:111], v[150:153], v[194:197], v[108:111]
	v_mfma_f32_16x16x32_bf16 v[104:107], v[158:161], v[194:197], v[104:107]
	v_mfma_f32_16x16x32_bf16 v[92:95], v[150:153], v[202:205], v[92:95]
	v_mfma_f32_16x16x32_bf16 v[88:91], v[158:161], v[202:205], v[88:91]
	v_mfma_f32_16x16x32_bf16 v[76:79], v[150:153], v[210:213], v[76:79]
	v_mfma_f32_16x16x32_bf16 v[72:75], v[158:161], v[210:213], v[72:75]
	v_mfma_f32_16x16x32_bf16 v[124:127], v[154:157], v[186:189], v[124:127]
	v_mfma_f32_16x16x32_bf16 v[120:123], v[162:165], v[186:189], v[120:123]
	v_mfma_f32_16x16x32_bf16 v[108:111], v[154:157], v[198:201], v[108:111]
	v_mfma_f32_16x16x32_bf16 v[104:107], v[162:165], v[198:201], v[104:107]
	v_mfma_f32_16x16x32_bf16 v[92:95], v[154:157], v[206:209], v[92:95]
	v_mfma_f32_16x16x32_bf16 v[88:91], v[162:165], v[206:209], v[88:91]
	v_mfma_f32_16x16x32_bf16 v[76:79], v[154:157], v[214:217], v[76:79]
	v_mfma_f32_16x16x32_bf16 v[72:75], v[162:165], v[214:217], v[72:75]
	v_mfma_f32_16x16x32_bf16 v[116:119], v[166:169], v[182:185], v[116:119]
	v_mfma_f32_16x16x32_bf16 v[112:115], v[174:177], v[182:185], v[112:115]
	v_mfma_f32_16x16x32_bf16 v[100:103], v[166:169], v[194:197], v[100:103]
	v_mfma_f32_16x16x32_bf16 v[96:99], v[174:177], v[194:197], v[96:99]
	v_mfma_f32_16x16x32_bf16 v[84:87], v[166:169], v[202:205], v[84:87]
	v_mfma_f32_16x16x32_bf16 v[80:83], v[174:177], v[202:205], v[80:83]
	v_mfma_f32_16x16x32_bf16 v[68:71], v[166:169], v[210:213], v[68:71]
	v_mfma_f32_16x16x32_bf16 v[64:67], v[174:177], v[210:213], v[64:67]
	v_mfma_f32_16x16x32_bf16 v[116:119], v[170:173], v[186:189], v[116:119]
	v_mfma_f32_16x16x32_bf16 v[112:115], v[178:181], v[186:189], v[112:115]
	v_mfma_f32_16x16x32_bf16 v[100:103], v[170:173], v[198:201], v[100:103]
	v_mfma_f32_16x16x32_bf16 v[96:99], v[178:181], v[198:201], v[96:99]
	v_mfma_f32_16x16x32_bf16 v[84:87], v[170:173], v[206:209], v[84:87]
	v_mfma_f32_16x16x32_bf16 v[80:83], v[178:181], v[206:209], v[80:83]
	v_mfma_f32_16x16x32_bf16 v[68:71], v[170:173], v[214:217], v[68:71]
	v_mfma_f32_16x16x32_bf16 v[64:67], v[178:181], v[214:217], v[64:67]
	s_setprio 0
	s_barrier
; #define PG8_STAGE(bufoff, gbase, voff) do { _Pragma("unroll") for (int _i = 0; _i < 2; ++_i) \
;         __builtin_amdgcn_global_load_lds((const unsigned*)((const char*)(gbase) + (voff)[_i]), (PG8_LAS unsigned*)(lds + (bufoff) + ldsw + _i * 8192), 16, 0, 0); } while (0)
; #define PG8_LDA(dst, b, h) do { _Pragma("unroll") for (int m = 0; m < 4; ++m) _Pragma("unroll") for (int k = 0; k < 2; ++k) dst[m][k] = *(const PG8_LAS bf16x8*)(lds + PG8_SA(b, h) + aoff + m * 2048 + k * 1024); } while (0)
; #define PG8_MMA(ai, bj, At, Bt) do { __builtin_amdgcn_s_setprio(1); _Pragma("unroll") for (int m = 0; m < 4; ++m) _Pragma("unroll") for (int n = 0; n < 2; ++n) _Pragma("unroll") for (int k = 0; k < 2; ++k) \
;         acc[ai][bj][m][n] = __builtin_amdgcn_mfma_f32_16x16x32_bf16(Bt[n][k], At[m][k], acc[ai][bj][m][n], 0, 0, 0); __builtin_amdgcn_s_setprio(0); } while (0)
; #define PG8_WAIT_V(n) asm volatile("s_waitcnt vmcnt(" #n ")" ::: "memory")
; #define PG8_WAIT_L(n) asm volatile("s_waitcnt lgkmcnt(" #n ")" ::: "memory")
; #define PG8_BAR __builtin_amdgcn_s_barrier()
; #define PG8_SCHED __builtin_amdgcn_sched_barrier(0)
; template <class Epi, class Sched, bool ALIGN_EPI = false, bool SP2 = false>
; __device__ __forceinline__ void gemm_phase(PG8_LAS unsigned char* lds, const Gemm g, const Sched& S, const Epi& E) {
;     ...
;             PG8_WAIT_V(8); PG8_WAIT_L(0); PG8_BAR; PG8_MMA(0, 0, At, B0); PG8_MMA(0, 1, At, B1); PG8_BAR; PG8_SCHED;
;             PG8_LDA(At, 1, 1); PG8_STAGE(PG8_SB(1, 0), b3, voffB); PG8_STAGE(PG8_SB(1, 1), b3 + hstep, voffB); PG8_STAGE(PG8_SA(1, 0), a3, voffA);
;             PG8_WAIT_V(8); PG8_WAIT_L(0); PG8_BAR; PG8_MMA(1, 0, At, B0); PG8_MMA(1, 1, At, B1); PG8_BAR; PG8_SCHED;
	s_mov_b32 m0, s84
	v_lshl_add_u64 v[190:191], v[190:191], 0, s[18:19]
	ds_read_b128 v[182:185], v146 offset:49152
	ds_read_b128 v[186:189], v146 offset:50176
	ds_read_b128 v[194:197], v146 offset:51200
	ds_read_b128 v[198:201], v146 offset:52224
	ds_read_b128 v[202:205], v146 offset:53248
	ds_read_b128 v[206:209], v146 offset:54272
	ds_read_b128 v[210:213], v146 offset:55296
	ds_read_b128 v[214:217], v146 offset:56320
	global_load_lds_dwordx4 v[190:191], off
	v_lshl_add_u64 v[190:191], v[218:219], 0, s[18:19]
	s_mov_b32 m0, s85
	s_nop 0
	global_load_lds_dwordx4 v[190:191], off
	v_lshl_add_u64 v[190:191], v[220:221], 0, s[18:19]
	s_mov_b32 m0, s86
	s_nop 0
	global_load_lds_dwordx4 v[190:191], off
	v_lshl_add_u64 v[190:191], v[222:223], 0, s[18:19]
	s_mov_b32 m0, s87
	s_nop 0
	global_load_lds_dwordx4 v[190:191], off
	v_lshl_add_u64 v[190:191], v[224:225], 0, s[18:19]
	s_mov_b32 m0, s69
	s_nop 0
	global_load_lds_dwordx4 v[190:191], off
	v_lshl_add_u64 v[190:191], v[226:227], 0, s[18:19]
	s_mov_b32 m0, s70
	s_nop 0
	global_load_lds_dwordx4 v[190:191], off
	s_waitcnt vmcnt(8)
	s_waitcnt lgkmcnt(0)
	s_barrier
	s_setprio 1
	v_mfma_f32_16x16x32_bf16 v[60:63], v[150:153], v[182:185], v[60:63]
	v_mfma_f32_16x16x32_bf16 v[56:59], v[158:161], v[182:185], v[56:59]
	v_mfma_f32_16x16x32_bf16 v[44:47], v[150:153], v[194:197], v[44:47]
	v_mfma_f32_16x16x32_bf16 v[40:43], v[158:161], v[194:197], v[40:43]
	v_mfma_f32_16x16x32_bf16 v[28:31], v[150:153], v[202:205], v[28:31]
	v_mfma_f32_16x16x32_bf16 v[24:27], v[158:161], v[202:205], v[24:27]
	v_mfma_f32_16x16x32_bf16 v[12:15], v[150:153], v[210:213], v[12:15]
	v_mfma_f32_16x16x32_bf16 v[8:11], v[158:161], v[210:213], v[8:11]
	v_mfma_f32_16x16x32_bf16 v[60:63], v[154:157], v[186:189], v[60:63]
	v_mfma_f32_16x16x32_bf16 v[56:59], v[162:165], v[186:189], v[56:59]
	v_mfma_f32_16x16x32_bf16 v[44:47], v[154:157], v[198:201], v[44:47]
	v_mfma_f32_16x16x32_bf16 v[40:43], v[162:165], v[198:201], v[40:43]
	v_mfma_f32_16x16x32_bf16 v[28:31], v[154:157], v[206:209], v[28:31]
	v_mfma_f32_16x16x32_bf16 v[24:27], v[162:165], v[206:209], v[24:27]
	v_mfma_f32_16x16x32_bf16 v[12:15], v[154:157], v[214:217], v[12:15]
	v_mfma_f32_16x16x32_bf16 v[8:11], v[162:165], v[214:217], v[8:11]
	v_mfma_f32_16x16x32_bf16 v[52:55], v[166:169], v[182:185], v[52:55]
	v_mfma_f32_16x16x32_bf16 v[48:51], v[174:177], v[182:185], v[48:51]
	v_mfma_f32_16x16x32_bf16 v[36:39], v[166:169], v[194:197], v[36:39]
	v_mfma_f32_16x16x32_bf16 v[32:35], v[174:177], v[194:197], v[32:35]
	v_mfma_f32_16x16x32_bf16 v[20:23], v[166:169], v[202:205], v[20:23]
	v_mfma_f32_16x16x32_bf16 v[16:19], v[174:177], v[202:205], v[16:19]
	v_mfma_f32_16x16x32_bf16 v[4:7], v[166:169], v[210:213], v[4:7]
	v_mfma_f32_16x16x32_bf16 v[0:3], v[174:177], v[210:213], v[0:3]
	v_mfma_f32_16x16x32_bf16 v[52:55], v[170:173], v[186:189], v[52:55]
	v_mfma_f32_16x16x32_bf16 v[48:51], v[178:181], v[186:189], v[48:51]
	v_mfma_f32_16x16x32_bf16 v[36:39], v[170:173], v[198:201], v[36:39]
	v_mfma_f32_16x16x32_bf16 v[32:35], v[178:181], v[198:201], v[32:35]
	v_mfma_f32_16x16x32_bf16 v[20:23], v[170:173], v[206:209], v[20:23]
	v_mfma_f32_16x16x32_bf16 v[16:19], v[178:181], v[206:209], v[16:19]
	v_mfma_f32_16x16x32_bf16 v[4:7], v[170:173], v[214:217], v[4:7]
	v_mfma_f32_16x16x32_bf16 v[0:3], v[178:181], v[214:217], v[0:3]
	s_setprio 0
	s_barrier
	s_add_u32 s60, s60, 0x100
	s_addc_u32 s61, s61, 0
	s_add_u32 s33, s33, 0x100
	s_addc_u32 s89, s89, 0
	s_cmp_ge_i32 s90, s72
	s_mov_b32 s62, s90
	s_cbranch_scc0 .LBB0_284

; #define PG8_STAGE(bufoff, gbase, voff) do { _Pragma("unroll") for (int _i = 0; _i < 2; ++_i) \
;         __builtin_amdgcn_global_load_lds((const unsigned*)((const char*)(gbase) + (voff)[_i]), (PG8_LAS unsigned*)(lds + (bufoff) + ldsw + _i * 8192), 16, 0, 0); } while (0)
; #define PG8_LDA(dst, b, h) do { _Pragma("unroll") for (int m = 0; m < 4; ++m) _Pragma("unroll") for (int k = 0; k < 2; ++k) dst[m][k] = *(const PG8_LAS bf16x8*)(lds + PG8_SA(b, h) + aoff + m * 2048 + k * 1024); } while (0)
; #define PG8_LDB(dst, b, h) do { _Pragma("unroll") for (int n = 0; n < 2; ++n) _Pragma("unroll") for (int k = 0; k < 2; ++k) dst[n][k] = *(const PG8_LAS bf16x8*)(lds + PG8_SB(b, h) + boff + n * 2048 + k * 1024); } while (0)
; #define PG8_MMA(ai, bj, At, Bt) do { __builtin_amdgcn_s_setprio(1); _Pragma("unroll") for (int m = 0; m < 4; ++m) _Pragma("unroll") for (int n = 0; n < 2; ++n) _Pragma("unroll") for (int k = 0; k < 2; ++k) \
;         acc[ai][bj][m][n] = __builtin_amdgcn_mfma_f32_16x16x32_bf16(Bt[n][k], At[m][k], acc[ai][bj][m][n], 0, 0, 0); __builtin_amdgcn_s_setprio(0); } while (0)
; #define PG8_WAIT_V(n) asm volatile("s_waitcnt vmcnt(" #n ")" ::: "memory")
; #define PG8_BAR __builtin_amdgcn_s_barrier()
; template <class Epi, class Sched, bool ALIGN_EPI = false, bool SP2 = false>
; __device__ __forceinline__ void gemm_phase(PG8_LAS unsigned char* lds, const Gemm g, const Sched& S, const Epi& E) {
;     ...
;         for (int t = 0; t < nt; t += 2) {
;             const bool last = (t == nt - 2);
;             const char* a1 = cA + (size_t)(t + 1) * kstep;
;             const char* a2 = last ? nA : cA + (size_t)(t + 2) * kstep; const char* b2 = last ? nB : cB + (size_t)(t + 2) * kstep;
;             const char* a3 = a2 + kstep; const char* b3 = b2 + kstep;
;             if (last && has_next) S.a_ready(nxt);
;             if constexpr (SP2) {
;             PG8_LDB(B0, 0, 0); PG8_LDB(B1, 0, 1); PG8_SCHED; PG8_LDA(At, 0, 0); PG8_STAGE(PG8_SA(1, 1), a1 + hstep, voffA);
;             PG8_WAIT_V(8); PG8_WAIT_L(0); PG8_BAR; PG8_MMA(0, 0, At, B0); PG8_MMA(0, 1, At, B1); PG8_BAR; PG8_SCHED;
;             PG8_LDA(At, 0, 1); PG8_STAGE(PG8_SB(0, 0), b2, voffB); PG8_STAGE(PG8_SB(0, 1), b2 + hstep, voffB); PG8_STAGE(PG8_SA(0, 0), a2, voffA);
;             PG8_WAIT_V(8); PG8_WAIT_L(0); PG8_BAR; PG8_MMA(1, 0, At, B0); PG8_MMA(1, 1, At, B1); PG8_BAR; PG8_SCHED;
.LBB0_368:
	ds_read_b128 v[144:147], v248
	ds_read_b128 v[148:151], v248 offset:1024
	ds_read_b128 v[152:155], v248 offset:2048
	ds_read_b128 v[156:159], v248 offset:3072
	ds_read_b128 v[160:163], v249
	ds_read_b128 v[164:167], v249 offset:1024
	ds_read_b128 v[168:171], v249 offset:2048
	ds_read_b128 v[172:175], v249 offset:3072
	s_add_i32 s38, s33, 2
	s_add_u32 s60, s58, 0x80
	s_addc_u32 s61, s59, 0
	s_cmp_eq_u32 s68, s33
	s_cselect_b32 s61, s11, s61
	s_cselect_b32 s60, s10, s60
	s_cselect_b32 s79, s57, s5
	s_cselect_b32 s78, s56, s4
	v_lshl_add_u64 v[210:211], s[58:59], 0, v[138:139]
	s_add_i32 m0, s39, 0xc000
	ds_read_b128 v[176:179], v250
	ds_read_b128 v[180:183], v250 offset:1024
	ds_read_b128 v[184:187], v250 offset:2048
	ds_read_b128 v[188:191], v250 offset:3072
	ds_read_b128 v[194:197], v250 offset:4096
	ds_read_b128 v[198:201], v250 offset:5120
	ds_read_b128 v[202:205], v250 offset:6144
	ds_read_b128 v[206:209], v250 offset:7168
	global_load_lds_dwordx4 v[210:211], off
	v_lshl_add_u64 v[210:211], s[58:59], 0, v[140:141]
	s_add_i32 m0, s39, 0xe000
	s_nop 0
	global_load_lds_dwordx4 v[210:211], off
	s_waitcnt vmcnt(8)
	s_waitcnt lgkmcnt(0)
	s_barrier
	s_setprio 1
	v_mfma_f32_16x16x32_bf16 v[124:127], v[144:147], v[176:179], v[124:127]
	v_mfma_f32_16x16x32_bf16 v[120:123], v[152:155], v[176:179], v[120:123]
	v_mfma_f32_16x16x32_bf16 v[116:119], v[144:147], v[184:187], v[116:119]
	v_mfma_f32_16x16x32_bf16 v[112:115], v[152:155], v[184:187], v[112:115]
	v_mfma_f32_16x16x32_bf16 v[104:107], v[144:147], v[194:197], v[104:107]
	v_mfma_f32_16x16x32_bf16 v[96:99], v[152:155], v[194:197], v[96:99]
	v_mfma_f32_16x16x32_bf16 v[88:91], v[144:147], v[202:205], v[88:91]
	v_mfma_f32_16x16x32_bf16 v[80:83], v[152:155], v[202:205], v[80:83]
	v_mfma_f32_16x16x32_bf16 v[124:127], v[148:151], v[180:183], v[124:127]
	v_mfma_f32_16x16x32_bf16 v[120:123], v[156:159], v[180:183], v[120:123]
	v_mfma_f32_16x16x32_bf16 v[116:119], v[148:151], v[188:191], v[116:119]
	v_mfma_f32_16x16x32_bf16 v[112:115], v[156:159], v[188:191], v[112:115]
	v_mfma_f32_16x16x32_bf16 v[104:107], v[148:151], v[198:201], v[104:107]
	v_mfma_f32_16x16x32_bf16 v[96:99], v[156:159], v[198:201], v[96:99]
	v_mfma_f32_16x16x32_bf16 v[88:91], v[148:151], v[206:209], v[88:91]
	v_mfma_f32_16x16x32_bf16 v[80:83], v[156:159], v[206:209], v[80:83]
	v_mfma_f32_16x16x32_bf16 v[108:111], v[160:163], v[176:179], v[108:111]
	v_mfma_f32_16x16x32_bf16 v[100:103], v[168:171], v[176:179], v[100:103]
	v_mfma_f32_16x16x32_bf16 v[92:95], v[160:163], v[184:187], v[92:95]
	v_mfma_f32_16x16x32_bf16 v[84:87], v[168:171], v[184:187], v[84:87]
	v_mfma_f32_16x16x32_bf16 v[76:79], v[160:163], v[194:197], v[76:79]
	v_mfma_f32_16x16x32_bf16 v[72:75], v[168:171], v[194:197], v[72:75]
	v_mfma_f32_16x16x32_bf16 v[68:71], v[160:163], v[202:205], v[68:71]
	v_mfma_f32_16x16x32_bf16 v[64:67], v[168:171], v[202:205], v[64:67]
	v_mfma_f32_16x16x32_bf16 v[108:111], v[164:167], v[180:183], v[108:111]
	v_mfma_f32_16x16x32_bf16 v[100:103], v[172:175], v[180:183], v[100:103]
	v_mfma_f32_16x16x32_bf16 v[92:95], v[164:167], v[188:191], v[92:95]
	v_mfma_f32_16x16x32_bf16 v[84:87], v[172:175], v[188:191], v[84:87]
	v_mfma_f32_16x16x32_bf16 v[76:79], v[164:167], v[198:201], v[76:79]
	v_mfma_f32_16x16x32_bf16 v[72:75], v[172:175], v[198:201], v[72:75]
	v_mfma_f32_16x16x32_bf16 v[68:71], v[164:167], v[206:209], v[68:71]
	v_mfma_f32_16x16x32_bf16 v[64:67], v[172:175], v[206:209], v[64:67]
	s_setprio 0
	s_barrier
	s_add_i32 s33, s72, s3
	v_lshl_add_u64 v[210:211], s[78:79], 0, v[132:133]
	s_mov_b32 m0, s33
	ds_read_b128 v[176:179], v250 offset:16384
	ds_read_b128 v[180:183], v250 offset:17408
	ds_read_b128 v[184:187], v250 offset:18432
	ds_read_b128 v[188:191], v250 offset:19456
	ds_read_b128 v[194:197], v250 offset:20480
	ds_read_b128 v[198:201], v250 offset:21504
	ds_read_b128 v[202:205], v250 offset:22528
	ds_read_b128 v[206:209], v250 offset:23552
	global_load_lds_dwordx4 v[210:211], off
	s_add_i32 m0, s33, 0x2000
	v_lshl_add_u64 v[212:213], s[78:79], 0, v[136:137]
	s_add_u32 s78, s78, s16
	s_addc_u32 s79, s79, s17
	s_add_i32 s33, s73, s3
	global_load_lds_dwordx4 v[212:213], off
	v_lshl_add_u64 v[214:215], s[78:79], 0, v[132:133]
	s_mov_b32 m0, s33
	v_lshl_add_u64 v[216:217], s[78:79], 0, v[136:137]
	global_load_lds_dwordx4 v[214:215], off
	s_add_i32 m0, s33, 0x2000
	v_lshl_add_u64 v[218:219], s[60:61], 0, v[130:131]
	global_load_lds_dwordx4 v[216:217], off
	s_mov_b32 m0, s39
	v_lshl_add_u64 v[220:221], s[60:61], 0, v[134:135]
	global_load_lds_dwordx4 v[218:219], off
	s_mov_b32 m0, s49
	s_nop 0
	global_load_lds_dwordx4 v[220:221], off
	s_waitcnt vmcnt(8)
	s_waitcnt lgkmcnt(0)
	s_barrier
; #define PG8_STAGE(bufoff, gbase, voff) do { _Pragma("unroll") for (int _i = 0; _i < 2; ++_i) \
;         __builtin_amdgcn_global_load_lds((const unsigned*)((const char*)(gbase) + (voff)[_i]), (PG8_LAS unsigned*)(lds + (bufoff) + ldsw + _i * 8192), 16, 0, 0); } while (0)
; #define PG8_LDA(dst, b, h) do { _Pragma("unroll") for (int m = 0; m < 4; ++m) _Pragma("unroll") for (int k = 0; k < 2; ++k) dst[m][k] = *(const PG8_LAS bf16x8*)(lds + PG8_SA(b, h) + aoff + m * 2048 + k * 1024); } while (0)
; #define PG8_LDB(dst, b, h) do { _Pragma("unroll") for (int n = 0; n < 2; ++n) _Pragma("unroll") for (int k = 0; k < 2; ++k) dst[n][k] = *(const PG8_LAS bf16x8*)(lds + PG8_SB(b, h) + boff + n * 2048 + k * 1024); } while (0)
; #define PG8_MMA(ai, bj, At, Bt) do { __builtin_amdgcn_s_setprio(1); _Pragma("unroll") for (int m = 0; m < 4; ++m) _Pragma("unroll") for (int n = 0; n < 2; ++n) _Pragma("unroll") for (int k = 0; k < 2; ++k) \
;         acc[ai][bj][m][n] = __builtin_amdgcn_mfma_f32_16x16x32_bf16(Bt[n][k], At[m][k], acc[ai][bj][m][n], 0, 0, 0); __builtin_amdgcn_s_setprio(0); } while (0)
; #define PG8_WAIT_V(n) asm volatile("s_waitcnt vmcnt(" #n ")" ::: "memory")
; #define PG8_WAIT_L(n) asm volatile("s_waitcnt lgkmcnt(" #n ")" ::: "memory")
; #define PG8_BAR __builtin_amdgcn_s_barrier()
; #define PG8_SCHED __builtin_amdgcn_sched_barrier(0)
; template <class Epi, class Sched, bool ALIGN_EPI = false, bool SP2 = false>
; __device__ __forceinline__ void gemm_phase(PG8_LAS unsigned char* lds, const Gemm g, const Sched& S, const Epi& E) {
;     ...
;             PG8_WAIT_V(8); PG8_WAIT_L(0); PG8_BAR; PG8_MMA(1, 0, At, B0); PG8_MMA(1, 1, At, B1); PG8_BAR; PG8_SCHED;
;             PG8_LDB(B0, 1, 0); PG8_LDB(B1, 1, 1); PG8_SCHED; PG8_LDA(At, 1, 0); PG8_STAGE(PG8_SA(0, 1), a2 + hstep, voffA);
;             PG8_WAIT_V(8); PG8_WAIT_L(0); PG8_BAR; PG8_MMA(0, 0, At, B0); PG8_MMA(0, 1, At, B1); PG8_BAR; PG8_SCHED;
	s_setprio 1
	v_mfma_f32_16x16x32_bf16 v[60:63], v[144:147], v[176:179], v[60:63]
	v_mfma_f32_16x16x32_bf16 v[56:59], v[152:155], v[176:179], v[56:59]
	v_mfma_f32_16x16x32_bf16 v[52:55], v[144:147], v[184:187], v[52:55]
	v_mfma_f32_16x16x32_bf16 v[48:51], v[152:155], v[184:187], v[48:51]
	v_mfma_f32_16x16x32_bf16 v[40:43], v[144:147], v[194:197], v[40:43]
	v_mfma_f32_16x16x32_bf16 v[32:35], v[152:155], v[194:197], v[32:35]
	v_mfma_f32_16x16x32_bf16 v[24:27], v[144:147], v[202:205], v[24:27]
	v_mfma_f32_16x16x32_bf16 v[16:19], v[152:155], v[202:205], v[16:19]
	v_mfma_f32_16x16x32_bf16 v[60:63], v[148:151], v[180:183], v[60:63]
	v_mfma_f32_16x16x32_bf16 v[56:59], v[156:159], v[180:183], v[56:59]
	v_mfma_f32_16x16x32_bf16 v[52:55], v[148:151], v[188:191], v[52:55]
	v_mfma_f32_16x16x32_bf16 v[48:51], v[156:159], v[188:191], v[48:51]
	v_mfma_f32_16x16x32_bf16 v[40:43], v[148:151], v[198:201], v[40:43]
	v_mfma_f32_16x16x32_bf16 v[32:35], v[156:159], v[198:201], v[32:35]
	v_mfma_f32_16x16x32_bf16 v[24:27], v[148:151], v[206:209], v[24:27]
	v_mfma_f32_16x16x32_bf16 v[16:19], v[156:159], v[206:209], v[16:19]
	v_mfma_f32_16x16x32_bf16 v[44:47], v[160:163], v[176:179], v[44:47]
	v_mfma_f32_16x16x32_bf16 v[36:39], v[168:171], v[176:179], v[36:39]
	v_mfma_f32_16x16x32_bf16 v[28:31], v[160:163], v[184:187], v[28:31]
	v_mfma_f32_16x16x32_bf16 v[20:23], v[168:171], v[184:187], v[20:23]
	v_mfma_f32_16x16x32_bf16 v[12:15], v[160:163], v[194:197], v[12:15]
	v_mfma_f32_16x16x32_bf16 v[8:11], v[168:171], v[194:197], v[8:11]
	v_mfma_f32_16x16x32_bf16 v[4:7], v[160:163], v[202:205], v[4:7]
	v_mfma_f32_16x16x32_bf16 v[0:3], v[168:171], v[202:205], v[0:3]
	v_mfma_f32_16x16x32_bf16 v[44:47], v[164:167], v[180:183], v[44:47]
	v_mfma_f32_16x16x32_bf16 v[36:39], v[172:175], v[180:183], v[36:39]
	v_mfma_f32_16x16x32_bf16 v[28:31], v[164:167], v[188:191], v[28:31]
	v_mfma_f32_16x16x32_bf16 v[20:23], v[172:175], v[188:191], v[20:23]
	v_mfma_f32_16x16x32_bf16 v[12:15], v[164:167], v[198:201], v[12:15]
	v_mfma_f32_16x16x32_bf16 v[8:11], v[172:175], v[198:201], v[8:11]
	v_mfma_f32_16x16x32_bf16 v[4:7], v[164:167], v[206:209], v[4:7]
	v_mfma_f32_16x16x32_bf16 v[0:3], v[172:175], v[206:209], v[0:3]
	s_setprio 0
	s_barrier
	s_add_i32 s33, 0, 0x18000
	v_add_u32_e32 v128, s33, v193
	s_add_i32 s77, 0, 0x1c000
	ds_read_b128 v[144:147], v128
	ds_read_b128 v[148:151], v128 offset:1024
	ds_read_b128 v[152:155], v128 offset:2048
	ds_read_b128 v[156:159], v128 offset:3072
	v_add_u32_e32 v128, s77, v193
	ds_read_b128 v[160:163], v128
	ds_read_b128 v[164:167], v128 offset:1024
	ds_read_b128 v[168:171], v128 offset:2048
	ds_read_b128 v[172:175], v128 offset:3072
	s_add_u32 s60, s60, s16
	s_addc_u32 s61, s61, s17
	s_mov_b32 m0, s62
	v_lshl_add_u64 v[222:223], s[60:61], 0, v[130:131]
	ds_read_b128 v[176:179], v250 offset:32768
	ds_read_b128 v[180:183], v250 offset:33792
	ds_read_b128 v[184:187], v250 offset:34816
	ds_read_b128 v[188:191], v250 offset:35840
	ds_read_b128 v[194:197], v250 offset:36864
	ds_read_b128 v[198:201], v250 offset:37888
	ds_read_b128 v[202:205], v250 offset:38912
	ds_read_b128 v[206:209], v250 offset:39936
	global_load_lds_dwordx4 v[222:223], off
	v_lshl_add_u64 v[222:223], s[60:61], 0, v[134:135]
	s_mov_b32 m0, s63
	s_nop 0
	global_load_lds_dwordx4 v[222:223], off
	s_waitcnt vmcnt(8)
	s_waitcnt lgkmcnt(0)
	s_barrier
	s_setprio 1
	v_mfma_f32_16x16x32_bf16 v[124:127], v[144:147], v[176:179], v[124:127]
	v_mfma_f32_16x16x32_bf16 v[120:123], v[152:155], v[176:179], v[120:123]
	v_mfma_f32_16x16x32_bf16 v[116:119], v[144:147], v[184:187], v[116:119]
	v_mfma_f32_16x16x32_bf16 v[112:115], v[152:155], v[184:187], v[112:115]
	v_mfma_f32_16x16x32_bf16 v[104:107], v[144:147], v[194:197], v[104:107]
	v_mfma_f32_16x16x32_bf16 v[96:99], v[152:155], v[194:197], v[96:99]
	v_mfma_f32_16x16x32_bf16 v[88:91], v[144:147], v[202:205], v[88:91]
	v_mfma_f32_16x16x32_bf16 v[80:83], v[152:155], v[202:205], v[80:83]
	v_mfma_f32_16x16x32_bf16 v[124:127], v[148:151], v[180:183], v[124:127]
	v_mfma_f32_16x16x32_bf16 v[120:123], v[156:159], v[180:183], v[120:123]
	v_mfma_f32_16x16x32_bf16 v[116:119], v[148:151], v[188:191], v[116:119]
	v_mfma_f32_16x16x32_bf16 v[112:115], v[156:159], v[188:191], v[112:115]
	v_mfma_f32_16x16x32_bf16 v[104:107], v[148:151], v[198:201], v[104:107]
	v_mfma_f32_16x16x32_bf16 v[96:99], v[156:159], v[198:201], v[96:99]
	v_mfma_f32_16x16x32_bf16 v[88:91], v[148:151], v[206:209], v[88:91]
	v_mfma_f32_16x16x32_bf16 v[80:83], v[156:159], v[206:209], v[80:83]
	v_mfma_f32_16x16x32_bf16 v[108:111], v[160:163], v[176:179], v[108:111]
	v_mfma_f32_16x16x32_bf16 v[100:103], v[168:171], v[176:179], v[100:103]
	v_mfma_f32_16x16x32_bf16 v[92:95], v[160:163], v[184:187], v[92:95]
	v_mfma_f32_16x16x32_bf16 v[84:87], v[168:171], v[184:187], v[84:87]
	v_mfma_f32_16x16x32_bf16 v[76:79], v[160:163], v[194:197], v[76:79]
	v_mfma_f32_16x16x32_bf16 v[72:75], v[168:171], v[194:197], v[72:75]
	v_mfma_f32_16x16x32_bf16 v[68:71], v[160:163], v[202:205], v[68:71]
	v_mfma_f32_16x16x32_bf16 v[64:67], v[168:171], v[202:205], v[64:67]
	v_mfma_f32_16x16x32_bf16 v[108:111], v[164:167], v[180:183], v[108:111]
	v_mfma_f32_16x16x32_bf16 v[100:103], v[172:175], v[180:183], v[100:103]
	v_mfma_f32_16x16x32_bf16 v[92:95], v[164:167], v[188:191], v[92:95]
	v_mfma_f32_16x16x32_bf16 v[84:87], v[172:175], v[188:191], v[84:87]
	v_mfma_f32_16x16x32_bf16 v[76:79], v[164:167], v[198:201], v[76:79]
	v_mfma_f32_16x16x32_bf16 v[72:75], v[172:175], v[198:201], v[72:75]
	v_mfma_f32_16x16x32_bf16 v[68:71], v[164:167], v[206:209], v[68:71]
	v_mfma_f32_16x16x32_bf16 v[64:67], v[172:175], v[206:209], v[64:67]
	s_setprio 0
	s_barrier
; #define PG8_STAGE(bufoff, gbase, voff) do { _Pragma("unroll") for (int _i = 0; _i < 2; ++_i) \
;         __builtin_amdgcn_global_load_lds((const unsigned*)((const char*)(gbase) + (voff)[_i]), (PG8_LAS unsigned*)(lds + (bufoff) + ldsw + _i * 8192), 16, 0, 0); } while (0)
; #define PG8_LDA(dst, b, h) do { _Pragma("unroll") for (int m = 0; m < 4; ++m) _Pragma("unroll") for (int k = 0; k < 2; ++k) dst[m][k] = *(const PG8_LAS bf16x8*)(lds + PG8_SA(b, h) + aoff + m * 2048 + k * 1024); } while (0)
; #define PG8_MMA(ai, bj, At, Bt) do { __builtin_amdgcn_s_setprio(1); _Pragma("unroll") for (int m = 0; m < 4; ++m) _Pragma("unroll") for (int n = 0; n < 2; ++n) _Pragma("unroll") for (int k = 0; k < 2; ++k) \
;         acc[ai][bj][m][n] = __builtin_amdgcn_mfma_f32_16x16x32_bf16(Bt[n][k], At[m][k], acc[ai][bj][m][n], 0, 0, 0); __builtin_amdgcn_s_setprio(0); } while (0)
; #define PG8_WAIT_V(n) asm volatile("s_waitcnt vmcnt(" #n ")" ::: "memory")
; #define PG8_WAIT_L(n) asm volatile("s_waitcnt lgkmcnt(" #n ")" ::: "memory")
; #define PG8_BAR __builtin_amdgcn_s_barrier()
; #define PG8_SCHED __builtin_amdgcn_sched_barrier(0)
; template <class Epi, class Sched, bool ALIGN_EPI = false, bool SP2 = false>
; __device__ __forceinline__ void gemm_phase(PG8_LAS unsigned char* lds, const Gemm g, const Sched& S, const Epi& E) {
;     ...
;             PG8_LDA(At, 1, 1); PG8_STAGE(PG8_SB(1, 0), b3, voffB); PG8_STAGE(PG8_SB(1, 1), b3 + hstep, voffB); PG8_STAGE(PG8_SA(1, 0), a3, voffA);
;             PG8_WAIT_V(8); PG8_WAIT_L(0); PG8_BAR; PG8_MMA(1, 0, At, B0); PG8_MMA(1, 1, At, B1); PG8_BAR; PG8_SCHED;
	s_add_i32 s33, s33, s3
	v_lshl_add_u64 v[210:211], v[210:211], 0, s[36:37]
	s_mov_b32 m0, s33
	ds_read_b128 v[176:179], v250 offset:49152
	ds_read_b128 v[180:183], v250 offset:50176
	ds_read_b128 v[184:187], v250 offset:51200
	ds_read_b128 v[188:191], v250 offset:52224
	ds_read_b128 v[194:197], v250 offset:53248
	ds_read_b128 v[198:201], v250 offset:54272
	ds_read_b128 v[202:205], v250 offset:55296
	ds_read_b128 v[206:209], v250 offset:56320
	global_load_lds_dwordx4 v[210:211], off
	v_lshl_add_u64 v[210:211], v[212:213], 0, s[36:37]
	s_add_i32 m0, s33, 0x2000
	s_add_i32 s33, s77, s3
	global_load_lds_dwordx4 v[210:211], off
	v_lshl_add_u64 v[210:211], v[214:215], 0, s[36:37]
	s_mov_b32 m0, s33
	s_nop 0
	global_load_lds_dwordx4 v[210:211], off
	v_lshl_add_u64 v[210:211], v[216:217], 0, s[36:37]
	s_add_i32 m0, s33, 0x2000
	s_nop 0
	global_load_lds_dwordx4 v[210:211], off
	v_lshl_add_u64 v[210:211], v[218:219], 0, s[36:37]
	s_mov_b32 m0, s64
	s_nop 0
	global_load_lds_dwordx4 v[210:211], off
	v_lshl_add_u64 v[210:211], v[220:221], 0, s[36:37]
	s_mov_b32 m0, s65
	s_nop 0
	global_load_lds_dwordx4 v[210:211], off
	s_waitcnt vmcnt(8)
	s_waitcnt lgkmcnt(0)
	s_barrier
	s_setprio 1
	v_mfma_f32_16x16x32_bf16 v[60:63], v[144:147], v[176:179], v[60:63]
	v_mfma_f32_16x16x32_bf16 v[56:59], v[152:155], v[176:179], v[56:59]
	v_mfma_f32_16x16x32_bf16 v[52:55], v[144:147], v[184:187], v[52:55]
	v_mfma_f32_16x16x32_bf16 v[48:51], v[152:155], v[184:187], v[48:51]
	v_mfma_f32_16x16x32_bf16 v[40:43], v[144:147], v[194:197], v[40:43]
	v_mfma_f32_16x16x32_bf16 v[32:35], v[152:155], v[194:197], v[32:35]
	v_mfma_f32_16x16x32_bf16 v[24:27], v[144:147], v[202:205], v[24:27]
	v_mfma_f32_16x16x32_bf16 v[16:19], v[152:155], v[202:205], v[16:19]
	v_mfma_f32_16x16x32_bf16 v[60:63], v[148:151], v[180:183], v[60:63]
	v_mfma_f32_16x16x32_bf16 v[56:59], v[156:159], v[180:183], v[56:59]
	v_mfma_f32_16x16x32_bf16 v[52:55], v[148:151], v[188:191], v[52:55]
	v_mfma_f32_16x16x32_bf16 v[48:51], v[156:159], v[188:191], v[48:51]
	v_mfma_f32_16x16x32_bf16 v[40:43], v[148:151], v[198:201], v[40:43]
	v_mfma_f32_16x16x32_bf16 v[32:35], v[156:159], v[198:201], v[32:35]
	v_mfma_f32_16x16x32_bf16 v[24:27], v[148:151], v[206:209], v[24:27]
	v_mfma_f32_16x16x32_bf16 v[16:19], v[156:159], v[206:209], v[16:19]
	v_mfma_f32_16x16x32_bf16 v[44:47], v[160:163], v[176:179], v[44:47]
	v_mfma_f32_16x16x32_bf16 v[36:39], v[168:171], v[176:179], v[36:39]
	v_mfma_f32_16x16x32_bf16 v[28:31], v[160:163], v[184:187], v[28:31]
	v_mfma_f32_16x16x32_bf16 v[20:23], v[168:171], v[184:187], v[20:23]
	v_mfma_f32_16x16x32_bf16 v[12:15], v[160:163], v[194:197], v[12:15]
	v_mfma_f32_16x16x32_bf16 v[8:11], v[168:171], v[194:197], v[8:11]
	v_mfma_f32_16x16x32_bf16 v[4:7], v[160:163], v[202:205], v[4:7]
	v_mfma_f32_16x16x32_bf16 v[0:3], v[168:171], v[202:205], v[0:3]
	v_mfma_f32_16x16x32_bf16 v[44:47], v[164:167], v[180:183], v[44:47]
	v_mfma_f32_16x16x32_bf16 v[36:39], v[172:175], v[180:183], v[36:39]
	v_mfma_f32_16x16x32_bf16 v[28:31], v[164:167], v[188:191], v[28:31]
	v_mfma_f32_16x16x32_bf16 v[20:23], v[172:175], v[188:191], v[20:23]
	v_mfma_f32_16x16x32_bf16 v[12:15], v[164:167], v[198:201], v[12:15]
	v_mfma_f32_16x16x32_bf16 v[8:11], v[172:175], v[198:201], v[8:11]
	v_mfma_f32_16x16x32_bf16 v[4:7], v[164:167], v[206:209], v[4:7]
	v_mfma_f32_16x16x32_bf16 v[0:3], v[172:175], v[206:209], v[0:3]
	s_setprio 0
	s_barrier
	s_add_u32 s58, s58, 0x100
	s_addc_u32 s59, s59, 0
	s_add_u32 s4, s4, 0x100
	s_addc_u32 s5, s5, 0
	s_cmp_ge_i32 s38, s67
	s_mov_b32 s33, s38
	s_cbranch_scc0 .LBB0_368
;     __device__ __forceinline__ void operator()(const f32x4 (&acc)[2][2][4][2], const Unit& u, int wr, int wc, int fr, int fq) const {
;     ...
;                 const u32x4 b0 = rb[ai][m][0], b1 = rb[ai][m][1];
;                 float ss = 0.f;
; #pragma unroll
;                 for (int bj = 0; bj < 2; ++bj) {
;                     const u32x4 b = bj ? b1 : b0;
;                     f32x4 v0, v1;
;                     v0[0] = __uint_as_float(b.x << 16); v0[1] = __uint_as_float(b.x & 0xffff0000u); v0[2] = __uint_as_float(b.y << 16); v0[3] = __uint_as_float(b.y & 0xffff0000u);
;                     v1[0] = __uint_as_float(b.z << 16); v1[1] = __uint_as_float(b.z & 0xffff0000u); v1[2] = __uint_as_float(b.w << 16); v1[3] = __uint_as_float(b.w & 0xffff0000u);
;                     v0 += acc[ai][bj][m][0] * alpha; v1 += acc[ai][bj][m][1] * alpha;
	v_pk_mul_f32 v[222:223], v[126:127], 0.5 op_sel_hi:[1,0]
	v_pk_mul_f32 v[224:225], v[124:125], 0.5 op_sel_hi:[1,0]
	v_pk_mul_f32 v[226:227], v[122:123], 0.5 op_sel_hi:[1,0]
	v_pk_mul_f32 v[228:229], v[120:121], 0.5 op_sel_hi:[1,0]
	v_pk_mul_f32 v[216:217], v[110:111], 0.5 op_sel_hi:[1,0]
	v_pk_mul_f32 v[214:215], v[108:109], 0.5 op_sel_hi:[1,0]
	v_pk_mul_f32 v[212:213], v[102:103], 0.5 op_sel_hi:[1,0]
	v_pk_mul_f32 v[208:209], v[100:101], 0.5 op_sel_hi:[1,0]
	v_pk_mul_f32 v[200:201], v[118:119], 0.5 op_sel_hi:[1,0]
	v_pk_mul_f32 v[198:199], v[116:117], 0.5 op_sel_hi:[1,0]
	v_pk_mul_f32 v[196:197], v[114:115], 0.5 op_sel_hi:[1,0]
	v_pk_mul_f32 v[194:195], v[112:113], 0.5 op_sel_hi:[1,0]
	v_pk_mul_f32 v[190:191], v[94:95], 0.5 op_sel_hi:[1,0]
	v_pk_mul_f32 v[188:189], v[92:93], 0.5 op_sel_hi:[1,0]
	v_pk_mul_f32 v[186:187], v[86:87], 0.5 op_sel_hi:[1,0]
	v_pk_mul_f32 v[184:185], v[84:85], 0.5 op_sel_hi:[1,0]
	v_pk_mul_f32 v[178:179], v[106:107], 0.5 op_sel_hi:[1,0]
	v_pk_mul_f32 v[176:177], v[104:105], 0.5 op_sel_hi:[1,0]
	v_pk_mul_f32 v[174:175], v[98:99], 0.5 op_sel_hi:[1,0]
	v_pk_mul_f32 v[172:173], v[96:97], 0.5 op_sel_hi:[1,0]
	v_pk_mul_f32 v[170:171], v[78:79], 0.5 op_sel_hi:[1,0]
	v_pk_mul_f32 v[168:169], v[76:77], 0.5 op_sel_hi:[1,0]
	v_pk_mul_f32 v[166:167], v[74:75], 0.5 op_sel_hi:[1,0]
	v_pk_mul_f32 v[164:165], v[72:73], 0.5 op_sel_hi:[1,0]
	v_pk_mul_f32 v[160:161], v[90:91], 0.5 op_sel_hi:[1,0]
	v_pk_mul_f32 v[158:159], v[88:89], 0.5 op_sel_hi:[1,0]
	v_pk_mul_f32 v[156:157], v[82:83], 0.5 op_sel_hi:[1,0]
	v_pk_mul_f32 v[154:155], v[80:81], 0.5 op_sel_hi:[1,0]
	v_pk_mul_f32 v[150:151], v[70:71], 0.5 op_sel_hi:[1,0]
	v_pk_mul_f32 v[148:149], v[68:69], 0.5 op_sel_hi:[1,0]
	v_pk_mul_f32 v[146:147], v[66:67], 0.5 op_sel_hi:[1,0]
	v_pk_mul_f32 v[144:145], v[64:65], 0.5 op_sel_hi:[1,0]
	v_pk_mul_f32 v[126:127], v[62:63], 0.5 op_sel_hi:[1,0]
	v_pk_mul_f32 v[124:125], v[60:61], 0.5 op_sel_hi:[1,0]
	v_pk_mul_f32 v[122:123], v[58:59], 0.5 op_sel_hi:[1,0]
	v_pk_mul_f32 v[120:121], v[56:57], 0.5 op_sel_hi:[1,0]
	v_pk_mul_f32 v[118:119], v[46:47], 0.5 op_sel_hi:[1,0]
	v_pk_mul_f32 v[116:117], v[44:45], 0.5 op_sel_hi:[1,0]
	v_pk_mul_f32 v[114:115], v[38:39], 0.5 op_sel_hi:[1,0]
	v_pk_mul_f32 v[112:113], v[36:37], 0.5 op_sel_hi:[1,0]
	v_pk_mul_f32 v[110:111], v[54:55], 0.5 op_sel_hi:[1,0]
	v_pk_mul_f32 v[108:109], v[52:53], 0.5 op_sel_hi:[1,0]
	v_pk_mul_f32 v[106:107], v[50:51], 0.5 op_sel_hi:[1,0]
	v_pk_mul_f32 v[104:105], v[48:49], 0.5 op_sel_hi:[1,0]
	v_pk_mul_f32 v[102:103], v[30:31], 0.5 op_sel_hi:[1,0]
	v_pk_mul_f32 v[100:101], v[28:29], 0.5 op_sel_hi:[1,0]
	v_pk_mul_f32 v[98:99], v[22:23], 0.5 op_sel_hi:[1,0]
	v_pk_mul_f32 v[96:97], v[20:21], 0.5 op_sel_hi:[1,0]
	v_pk_mul_f32 v[94:95], v[42:43], 0.5 op_sel_hi:[1,0]
	v_pk_mul_f32 v[92:93], v[40:41], 0.5 op_sel_hi:[1,0]
	v_pk_mul_f32 v[90:91], v[34:35], 0.5 op_sel_hi:[1,0]
	v_pk_mul_f32 v[88:89], v[32:33], 0.5 op_sel_hi:[1,0]
	v_pk_mul_f32 v[86:87], v[14:15], 0.5 op_sel_hi:[1,0]
	v_pk_mul_f32 v[84:85], v[12:13], 0.5 op_sel_hi:[1,0]
	v_pk_mul_f32 v[82:83], v[10:11], 0.5 op_sel_hi:[1,0]
	v_pk_mul_f32 v[80:81], v[8:9], 0.5 op_sel_hi:[1,0]
	v_pk_mul_f32 v[78:79], v[26:27], 0.5 op_sel_hi:[1,0]
	v_pk_mul_f32 v[76:77], v[24:25], 0.5 op_sel_hi:[1,0]
	v_pk_mul_f32 v[74:75], v[18:19], 0.5 op_sel_hi:[1,0]
	v_pk_mul_f32 v[72:73], v[16:17], 0.5 op_sel_hi:[1,0]
	v_pk_mul_f32 v[70:71], v[6:7], 0.5 op_sel_hi:[1,0]
	v_pk_mul_f32 v[68:69], v[4:5], 0.5 op_sel_hi:[1,0]
	v_pk_mul_f32 v[66:67], v[2:3], 0.5 op_sel_hi:[1,0]
	v_pk_mul_f32 v[64:65], v[0:1], 0.5 op_sel_hi:[1,0]

; #define PG8_STAGE(bufoff, gbase, voff) do { _Pragma("unroll") for (int _i = 0; _i < 2; ++_i) \
;         __builtin_amdgcn_global_load_lds((const unsigned*)((const char*)(gbase) + (voff)[_i]), (PG8_LAS unsigned*)(lds + (bufoff) + ldsw + _i * 8192), 16, 0, 0); } while (0)
; #define PG8_LDA(dst, b, h) do { _Pragma("unroll") for (int m = 0; m < 4; ++m) _Pragma("unroll") for (int k = 0; k < 2; ++k) dst[m][k] = *(const PG8_LAS bf16x8*)(lds + PG8_SA(b, h) + aoff + m * 2048 + k * 1024); } while (0)
; #define PG8_LDB(dst, b, h) do { _Pragma("unroll") for (int n = 0; n < 2; ++n) _Pragma("unroll") for (int k = 0; k < 2; ++k) dst[n][k] = *(const PG8_LAS bf16x8*)(lds + PG8_SB(b, h) + boff + n * 2048 + k * 1024); } while (0)
; #define PG8_MMA(ai, bj, At, Bt) do { __builtin_amdgcn_s_setprio(1); _Pragma("unroll") for (int m = 0; m < 4; ++m) _Pragma("unroll") for (int n = 0; n < 2; ++n) _Pragma("unroll") for (int k = 0; k < 2; ++k) \
;         acc[ai][bj][m][n] = __builtin_amdgcn_mfma_f32_16x16x32_bf16(Bt[n][k], At[m][k], acc[ai][bj][m][n], 0, 0, 0); __builtin_amdgcn_s_setprio(0); } while (0)
; #define PG8_WAIT_V(n) asm volatile("s_waitcnt vmcnt(" #n ")" ::: "memory")
; #define PG8_BAR __builtin_amdgcn_s_barrier()
; template <class Epi, class Sched, bool ALIGN_EPI = false, bool SP2 = false>
; __device__ __forceinline__ void gemm_phase(PG8_LAS unsigned char* lds, const Gemm g, const Sched& S, const Epi& E) {
;     ...
;         for (int t = 0; t < nt; t += 2) {
;             const bool last = (t == nt - 2);
;             const char* a1 = cA + (size_t)(t + 1) * kstep;
;             const char* a2 = last ? nA : cA + (size_t)(t + 2) * kstep; const char* b2 = last ? nB : cB + (size_t)(t + 2) * kstep;
;             const char* a3 = a2 + kstep; const char* b3 = b2 + kstep;
;             if (last && has_next) S.a_ready(nxt);
;             if constexpr (SP2) {
;             PG8_LDB(B0, 0, 0); PG8_LDB(B1, 0, 1); PG8_SCHED; PG8_LDA(At, 0, 0); PG8_STAGE(PG8_SA(1, 1), a1 + hstep, voffA);
;             PG8_WAIT_V(8); PG8_WAIT_L(0); PG8_BAR; PG8_MMA(0, 0, At, B0); PG8_MMA(0, 1, At, B1); PG8_BAR; PG8_SCHED;
;             PG8_LDA(At, 0, 1); PG8_STAGE(PG8_SB(0, 0), b2, voffB); PG8_STAGE(PG8_SB(0, 1), b2 + hstep, voffB); PG8_STAGE(PG8_SA(0, 0), a2, voffA);
;             PG8_WAIT_V(8); PG8_WAIT_L(0); PG8_BAR; PG8_MMA(1, 0, At, B0); PG8_MMA(1, 1, At, B1); PG8_BAR; PG8_SCHED;
.LBB0_473:
	ds_read_b128 v[150:153], v190
	ds_read_b128 v[154:157], v190 offset:1024
	ds_read_b128 v[158:161], v190 offset:2048
	ds_read_b128 v[162:165], v190 offset:3072
	ds_read_b128 v[166:169], v191
	ds_read_b128 v[170:173], v191 offset:1024
	ds_read_b128 v[174:177], v191 offset:2048
	ds_read_b128 v[178:181], v191 offset:3072
	s_add_i32 s15, s12, 2
	s_add_u32 s33, s10, 0x80
	s_addc_u32 s13, s11, 0
	s_cmp_eq_u32 s73, s12
	s_cselect_b32 s12, s60, s33
	s_cselect_b32 s13, s61, s13
	s_cselect_b32 s65, s63, s14
	s_cselect_b32 s64, s62, s5
	v_lshl_add_u64 v[186:187], s[10:11], 0, v[142:143]
	s_add_i32 m0, s66, 0xc000
	ds_read_b128 v[182:185], v193
	ds_read_b128 v[196:199], v193 offset:1024
	ds_read_b128 v[200:203], v193 offset:2048
	ds_read_b128 v[204:207], v193 offset:3072
	ds_read_b128 v[208:211], v193 offset:4096
	ds_read_b128 v[212:215], v193 offset:5120
	ds_read_b128 v[216:219], v193 offset:6144
	ds_read_b128 v[220:223], v193 offset:7168
	global_load_lds_dwordx4 v[186:187], off
	v_lshl_add_u64 v[186:187], s[10:11], 0, v[144:145]
	s_add_i32 m0, s66, 0xe000
	s_nop 0
	global_load_lds_dwordx4 v[186:187], off
	s_waitcnt vmcnt(8)
	s_waitcnt lgkmcnt(0)
	s_barrier
	s_setprio 1
	v_mfma_f32_16x16x32_bf16 v[124:127], v[150:153], v[182:185], v[124:127]
	v_mfma_f32_16x16x32_bf16 v[120:123], v[158:161], v[182:185], v[120:123]
	v_mfma_f32_16x16x32_bf16 v[108:111], v[150:153], v[200:203], v[108:111]
	v_mfma_f32_16x16x32_bf16 v[104:107], v[158:161], v[200:203], v[104:107]
	v_mfma_f32_16x16x32_bf16 v[92:95], v[150:153], v[208:211], v[92:95]
	v_mfma_f32_16x16x32_bf16 v[88:91], v[158:161], v[208:211], v[88:91]
	v_mfma_f32_16x16x32_bf16 v[76:79], v[150:153], v[216:219], v[76:79]
	v_mfma_f32_16x16x32_bf16 v[72:75], v[158:161], v[216:219], v[72:75]
	v_mfma_f32_16x16x32_bf16 v[124:127], v[154:157], v[196:199], v[124:127]
	v_mfma_f32_16x16x32_bf16 v[120:123], v[162:165], v[196:199], v[120:123]
	v_mfma_f32_16x16x32_bf16 v[108:111], v[154:157], v[204:207], v[108:111]
	v_mfma_f32_16x16x32_bf16 v[104:107], v[162:165], v[204:207], v[104:107]
	v_mfma_f32_16x16x32_bf16 v[92:95], v[154:157], v[212:215], v[92:95]
	v_mfma_f32_16x16x32_bf16 v[88:91], v[162:165], v[212:215], v[88:91]
	v_mfma_f32_16x16x32_bf16 v[76:79], v[154:157], v[220:223], v[76:79]
	v_mfma_f32_16x16x32_bf16 v[72:75], v[162:165], v[220:223], v[72:75]
	v_mfma_f32_16x16x32_bf16 v[116:119], v[166:169], v[182:185], v[116:119]
	v_mfma_f32_16x16x32_bf16 v[112:115], v[174:177], v[182:185], v[112:115]
	v_mfma_f32_16x16x32_bf16 v[100:103], v[166:169], v[200:203], v[100:103]
	v_mfma_f32_16x16x32_bf16 v[96:99], v[174:177], v[200:203], v[96:99]
	v_mfma_f32_16x16x32_bf16 v[84:87], v[166:169], v[208:211], v[84:87]
	v_mfma_f32_16x16x32_bf16 v[80:83], v[174:177], v[208:211], v[80:83]
	v_mfma_f32_16x16x32_bf16 v[68:71], v[166:169], v[216:219], v[68:71]
	v_mfma_f32_16x16x32_bf16 v[64:67], v[174:177], v[216:219], v[64:67]
	v_mfma_f32_16x16x32_bf16 v[116:119], v[170:173], v[196:199], v[116:119]
	v_mfma_f32_16x16x32_bf16 v[112:115], v[178:181], v[196:199], v[112:115]
	v_mfma_f32_16x16x32_bf16 v[100:103], v[170:173], v[204:207], v[100:103]
	v_mfma_f32_16x16x32_bf16 v[96:99], v[178:181], v[204:207], v[96:99]
	v_mfma_f32_16x16x32_bf16 v[84:87], v[170:173], v[212:215], v[84:87]
	v_mfma_f32_16x16x32_bf16 v[80:83], v[178:181], v[212:215], v[80:83]
	v_mfma_f32_16x16x32_bf16 v[68:71], v[170:173], v[220:223], v[68:71]
	v_mfma_f32_16x16x32_bf16 v[64:67], v[178:181], v[220:223], v[64:67]
	s_setprio 0
	s_barrier
	s_add_i32 s33, s78, s49
	v_lshl_add_u64 v[186:187], s[64:65], 0, v[132:133]
	s_mov_b32 m0, s33
	ds_read_b128 v[182:185], v193 offset:16384
	ds_read_b128 v[196:199], v193 offset:17408
	ds_read_b128 v[200:203], v193 offset:18432
	ds_read_b128 v[204:207], v193 offset:19456
	ds_read_b128 v[208:211], v193 offset:20480
	ds_read_b128 v[212:215], v193 offset:21504
	ds_read_b128 v[216:219], v193 offset:22528
	ds_read_b128 v[220:223], v193 offset:23552
	global_load_lds_dwordx4 v[186:187], off
	s_add_i32 m0, s33, 0x2000
	v_lshl_add_u64 v[224:225], s[64:65], 0, v[136:137]
	s_add_u32 s64, s64, s18
	s_addc_u32 s65, s65, s19
	s_add_i32 s33, s79, s49
	global_load_lds_dwordx4 v[224:225], off
	v_lshl_add_u64 v[226:227], s[64:65], 0, v[132:133]
	s_mov_b32 m0, s33
	v_lshl_add_u64 v[228:229], s[64:65], 0, v[136:137]
	global_load_lds_dwordx4 v[226:227], off
	s_add_i32 m0, s33, 0x2000
	v_lshl_add_u64 v[230:231], s[12:13], 0, v[130:131]
	global_load_lds_dwordx4 v[228:229], off
	s_mov_b32 m0, s66
	v_lshl_add_u64 v[232:233], s[12:13], 0, v[134:135]
	global_load_lds_dwordx4 v[230:231], off
	s_mov_b32 m0, s67
	s_nop 0
	global_load_lds_dwordx4 v[232:233], off
	s_waitcnt vmcnt(8)
	s_waitcnt lgkmcnt(0)
	s_barrier
; #define PG8_STAGE(bufoff, gbase, voff) do { _Pragma("unroll") for (int _i = 0; _i < 2; ++_i) \
;         __builtin_amdgcn_global_load_lds((const unsigned*)((const char*)(gbase) + (voff)[_i]), (PG8_LAS unsigned*)(lds + (bufoff) + ldsw + _i * 8192), 16, 0, 0); } while (0)
; #define PG8_LDA(dst, b, h) do { _Pragma("unroll") for (int m = 0; m < 4; ++m) _Pragma("unroll") for (int k = 0; k < 2; ++k) dst[m][k] = *(const PG8_LAS bf16x8*)(lds + PG8_SA(b, h) + aoff + m * 2048 + k * 1024); } while (0)
; #define PG8_LDB(dst, b, h) do { _Pragma("unroll") for (int n = 0; n < 2; ++n) _Pragma("unroll") for (int k = 0; k < 2; ++k) dst[n][k] = *(const PG8_LAS bf16x8*)(lds + PG8_SB(b, h) + boff + n * 2048 + k * 1024); } while (0)
; #define PG8_MMA(ai, bj, At, Bt) do { __builtin_amdgcn_s_setprio(1); _Pragma("unroll") for (int m = 0; m < 4; ++m) _Pragma("unroll") for (int n = 0; n < 2; ++n) _Pragma("unroll") for (int k = 0; k < 2; ++k) \
;         acc[ai][bj][m][n] = __builtin_amdgcn_mfma_f32_16x16x32_bf16(Bt[n][k], At[m][k], acc[ai][bj][m][n], 0, 0, 0); __builtin_amdgcn_s_setprio(0); } while (0)
; #define PG8_WAIT_V(n) asm volatile("s_waitcnt vmcnt(" #n ")" ::: "memory")
; #define PG8_WAIT_L(n) asm volatile("s_waitcnt lgkmcnt(" #n ")" ::: "memory")
; #define PG8_BAR __builtin_amdgcn_s_barrier()
; #define PG8_SCHED __builtin_amdgcn_sched_barrier(0)
; template <class Epi, class Sched, bool ALIGN_EPI = false, bool SP2 = false>
; __device__ __forceinline__ void gemm_phase(PG8_LAS unsigned char* lds, const Gemm g, const Sched& S, const Epi& E) {
;     ...
;             PG8_WAIT_V(8); PG8_WAIT_L(0); PG8_BAR; PG8_MMA(1, 0, At, B0); PG8_MMA(1, 1, At, B1); PG8_BAR; PG8_SCHED;
;             PG8_LDB(B0, 1, 0); PG8_LDB(B1, 1, 1); PG8_SCHED; PG8_LDA(At, 1, 0); PG8_STAGE(PG8_SA(0, 1), a2 + hstep, voffA);
;             PG8_WAIT_V(8); PG8_WAIT_L(0); PG8_BAR; PG8_MMA(0, 0, At, B0); PG8_MMA(0, 1, At, B1); PG8_BAR; PG8_SCHED;
	s_setprio 1
	v_mfma_f32_16x16x32_bf16 v[60:63], v[150:153], v[182:185], v[60:63]
	v_mfma_f32_16x16x32_bf16 v[56:59], v[158:161], v[182:185], v[56:59]
	v_mfma_f32_16x16x32_bf16 v[44:47], v[150:153], v[200:203], v[44:47]
	v_mfma_f32_16x16x32_bf16 v[40:43], v[158:161], v[200:203], v[40:43]
	v_mfma_f32_16x16x32_bf16 v[28:31], v[150:153], v[208:211], v[28:31]
	v_mfma_f32_16x16x32_bf16 v[24:27], v[158:161], v[208:211], v[24:27]
	v_mfma_f32_16x16x32_bf16 v[12:15], v[150:153], v[216:219], v[12:15]
	v_mfma_f32_16x16x32_bf16 v[8:11], v[158:161], v[216:219], v[8:11]
	v_mfma_f32_16x16x32_bf16 v[60:63], v[154:157], v[196:199], v[60:63]
	v_mfma_f32_16x16x32_bf16 v[56:59], v[162:165], v[196:199], v[56:59]
	v_mfma_f32_16x16x32_bf16 v[44:47], v[154:157], v[204:207], v[44:47]
	v_mfma_f32_16x16x32_bf16 v[40:43], v[162:165], v[204:207], v[40:43]
	v_mfma_f32_16x16x32_bf16 v[28:31], v[154:157], v[212:215], v[28:31]
	v_mfma_f32_16x16x32_bf16 v[24:27], v[162:165], v[212:215], v[24:27]
	v_mfma_f32_16x16x32_bf16 v[12:15], v[154:157], v[220:223], v[12:15]
	v_mfma_f32_16x16x32_bf16 v[8:11], v[162:165], v[220:223], v[8:11]
	v_mfma_f32_16x16x32_bf16 v[52:55], v[166:169], v[182:185], v[52:55]
	v_mfma_f32_16x16x32_bf16 v[48:51], v[174:177], v[182:185], v[48:51]
	v_mfma_f32_16x16x32_bf16 v[36:39], v[166:169], v[200:203], v[36:39]
	v_mfma_f32_16x16x32_bf16 v[32:35], v[174:177], v[200:203], v[32:35]
	v_mfma_f32_16x16x32_bf16 v[20:23], v[166:169], v[208:211], v[20:23]
	v_mfma_f32_16x16x32_bf16 v[16:19], v[174:177], v[208:211], v[16:19]
	v_mfma_f32_16x16x32_bf16 v[4:7], v[166:169], v[216:219], v[4:7]
	v_mfma_f32_16x16x32_bf16 v[0:3], v[174:177], v[216:219], v[0:3]
	v_mfma_f32_16x16x32_bf16 v[52:55], v[170:173], v[196:199], v[52:55]
	v_mfma_f32_16x16x32_bf16 v[48:51], v[178:181], v[196:199], v[48:51]
	v_mfma_f32_16x16x32_bf16 v[36:39], v[170:173], v[204:207], v[36:39]
	v_mfma_f32_16x16x32_bf16 v[32:35], v[178:181], v[204:207], v[32:35]
	v_mfma_f32_16x16x32_bf16 v[20:23], v[170:173], v[212:215], v[20:23]
	v_mfma_f32_16x16x32_bf16 v[16:19], v[178:181], v[212:215], v[16:19]
	v_mfma_f32_16x16x32_bf16 v[4:7], v[170:173], v[220:223], v[4:7]
	v_mfma_f32_16x16x32_bf16 v[0:3], v[178:181], v[220:223], v[0:3]
	s_setprio 0
	s_barrier
	s_add_i32 s33, 0, 0x18000
	v_add_u32_e32 v128, s33, v188
	s_add_i32 s38, 0, 0x1c000
	ds_read_b128 v[150:153], v128
	ds_read_b128 v[154:157], v128 offset:1024
	ds_read_b128 v[158:161], v128 offset:2048
	ds_read_b128 v[162:165], v128 offset:3072
	v_add_u32_e32 v128, s38, v188
	ds_read_b128 v[166:169], v128
	ds_read_b128 v[170:173], v128 offset:1024
	ds_read_b128 v[174:177], v128 offset:2048
	ds_read_b128 v[178:181], v128 offset:3072
	s_add_u32 s12, s12, s18
	s_addc_u32 s13, s13, s19
	s_mov_b32 m0, s68
	v_lshl_add_u64 v[234:235], s[12:13], 0, v[130:131]
	ds_read_b128 v[182:185], v193 offset:32768
	ds_read_b128 v[196:199], v193 offset:33792
	ds_read_b128 v[200:203], v193 offset:34816
	ds_read_b128 v[204:207], v193 offset:35840
	ds_read_b128 v[208:211], v193 offset:36864
	ds_read_b128 v[212:215], v193 offset:37888
	ds_read_b128 v[216:219], v193 offset:38912
	ds_read_b128 v[220:223], v193 offset:39936
	global_load_lds_dwordx4 v[234:235], off
	v_lshl_add_u64 v[234:235], s[12:13], 0, v[134:135]
	s_mov_b32 m0, s69
	s_nop 0
	global_load_lds_dwordx4 v[234:235], off
	s_waitcnt vmcnt(8)
	s_waitcnt lgkmcnt(0)
	s_barrier
	s_setprio 1
	v_mfma_f32_16x16x32_bf16 v[124:127], v[150:153], v[182:185], v[124:127]
	v_mfma_f32_16x16x32_bf16 v[120:123], v[158:161], v[182:185], v[120:123]
	v_mfma_f32_16x16x32_bf16 v[108:111], v[150:153], v[200:203], v[108:111]
	v_mfma_f32_16x16x32_bf16 v[104:107], v[158:161], v[200:203], v[104:107]
	v_mfma_f32_16x16x32_bf16 v[92:95], v[150:153], v[208:211], v[92:95]
	v_mfma_f32_16x16x32_bf16 v[88:91], v[158:161], v[208:211], v[88:91]
	v_mfma_f32_16x16x32_bf16 v[76:79], v[150:153], v[216:219], v[76:79]
	v_mfma_f32_16x16x32_bf16 v[72:75], v[158:161], v[216:219], v[72:75]
	v_mfma_f32_16x16x32_bf16 v[124:127], v[154:157], v[196:199], v[124:127]
	v_mfma_f32_16x16x32_bf16 v[120:123], v[162:165], v[196:199], v[120:123]
	v_mfma_f32_16x16x32_bf16 v[108:111], v[154:157], v[204:207], v[108:111]
	v_mfma_f32_16x16x32_bf16 v[104:107], v[162:165], v[204:207], v[104:107]
	v_mfma_f32_16x16x32_bf16 v[92:95], v[154:157], v[212:215], v[92:95]
	v_mfma_f32_16x16x32_bf16 v[88:91], v[162:165], v[212:215], v[88:91]
	v_mfma_f32_16x16x32_bf16 v[76:79], v[154:157], v[220:223], v[76:79]
	v_mfma_f32_16x16x32_bf16 v[72:75], v[162:165], v[220:223], v[72:75]
	v_mfma_f32_16x16x32_bf16 v[116:119], v[166:169], v[182:185], v[116:119]
	v_mfma_f32_16x16x32_bf16 v[112:115], v[174:177], v[182:185], v[112:115]
	v_mfma_f32_16x16x32_bf16 v[100:103], v[166:169], v[200:203], v[100:103]
	v_mfma_f32_16x16x32_bf16 v[96:99], v[174:177], v[200:203], v[96:99]
	v_mfma_f32_16x16x32_bf16 v[84:87], v[166:169], v[208:211], v[84:87]
	v_mfma_f32_16x16x32_bf16 v[80:83], v[174:177], v[208:211], v[80:83]
	v_mfma_f32_16x16x32_bf16 v[68:71], v[166:169], v[216:219], v[68:71]
	v_mfma_f32_16x16x32_bf16 v[64:67], v[174:177], v[216:219], v[64:67]
	v_mfma_f32_16x16x32_bf16 v[116:119], v[170:173], v[196:199], v[116:119]
	v_mfma_f32_16x16x32_bf16 v[112:115], v[178:181], v[196:199], v[112:115]
	v_mfma_f32_16x16x32_bf16 v[100:103], v[170:173], v[204:207], v[100:103]
	v_mfma_f32_16x16x32_bf16 v[96:99], v[178:181], v[204:207], v[96:99]
	v_mfma_f32_16x16x32_bf16 v[84:87], v[170:173], v[212:215], v[84:87]
	v_mfma_f32_16x16x32_bf16 v[80:83], v[178:181], v[212:215], v[80:83]
	v_mfma_f32_16x16x32_bf16 v[68:71], v[170:173], v[220:223], v[68:71]
	v_mfma_f32_16x16x32_bf16 v[64:67], v[178:181], v[220:223], v[64:67]
	s_setprio 0
	s_barrier
; #define PG8_STAGE(bufoff, gbase, voff) do { _Pragma("unroll") for (int _i = 0; _i < 2; ++_i) \
;         __builtin_amdgcn_global_load_lds((const unsigned*)((const char*)(gbase) + (voff)[_i]), (PG8_LAS unsigned*)(lds + (bufoff) + ldsw + _i * 8192), 16, 0, 0); } while (0)
; #define PG8_LDA(dst, b, h) do { _Pragma("unroll") for (int m = 0; m < 4; ++m) _Pragma("unroll") for (int k = 0; k < 2; ++k) dst[m][k] = *(const PG8_LAS bf16x8*)(lds + PG8_SA(b, h) + aoff + m * 2048 + k * 1024); } while (0)
; #define PG8_MMA(ai, bj, At, Bt) do { __builtin_amdgcn_s_setprio(1); _Pragma("unroll") for (int m = 0; m < 4; ++m) _Pragma("unroll") for (int n = 0; n < 2; ++n) _Pragma("unroll") for (int k = 0; k < 2; ++k) \
;         acc[ai][bj][m][n] = __builtin_amdgcn_mfma_f32_16x16x32_bf16(Bt[n][k], At[m][k], acc[ai][bj][m][n], 0, 0, 0); __builtin_amdgcn_s_setprio(0); } while (0)
; #define PG8_WAIT_V(n) asm volatile("s_waitcnt vmcnt(" #n ")" ::: "memory")
; #define PG8_WAIT_L(n) asm volatile("s_waitcnt lgkmcnt(" #n ")" ::: "memory")
; #define PG8_BAR __builtin_amdgcn_s_barrier()
; #define PG8_SCHED __builtin_amdgcn_sched_barrier(0)
; template <class Epi, class Sched, bool ALIGN_EPI = false, bool SP2 = false>
; __device__ __forceinline__ void gemm_phase(PG8_LAS unsigned char* lds, const Gemm g, const Sched& S, const Epi& E) {
;     ...
;             PG8_LDA(At, 1, 1); PG8_STAGE(PG8_SB(1, 0), b3, voffB); PG8_STAGE(PG8_SB(1, 1), b3 + hstep, voffB); PG8_STAGE(PG8_SA(1, 0), a3, voffA);
;             PG8_WAIT_V(8); PG8_WAIT_L(0); PG8_BAR; PG8_MMA(1, 0, At, B0); PG8_MMA(1, 1, At, B1); PG8_BAR; PG8_SCHED;
	s_add_i32 s12, s33, s49
	v_lshl_add_u64 v[186:187], v[186:187], 0, s[42:43]
	s_mov_b32 m0, s12
	ds_read_b128 v[182:185], v193 offset:49152
	ds_read_b128 v[196:199], v193 offset:50176
	ds_read_b128 v[200:203], v193 offset:51200
	ds_read_b128 v[204:207], v193 offset:52224
	ds_read_b128 v[208:211], v193 offset:53248
	ds_read_b128 v[212:215], v193 offset:54272
	ds_read_b128 v[216:219], v193 offset:55296
	ds_read_b128 v[220:223], v193 offset:56320
	global_load_lds_dwordx4 v[186:187], off
	v_lshl_add_u64 v[186:187], v[224:225], 0, s[42:43]
	s_add_i32 m0, s12, 0x2000
	s_add_i32 s12, s38, s49
	global_load_lds_dwordx4 v[186:187], off
	v_lshl_add_u64 v[186:187], v[226:227], 0, s[42:43]
	s_mov_b32 m0, s12
	s_nop 0
	global_load_lds_dwordx4 v[186:187], off
	v_lshl_add_u64 v[186:187], v[228:229], 0, s[42:43]
	s_add_i32 m0, s12, 0x2000
	s_nop 0
	global_load_lds_dwordx4 v[186:187], off
	v_lshl_add_u64 v[186:187], v[230:231], 0, s[42:43]
	s_mov_b32 m0, s70
	s_nop 0
	global_load_lds_dwordx4 v[186:187], off
	v_lshl_add_u64 v[186:187], v[232:233], 0, s[42:43]
	s_mov_b32 m0, s71
	s_nop 0
	global_load_lds_dwordx4 v[186:187], off
	s_waitcnt vmcnt(8)
	s_waitcnt lgkmcnt(0)
	s_barrier
	s_setprio 1
	v_mfma_f32_16x16x32_bf16 v[60:63], v[150:153], v[182:185], v[60:63]
	v_mfma_f32_16x16x32_bf16 v[56:59], v[158:161], v[182:185], v[56:59]
	v_mfma_f32_16x16x32_bf16 v[44:47], v[150:153], v[200:203], v[44:47]
	v_mfma_f32_16x16x32_bf16 v[40:43], v[158:161], v[200:203], v[40:43]
	v_mfma_f32_16x16x32_bf16 v[28:31], v[150:153], v[208:211], v[28:31]
	v_mfma_f32_16x16x32_bf16 v[24:27], v[158:161], v[208:211], v[24:27]
	v_mfma_f32_16x16x32_bf16 v[12:15], v[150:153], v[216:219], v[12:15]
	v_mfma_f32_16x16x32_bf16 v[8:11], v[158:161], v[216:219], v[8:11]
	v_mfma_f32_16x16x32_bf16 v[60:63], v[154:157], v[196:199], v[60:63]
	v_mfma_f32_16x16x32_bf16 v[56:59], v[162:165], v[196:199], v[56:59]
	v_mfma_f32_16x16x32_bf16 v[44:47], v[154:157], v[204:207], v[44:47]
	v_mfma_f32_16x16x32_bf16 v[40:43], v[162:165], v[204:207], v[40:43]
	v_mfma_f32_16x16x32_bf16 v[28:31], v[154:157], v[212:215], v[28:31]
	v_mfma_f32_16x16x32_bf16 v[24:27], v[162:165], v[212:215], v[24:27]
	v_mfma_f32_16x16x32_bf16 v[12:15], v[154:157], v[220:223], v[12:15]
	v_mfma_f32_16x16x32_bf16 v[8:11], v[162:165], v[220:223], v[8:11]
	v_mfma_f32_16x16x32_bf16 v[52:55], v[166:169], v[182:185], v[52:55]
	v_mfma_f32_16x16x32_bf16 v[48:51], v[174:177], v[182:185], v[48:51]
	v_mfma_f32_16x16x32_bf16 v[36:39], v[166:169], v[200:203], v[36:39]
	v_mfma_f32_16x16x32_bf16 v[32:35], v[174:177], v[200:203], v[32:35]
	v_mfma_f32_16x16x32_bf16 v[20:23], v[166:169], v[208:211], v[20:23]
	v_mfma_f32_16x16x32_bf16 v[16:19], v[174:177], v[208:211], v[16:19]
	v_mfma_f32_16x16x32_bf16 v[4:7], v[166:169], v[216:219], v[4:7]
	v_mfma_f32_16x16x32_bf16 v[0:3], v[174:177], v[216:219], v[0:3]
	v_mfma_f32_16x16x32_bf16 v[52:55], v[170:173], v[196:199], v[52:55]
	v_mfma_f32_16x16x32_bf16 v[48:51], v[178:181], v[196:199], v[48:51]
	v_mfma_f32_16x16x32_bf16 v[36:39], v[170:173], v[204:207], v[36:39]
	v_mfma_f32_16x16x32_bf16 v[32:35], v[178:181], v[204:207], v[32:35]
	v_mfma_f32_16x16x32_bf16 v[20:23], v[170:173], v[212:215], v[20:23]
	v_mfma_f32_16x16x32_bf16 v[16:19], v[178:181], v[212:215], v[16:19]
	v_mfma_f32_16x16x32_bf16 v[4:7], v[170:173], v[220:223], v[4:7]
	v_mfma_f32_16x16x32_bf16 v[0:3], v[178:181], v[220:223], v[0:3]
	s_setprio 0
	s_barrier
	s_add_u32 s10, s10, 0x100
	s_addc_u32 s11, s11, 0
	s_add_u32 s5, s5, 0x100
	s_addc_u32 s14, s14, 0
	s_cmp_ge_i32 s15, s72
	s_mov_b32 s12, s15
	s_cbranch_scc0 .LBB0_473

; #define PG8_STAGE(bufoff, gbase, voff) do { _Pragma("unroll") for (int _i = 0; _i < 2; ++_i) \
;         __builtin_amdgcn_global_load_lds((const unsigned*)((const char*)(gbase) + (voff)[_i]), (PG8_LAS unsigned*)(lds + (bufoff) + ldsw + _i * 8192), 16, 0, 0); } while (0)
; #define PG8_LDA(dst, b, h) do { _Pragma("unroll") for (int m = 0; m < 4; ++m) _Pragma("unroll") for (int k = 0; k < 2; ++k) dst[m][k] = *(const PG8_LAS bf16x8*)(lds + PG8_SA(b, h) + aoff + m * 2048 + k * 1024); } while (0)
; #define PG8_LDB(dst, b, h) do { _Pragma("unroll") for (int n = 0; n < 2; ++n) _Pragma("unroll") for (int k = 0; k < 2; ++k) dst[n][k] = *(const PG8_LAS bf16x8*)(lds + PG8_SB(b, h) + boff + n * 2048 + k * 1024); } while (0)
; #define PG8_MMA(ai, bj, At, Bt) do { __builtin_amdgcn_s_setprio(1); _Pragma("unroll") for (int m = 0; m < 4; ++m) _Pragma("unroll") for (int n = 0; n < 2; ++n) _Pragma("unroll") for (int k = 0; k < 2; ++k) \
;         acc[ai][bj][m][n] = __builtin_amdgcn_mfma_f32_16x16x32_bf16(Bt[n][k], At[m][k], acc[ai][bj][m][n], 0, 0, 0); __builtin_amdgcn_s_setprio(0); } while (0)
; #define PG8_WAIT_V(n) asm volatile("s_waitcnt vmcnt(" #n ")" ::: "memory")
; #define PG8_BAR __builtin_amdgcn_s_barrier()
; template <class Epi, class Sched, bool ALIGN_EPI = false, bool SP2 = false>
; __device__ __forceinline__ void gemm_phase(PG8_LAS unsigned char* lds, const Gemm g, const Sched& S, const Epi& E) {
;     ...
;         for (int t = 0; t < nt; t += 2) {
;             const bool last = (t == nt - 2);
;             const char* a1 = cA + (size_t)(t + 1) * kstep;
;             const char* a2 = last ? nA : cA + (size_t)(t + 2) * kstep; const char* b2 = last ? nB : cB + (size_t)(t + 2) * kstep;
;             const char* a3 = a2 + kstep; const char* b3 = b2 + kstep;
;             if (last && has_next) S.a_ready(nxt);
;             if constexpr (SP2) {
;             PG8_LDB(B0, 0, 0); PG8_LDB(B1, 0, 1); PG8_SCHED; PG8_LDA(At, 0, 0); PG8_STAGE(PG8_SA(1, 1), a1 + hstep, voffA);
;             PG8_WAIT_V(8); PG8_WAIT_L(0); PG8_BAR; PG8_MMA(0, 0, At, B0); PG8_MMA(0, 1, At, B1); PG8_BAR; PG8_SCHED;
;             PG8_LDA(At, 0, 1); PG8_STAGE(PG8_SB(0, 0), b2, voffB); PG8_STAGE(PG8_SB(0, 1), b2 + hstep, voffB); PG8_STAGE(PG8_SA(0, 0), a2, voffA);
;             PG8_WAIT_V(8); PG8_WAIT_L(0); PG8_BAR; PG8_MMA(1, 0, At, B0); PG8_MMA(1, 1, At, B1); PG8_BAR; PG8_SCHED;
.LBB0_633:
	ds_read_b128 v[150:153], v144
	ds_read_b128 v[154:157], v144 offset:1024
	ds_read_b128 v[158:161], v144 offset:2048
	ds_read_b128 v[162:165], v144 offset:3072
	ds_read_b128 v[166:169], v145
	ds_read_b128 v[170:173], v145 offset:1024
	ds_read_b128 v[174:177], v145 offset:2048
	ds_read_b128 v[178:181], v145 offset:3072
	s_add_i32 s90, s60, 2
	s_add_u32 s91, s58, 0x80
	s_addc_u32 s61, s59, 0
	s_cmp_eq_u32 s72, s60
	s_cselect_b32 s60, s42, s91
	s_cselect_b32 s61, s43, s61
	s_cselect_b32 s93, s57, s89
	s_cselect_b32 s92, s56, s33
	s_mov_b32 m0, s74
	v_lshl_add_u64 v[190:191], s[58:59], 0, v[140:141]
	ds_read_b128 v[182:185], v146
	ds_read_b128 v[186:189], v146 offset:1024
	ds_read_b128 v[194:197], v146 offset:2048
	ds_read_b128 v[198:201], v146 offset:3072
	ds_read_b128 v[202:205], v146 offset:4096
	ds_read_b128 v[206:209], v146 offset:5120
	ds_read_b128 v[210:213], v146 offset:6144
	ds_read_b128 v[214:217], v146 offset:7168
	global_load_lds_dwordx4 v[190:191], off
	v_lshl_add_u64 v[190:191], s[58:59], 0, v[142:143]
	s_mov_b32 m0, s75
	s_nop 0
	global_load_lds_dwordx4 v[190:191], off
	s_waitcnt vmcnt(8)
	s_waitcnt lgkmcnt(0)
	s_barrier
	s_setprio 1
	v_mfma_f32_16x16x32_bf16 v[124:127], v[150:153], v[182:185], v[124:127]
	v_mfma_f32_16x16x32_bf16 v[120:123], v[158:161], v[182:185], v[120:123]
	v_mfma_f32_16x16x32_bf16 v[108:111], v[150:153], v[194:197], v[108:111]
	v_mfma_f32_16x16x32_bf16 v[104:107], v[158:161], v[194:197], v[104:107]
	v_mfma_f32_16x16x32_bf16 v[92:95], v[150:153], v[202:205], v[92:95]
	v_mfma_f32_16x16x32_bf16 v[88:91], v[158:161], v[202:205], v[88:91]
	v_mfma_f32_16x16x32_bf16 v[76:79], v[150:153], v[210:213], v[76:79]
	v_mfma_f32_16x16x32_bf16 v[72:75], v[158:161], v[210:213], v[72:75]
	v_mfma_f32_16x16x32_bf16 v[124:127], v[154:157], v[186:189], v[124:127]
	v_mfma_f32_16x16x32_bf16 v[120:123], v[162:165], v[186:189], v[120:123]
	v_mfma_f32_16x16x32_bf16 v[108:111], v[154:157], v[198:201], v[108:111]
	v_mfma_f32_16x16x32_bf16 v[104:107], v[162:165], v[198:201], v[104:107]
	v_mfma_f32_16x16x32_bf16 v[92:95], v[154:157], v[206:209], v[92:95]
	v_mfma_f32_16x16x32_bf16 v[88:91], v[162:165], v[206:209], v[88:91]
	v_mfma_f32_16x16x32_bf16 v[76:79], v[154:157], v[214:217], v[76:79]
	v_mfma_f32_16x16x32_bf16 v[72:75], v[162:165], v[214:217], v[72:75]
	v_mfma_f32_16x16x32_bf16 v[116:119], v[166:169], v[182:185], v[116:119]
	v_mfma_f32_16x16x32_bf16 v[112:115], v[174:177], v[182:185], v[112:115]
	v_mfma_f32_16x16x32_bf16 v[100:103], v[166:169], v[194:197], v[100:103]
	v_mfma_f32_16x16x32_bf16 v[96:99], v[174:177], v[194:197], v[96:99]
	v_mfma_f32_16x16x32_bf16 v[84:87], v[166:169], v[202:205], v[84:87]
	v_mfma_f32_16x16x32_bf16 v[80:83], v[174:177], v[202:205], v[80:83]
	v_mfma_f32_16x16x32_bf16 v[68:71], v[166:169], v[210:213], v[68:71]
	v_mfma_f32_16x16x32_bf16 v[64:67], v[174:177], v[210:213], v[64:67]
	v_mfma_f32_16x16x32_bf16 v[116:119], v[170:173], v[186:189], v[116:119]
	v_mfma_f32_16x16x32_bf16 v[112:115], v[178:181], v[186:189], v[112:115]
	v_mfma_f32_16x16x32_bf16 v[100:103], v[170:173], v[198:201], v[100:103]
	v_mfma_f32_16x16x32_bf16 v[96:99], v[178:181], v[198:201], v[96:99]
	v_mfma_f32_16x16x32_bf16 v[84:87], v[170:173], v[206:209], v[84:87]
	v_mfma_f32_16x16x32_bf16 v[80:83], v[178:181], v[206:209], v[80:83]
	v_mfma_f32_16x16x32_bf16 v[68:71], v[170:173], v[214:217], v[68:71]
	v_mfma_f32_16x16x32_bf16 v[64:67], v[178:181], v[214:217], v[64:67]
	s_setprio 0
	s_barrier
	s_mov_b32 m0, s76
	v_lshl_add_u64 v[190:191], s[92:93], 0, v[134:135]
	v_lshl_add_u64 v[218:219], s[92:93], 0, v[130:131]
	s_add_u32 s92, s92, s8
	ds_read_b128 v[182:185], v146 offset:16384
	ds_read_b128 v[186:189], v146 offset:17408
	ds_read_b128 v[194:197], v146 offset:18432
	ds_read_b128 v[198:201], v146 offset:19456
	ds_read_b128 v[202:205], v146 offset:20480
	ds_read_b128 v[206:209], v146 offset:21504
	ds_read_b128 v[210:213], v146 offset:22528
	ds_read_b128 v[214:217], v146 offset:23552
	global_load_lds_dwordx4 v[190:191], off
	s_mov_b32 m0, s77
	s_addc_u32 s93, s93, s9
	global_load_lds_dwordx4 v[218:219], off
	v_lshl_add_u64 v[220:221], s[92:93], 0, v[134:135]
	s_mov_b32 m0, s78
	v_lshl_add_u64 v[222:223], s[92:93], 0, v[130:131]
	global_load_lds_dwordx4 v[220:221], off
	s_mov_b32 m0, s79
	v_lshl_add_u64 v[224:225], s[60:61], 0, v[136:137]
	global_load_lds_dwordx4 v[222:223], off
	s_mov_b32 m0, s4
	v_lshl_add_u64 v[226:227], s[60:61], 0, v[132:133]
	global_load_lds_dwordx4 v[224:225], off
	s_mov_b32 m0, s5
	s_nop 0
	global_load_lds_dwordx4 v[226:227], off
	s_waitcnt vmcnt(8)
	s_waitcnt lgkmcnt(0)
	s_barrier
; #define PG8_STAGE(bufoff, gbase, voff) do { _Pragma("unroll") for (int _i = 0; _i < 2; ++_i) \
;         __builtin_amdgcn_global_load_lds((const unsigned*)((const char*)(gbase) + (voff)[_i]), (PG8_LAS unsigned*)(lds + (bufoff) + ldsw + _i * 8192), 16, 0, 0); } while (0)
; #define PG8_LDA(dst, b, h) do { _Pragma("unroll") for (int m = 0; m < 4; ++m) _Pragma("unroll") for (int k = 0; k < 2; ++k) dst[m][k] = *(const PG8_LAS bf16x8*)(lds + PG8_SA(b, h) + aoff + m * 2048 + k * 1024); } while (0)
; #define PG8_LDB(dst, b, h) do { _Pragma("unroll") for (int n = 0; n < 2; ++n) _Pragma("unroll") for (int k = 0; k < 2; ++k) dst[n][k] = *(const PG8_LAS bf16x8*)(lds + PG8_SB(b, h) + boff + n * 2048 + k * 1024); } while (0)
; #define PG8_MMA(ai, bj, At, Bt) do { __builtin_amdgcn_s_setprio(1); _Pragma("unroll") for (int m = 0; m < 4; ++m) _Pragma("unroll") for (int n = 0; n < 2; ++n) _Pragma("unroll") for (int k = 0; k < 2; ++k) \
;         acc[ai][bj][m][n] = __builtin_amdgcn_mfma_f32_16x16x32_bf16(Bt[n][k], At[m][k], acc[ai][bj][m][n], 0, 0, 0); __builtin_amdgcn_s_setprio(0); } while (0)
; #define PG8_WAIT_V(n) asm volatile("s_waitcnt vmcnt(" #n ")" ::: "memory")
; #define PG8_WAIT_L(n) asm volatile("s_waitcnt lgkmcnt(" #n ")" ::: "memory")
; #define PG8_BAR __builtin_amdgcn_s_barrier()
; #define PG8_SCHED __builtin_amdgcn_sched_barrier(0)
; template <class Epi, class Sched, bool ALIGN_EPI = false, bool SP2 = false>
; __device__ __forceinline__ void gemm_phase(PG8_LAS unsigned char* lds, const Gemm g, const Sched& S, const Epi& E) {
;     ...
;             PG8_WAIT_V(8); PG8_WAIT_L(0); PG8_BAR; PG8_MMA(1, 0, At, B0); PG8_MMA(1, 1, At, B1); PG8_BAR; PG8_SCHED;
;             PG8_LDB(B0, 1, 0); PG8_LDB(B1, 1, 1); PG8_SCHED; PG8_LDA(At, 1, 0); PG8_STAGE(PG8_SA(0, 1), a2 + hstep, voffA);
;             PG8_WAIT_V(8); PG8_WAIT_L(0); PG8_BAR; PG8_MMA(0, 0, At, B0); PG8_MMA(0, 1, At, B1); PG8_BAR; PG8_SCHED;
	s_setprio 1
	v_mfma_f32_16x16x32_bf16 v[60:63], v[150:153], v[182:185], v[60:63]
	v_mfma_f32_16x16x32_bf16 v[56:59], v[158:161], v[182:185], v[56:59]
	v_mfma_f32_16x16x32_bf16 v[44:47], v[150:153], v[194:197], v[44:47]
	v_mfma_f32_16x16x32_bf16 v[40:43], v[158:161], v[194:197], v[40:43]
	v_mfma_f32_16x16x32_bf16 v[28:31], v[150:153], v[202:205], v[28:31]
	v_mfma_f32_16x16x32_bf16 v[24:27], v[158:161], v[202:205], v[24:27]
	v_mfma_f32_16x16x32_bf16 v[12:15], v[150:153], v[210:213], v[12:15]
	v_mfma_f32_16x16x32_bf16 v[8:11], v[158:161], v[210:213], v[8:11]
	v_mfma_f32_16x16x32_bf16 v[60:63], v[154:157], v[186:189], v[60:63]
	v_mfma_f32_16x16x32_bf16 v[56:59], v[162:165], v[186:189], v[56:59]
	v_mfma_f32_16x16x32_bf16 v[44:47], v[154:157], v[198:201], v[44:47]
	v_mfma_f32_16x16x32_bf16 v[40:43], v[162:165], v[198:201], v[40:43]
	v_mfma_f32_16x16x32_bf16 v[28:31], v[154:157], v[206:209], v[28:31]
	v_mfma_f32_16x16x32_bf16 v[24:27], v[162:165], v[206:209], v[24:27]
	v_mfma_f32_16x16x32_bf16 v[12:15], v[154:157], v[214:217], v[12:15]
	v_mfma_f32_16x16x32_bf16 v[8:11], v[162:165], v[214:217], v[8:11]
	v_mfma_f32_16x16x32_bf16 v[52:55], v[166:169], v[182:185], v[52:55]
	v_mfma_f32_16x16x32_bf16 v[48:51], v[174:177], v[182:185], v[48:51]
	v_mfma_f32_16x16x32_bf16 v[36:39], v[166:169], v[194:197], v[36:39]
	v_mfma_f32_16x16x32_bf16 v[32:35], v[174:177], v[194:197], v[32:35]
	v_mfma_f32_16x16x32_bf16 v[20:23], v[166:169], v[202:205], v[20:23]
	v_mfma_f32_16x16x32_bf16 v[16:19], v[174:177], v[202:205], v[16:19]
	v_mfma_f32_16x16x32_bf16 v[4:7], v[166:169], v[210:213], v[4:7]
	v_mfma_f32_16x16x32_bf16 v[0:3], v[174:177], v[210:213], v[0:3]
	v_mfma_f32_16x16x32_bf16 v[52:55], v[170:173], v[186:189], v[52:55]
	v_mfma_f32_16x16x32_bf16 v[48:51], v[178:181], v[186:189], v[48:51]
	v_mfma_f32_16x16x32_bf16 v[36:39], v[170:173], v[198:201], v[36:39]
	v_mfma_f32_16x16x32_bf16 v[32:35], v[178:181], v[198:201], v[32:35]
	v_mfma_f32_16x16x32_bf16 v[20:23], v[170:173], v[206:209], v[20:23]
	v_mfma_f32_16x16x32_bf16 v[16:19], v[178:181], v[206:209], v[16:19]
	v_mfma_f32_16x16x32_bf16 v[4:7], v[170:173], v[214:217], v[4:7]
	v_mfma_f32_16x16x32_bf16 v[0:3], v[178:181], v[214:217], v[0:3]
	s_setprio 0
	s_barrier
	ds_read_b128 v[150:153], v147
	ds_read_b128 v[154:157], v147 offset:1024
	ds_read_b128 v[158:161], v147 offset:2048
	ds_read_b128 v[162:165], v147 offset:3072
	ds_read_b128 v[166:169], v148
	ds_read_b128 v[170:173], v148 offset:1024
	ds_read_b128 v[174:177], v148 offset:2048
	ds_read_b128 v[178:181], v148 offset:3072
	s_add_u32 s60, s60, s8
	s_addc_u32 s61, s61, s9
	s_mov_b32 m0, s63
	v_lshl_add_u64 v[228:229], s[60:61], 0, v[136:137]
	ds_read_b128 v[182:185], v146 offset:32768
	ds_read_b128 v[186:189], v146 offset:33792
	ds_read_b128 v[194:197], v146 offset:34816
	ds_read_b128 v[198:201], v146 offset:35840
	ds_read_b128 v[202:205], v146 offset:36864
	ds_read_b128 v[206:209], v146 offset:37888
	ds_read_b128 v[210:213], v146 offset:38912
	ds_read_b128 v[214:217], v146 offset:39936
	global_load_lds_dwordx4 v[228:229], off
	v_lshl_add_u64 v[228:229], s[60:61], 0, v[132:133]
	s_mov_b32 m0, s64
	s_nop 0
	global_load_lds_dwordx4 v[228:229], off
	s_waitcnt vmcnt(8)
	s_waitcnt lgkmcnt(0)
	s_barrier
	s_setprio 1
	v_mfma_f32_16x16x32_bf16 v[124:127], v[150:153], v[182:185], v[124:127]
	v_mfma_f32_16x16x32_bf16 v[120:123], v[158:161], v[182:185], v[120:123]
	v_mfma_f32_16x16x32_bf16 v[108:111], v[150:153], v[194:197], v[108:111]
	v_mfma_f32_16x16x32_bf16 v[104:107], v[158:161], v[194:197], v[104:107]
	v_mfma_f32_16x16x32_bf16 v[92:95], v[150:153], v[202:205], v[92:95]
	v_mfma_f32_16x16x32_bf16 v[88:91], v[158:161], v[202:205], v[88:91]
	v_mfma_f32_16x16x32_bf16 v[76:79], v[150:153], v[210:213], v[76:79]
	v_mfma_f32_16x16x32_bf16 v[72:75], v[158:161], v[210:213], v[72:75]
	v_mfma_f32_16x16x32_bf16 v[124:127], v[154:157], v[186:189], v[124:127]
	v_mfma_f32_16x16x32_bf16 v[120:123], v[162:165], v[186:189], v[120:123]
	v_mfma_f32_16x16x32_bf16 v[108:111], v[154:157], v[198:201], v[108:111]
	v_mfma_f32_16x16x32_bf16 v[104:107], v[162:165], v[198:201], v[104:107]
	v_mfma_f32_16x16x32_bf16 v[92:95], v[154:157], v[206:209], v[92:95]
	v_mfma_f32_16x16x32_bf16 v[88:91], v[162:165], v[206:209], v[88:91]
	v_mfma_f32_16x16x32_bf16 v[76:79], v[154:157], v[214:217], v[76:79]
	v_mfma_f32_16x16x32_bf16 v[72:75], v[162:165], v[214:217], v[72:75]
	v_mfma_f32_16x16x32_bf16 v[116:119], v[166:169], v[182:185], v[116:119]
	v_mfma_f32_16x16x32_bf16 v[112:115], v[174:177], v[182:185], v[112:115]
	v_mfma_f32_16x16x32_bf16 v[100:103], v[166:169], v[194:197], v[100:103]
	v_mfma_f32_16x16x32_bf16 v[96:99], v[174:177], v[194:197], v[96:99]
	v_mfma_f32_16x16x32_bf16 v[84:87], v[166:169], v[202:205], v[84:87]
	v_mfma_f32_16x16x32_bf16 v[80:83], v[174:177], v[202:205], v[80:83]
	v_mfma_f32_16x16x32_bf16 v[68:71], v[166:169], v[210:213], v[68:71]
	v_mfma_f32_16x16x32_bf16 v[64:67], v[174:177], v[210:213], v[64:67]
	v_mfma_f32_16x16x32_bf16 v[116:119], v[170:173], v[186:189], v[116:119]
	v_mfma_f32_16x16x32_bf16 v[112:115], v[178:181], v[186:189], v[112:115]
	v_mfma_f32_16x16x32_bf16 v[100:103], v[170:173], v[198:201], v[100:103]
	v_mfma_f32_16x16x32_bf16 v[96:99], v[178:181], v[198:201], v[96:99]
	v_mfma_f32_16x16x32_bf16 v[84:87], v[170:173], v[206:209], v[84:87]
	v_mfma_f32_16x16x32_bf16 v[80:83], v[178:181], v[206:209], v[80:83]
	v_mfma_f32_16x16x32_bf16 v[68:71], v[170:173], v[214:217], v[68:71]
	v_mfma_f32_16x16x32_bf16 v[64:67], v[178:181], v[214:217], v[64:67]
	s_setprio 0
	s_barrier
; #define PG8_STAGE(bufoff, gbase, voff) do { _Pragma("unroll") for (int _i = 0; _i < 2; ++_i) \
;         __builtin_amdgcn_global_load_lds((const unsigned*)((const char*)(gbase) + (voff)[_i]), (PG8_LAS unsigned*)(lds + (bufoff) + ldsw + _i * 8192), 16, 0, 0); } while (0)
; #define PG8_LDA(dst, b, h) do { _Pragma("unroll") for (int m = 0; m < 4; ++m) _Pragma("unroll") for (int k = 0; k < 2; ++k) dst[m][k] = *(const PG8_LAS bf16x8*)(lds + PG8_SA(b, h) + aoff + m * 2048 + k * 1024); } while (0)
; #define PG8_MMA(ai, bj, At, Bt) do { __builtin_amdgcn_s_setprio(1); _Pragma("unroll") for (int m = 0; m < 4; ++m) _Pragma("unroll") for (int n = 0; n < 2; ++n) _Pragma("unroll") for (int k = 0; k < 2; ++k) \
;         acc[ai][bj][m][n] = __builtin_amdgcn_mfma_f32_16x16x32_bf16(Bt[n][k], At[m][k], acc[ai][bj][m][n], 0, 0, 0); __builtin_amdgcn_s_setprio(0); } while (0)
; #define PG8_WAIT_V(n) asm volatile("s_waitcnt vmcnt(" #n ")" ::: "memory")
; #define PG8_WAIT_L(n) asm volatile("s_waitcnt lgkmcnt(" #n ")" ::: "memory")
; #define PG8_BAR __builtin_amdgcn_s_barrier()
; #define PG8_SCHED __builtin_amdgcn_sched_barrier(0)
; template <class Epi, class Sched, bool ALIGN_EPI = false, bool SP2 = false>
; __device__ __forceinline__ void gemm_phase(PG8_LAS unsigned char* lds, const Gemm g, const Sched& S, const Epi& E) {
;     ...
;             PG8_LDA(At, 1, 1); PG8_STAGE(PG8_SB(1, 0), b3, voffB); PG8_STAGE(PG8_SB(1, 1), b3 + hstep, voffB); PG8_STAGE(PG8_SA(1, 0), a3, voffA);
;             PG8_WAIT_V(8); PG8_WAIT_L(0); PG8_BAR; PG8_MMA(1, 0, At, B0); PG8_MMA(1, 1, At, B1); PG8_BAR; PG8_SCHED;
	s_mov_b32 m0, s80
	v_lshl_add_u64 v[190:191], v[190:191], 0, s[14:15]
	ds_read_b128 v[182:185], v146 offset:49152
	ds_read_b128 v[186:189], v146 offset:50176
	ds_read_b128 v[194:197], v146 offset:51200
	ds_read_b128 v[198:201], v146 offset:52224
	ds_read_b128 v[202:205], v146 offset:53248
	ds_read_b128 v[206:209], v146 offset:54272
	ds_read_b128 v[210:213], v146 offset:55296
	ds_read_b128 v[214:217], v146 offset:56320
	global_load_lds_dwordx4 v[190:191], off
	v_lshl_add_u64 v[190:191], v[218:219], 0, s[14:15]
	s_mov_b32 m0, s81
	s_nop 0
	global_load_lds_dwordx4 v[190:191], off
	v_lshl_add_u64 v[190:191], v[220:221], 0, s[14:15]
	s_mov_b32 m0, s82
	s_nop 0
	global_load_lds_dwordx4 v[190:191], off
	v_lshl_add_u64 v[190:191], v[222:223], 0, s[14:15]
	s_mov_b32 m0, s83
	s_nop 0
	global_load_lds_dwordx4 v[190:191], off
	v_lshl_add_u64 v[190:191], v[224:225], 0, s[14:15]
	s_mov_b32 m0, s67
	s_nop 0
	global_load_lds_dwordx4 v[190:191], off
	v_lshl_add_u64 v[190:191], v[226:227], 0, s[14:15]
	s_mov_b32 m0, s68
	s_nop 0
	global_load_lds_dwordx4 v[190:191], off
	s_waitcnt vmcnt(8)
	s_waitcnt lgkmcnt(0)
	s_barrier
	s_setprio 1
	v_mfma_f32_16x16x32_bf16 v[60:63], v[150:153], v[182:185], v[60:63]
	v_mfma_f32_16x16x32_bf16 v[56:59], v[158:161], v[182:185], v[56:59]
	v_mfma_f32_16x16x32_bf16 v[44:47], v[150:153], v[194:197], v[44:47]
	v_mfma_f32_16x16x32_bf16 v[40:43], v[158:161], v[194:197], v[40:43]
	v_mfma_f32_16x16x32_bf16 v[28:31], v[150:153], v[202:205], v[28:31]
	v_mfma_f32_16x16x32_bf16 v[24:27], v[158:161], v[202:205], v[24:27]
	v_mfma_f32_16x16x32_bf16 v[12:15], v[150:153], v[210:213], v[12:15]
	v_mfma_f32_16x16x32_bf16 v[8:11], v[158:161], v[210:213], v[8:11]
	v_mfma_f32_16x16x32_bf16 v[60:63], v[154:157], v[186:189], v[60:63]
	v_mfma_f32_16x16x32_bf16 v[56:59], v[162:165], v[186:189], v[56:59]
	v_mfma_f32_16x16x32_bf16 v[44:47], v[154:157], v[198:201], v[44:47]
	v_mfma_f32_16x16x32_bf16 v[40:43], v[162:165], v[198:201], v[40:43]
	v_mfma_f32_16x16x32_bf16 v[28:31], v[154:157], v[206:209], v[28:31]
	v_mfma_f32_16x16x32_bf16 v[24:27], v[162:165], v[206:209], v[24:27]
	v_mfma_f32_16x16x32_bf16 v[12:15], v[154:157], v[214:217], v[12:15]
	v_mfma_f32_16x16x32_bf16 v[8:11], v[162:165], v[214:217], v[8:11]
	v_mfma_f32_16x16x32_bf16 v[52:55], v[166:169], v[182:185], v[52:55]
	v_mfma_f32_16x16x32_bf16 v[48:51], v[174:177], v[182:185], v[48:51]
	v_mfma_f32_16x16x32_bf16 v[36:39], v[166:169], v[194:197], v[36:39]
	v_mfma_f32_16x16x32_bf16 v[32:35], v[174:177], v[194:197], v[32:35]
	v_mfma_f32_16x16x32_bf16 v[20:23], v[166:169], v[202:205], v[20:23]
	v_mfma_f32_16x16x32_bf16 v[16:19], v[174:177], v[202:205], v[16:19]
	v_mfma_f32_16x16x32_bf16 v[4:7], v[166:169], v[210:213], v[4:7]
	v_mfma_f32_16x16x32_bf16 v[0:3], v[174:177], v[210:213], v[0:3]
	v_mfma_f32_16x16x32_bf16 v[52:55], v[170:173], v[186:189], v[52:55]
	v_mfma_f32_16x16x32_bf16 v[48:51], v[178:181], v[186:189], v[48:51]
	v_mfma_f32_16x16x32_bf16 v[36:39], v[170:173], v[198:201], v[36:39]
	v_mfma_f32_16x16x32_bf16 v[32:35], v[178:181], v[198:201], v[32:35]
	v_mfma_f32_16x16x32_bf16 v[20:23], v[170:173], v[206:209], v[20:23]
	v_mfma_f32_16x16x32_bf16 v[16:19], v[178:181], v[206:209], v[16:19]
	v_mfma_f32_16x16x32_bf16 v[4:7], v[170:173], v[214:217], v[4:7]
	v_mfma_f32_16x16x32_bf16 v[0:3], v[178:181], v[214:217], v[0:3]
	s_setprio 0
	s_barrier
	s_add_u32 s58, s58, 0x100
	s_addc_u32 s59, s59, 0
	s_add_u32 s33, s33, 0x100
	s_addc_u32 s89, s89, 0
	s_cmp_ge_i32 s90, s70
	s_mov_b32 s60, s90
	s_cbranch_scc0 .LBB0_633

; #define PG8_STAGE(bufoff, gbase, voff) do { _Pragma("unroll") for (int _i = 0; _i < 2; ++_i) \
;         __builtin_amdgcn_global_load_lds((const unsigned*)((const char*)(gbase) + (voff)[_i]), (PG8_LAS unsigned*)(lds + (bufoff) + ldsw + _i * 8192), 16, 0, 0); } while (0)
; #define PG8_LDA(dst, b, h) do { _Pragma("unroll") for (int m = 0; m < 4; ++m) _Pragma("unroll") for (int k = 0; k < 2; ++k) dst[m][k] = *(const PG8_LAS bf16x8*)(lds + PG8_SA(b, h) + aoff + m * 2048 + k * 1024); } while (0)
; #define PG8_LDB(dst, b, h) do { _Pragma("unroll") for (int n = 0; n < 2; ++n) _Pragma("unroll") for (int k = 0; k < 2; ++k) dst[n][k] = *(const PG8_LAS bf16x8*)(lds + PG8_SB(b, h) + boff + n * 2048 + k * 1024); } while (0)
; #define PG8_MMA(ai, bj, At, Bt) do { __builtin_amdgcn_s_setprio(1); _Pragma("unroll") for (int m = 0; m < 4; ++m) _Pragma("unroll") for (int n = 0; n < 2; ++n) _Pragma("unroll") for (int k = 0; k < 2; ++k) \
;         acc[ai][bj][m][n] = __builtin_amdgcn_mfma_f32_16x16x32_bf16(Bt[n][k], At[m][k], acc[ai][bj][m][n], 0, 0, 0); __builtin_amdgcn_s_setprio(0); } while (0)
; #define PG8_WAIT_V(n) asm volatile("s_waitcnt vmcnt(" #n ")" ::: "memory")
; #define PG8_BAR __builtin_amdgcn_s_barrier()
; template <class Epi, class Sched, bool ALIGN_EPI = false, bool SP2 = false>
; __device__ __forceinline__ void gemm_phase(PG8_LAS unsigned char* lds, const Gemm g, const Sched& S, const Epi& E) {
;     ...
;         for (int t = 0; t < nt; t += 2) {
;             const bool last = (t == nt - 2);
;             const char* a1 = cA + (size_t)(t + 1) * kstep;
;             const char* a2 = last ? nA : cA + (size_t)(t + 2) * kstep; const char* b2 = last ? nB : cB + (size_t)(t + 2) * kstep;
;             const char* a3 = a2 + kstep; const char* b3 = b2 + kstep;
;             if (last && has_next) S.a_ready(nxt);
;             if constexpr (SP2) {
;             PG8_LDB(B0, 0, 0); PG8_LDB(B1, 0, 1); PG8_SCHED; PG8_LDA(At, 0, 0); PG8_STAGE(PG8_SA(1, 1), a1 + hstep, voffA);
;             PG8_WAIT_V(8); PG8_WAIT_L(0); PG8_BAR; PG8_MMA(0, 0, At, B0); PG8_MMA(0, 1, At, B1); PG8_BAR; PG8_SCHED;
;             PG8_LDA(At, 0, 1); PG8_STAGE(PG8_SB(0, 0), b2, voffB); PG8_STAGE(PG8_SB(0, 1), b2 + hstep, voffB); PG8_STAGE(PG8_SA(0, 0), a2, voffA);
;             PG8_WAIT_V(8); PG8_WAIT_L(0); PG8_BAR; PG8_MMA(1, 0, At, B0); PG8_MMA(1, 1, At, B1); PG8_BAR; PG8_SCHED;
.LBB0_921:
	ds_read_b128 v[128:131], v247
	ds_read_b128 v[132:135], v247 offset:1024
	ds_read_b128 v[136:139], v247 offset:2048
	ds_read_b128 v[140:143], v247 offset:3072
	ds_read_b128 v[144:147], v248
	ds_read_b128 v[148:151], v248 offset:1024
	ds_read_b128 v[152:155], v248 offset:2048
	ds_read_b128 v[156:159], v248 offset:3072
	s_add_i32 s75, s58, 2
	s_add_u32 s76, s42, 0x80
	s_addc_u32 s59, s43, 0
	s_cmp_eq_u32 s66, s58
	s_cselect_b32 s58, s8, s76
	s_cselect_b32 s59, s9, s59
	s_cselect_b32 s77, s41, s33
	s_cselect_b32 s76, s40, s5
	v_lshl_add_u64 v[208:209], s[42:43], 0, v[202:203]
	s_add_i32 m0, s48, 0xc000
	ds_read_b128 v[160:163], v249
	ds_read_b128 v[164:167], v249 offset:1024
	ds_read_b128 v[168:171], v249 offset:2048
	ds_read_b128 v[172:175], v249 offset:3072
	ds_read_b128 v[176:179], v249 offset:4096
	ds_read_b128 v[180:183], v249 offset:5120
	ds_read_b128 v[184:187], v249 offset:6144
	ds_read_b128 v[188:191], v249 offset:7168
	global_load_lds_dwordx4 v[208:209], off
	v_lshl_add_u64 v[208:209], s[42:43], 0, v[204:205]
	s_add_i32 m0, s48, 0xe000
	s_nop 0
	global_load_lds_dwordx4 v[208:209], off
	s_waitcnt vmcnt(8)
	s_waitcnt lgkmcnt(0)
	s_barrier
	s_setprio 1
	v_mfma_f32_16x16x32_bf16 v[120:123], v[128:131], v[160:163], v[120:123]
	v_mfma_f32_16x16x32_bf16 v[124:127], v[136:139], v[160:163], v[124:127]
	v_mfma_f32_16x16x32_bf16 v[108:111], v[128:131], v[168:171], v[108:111]
	v_mfma_f32_16x16x32_bf16 v[104:107], v[136:139], v[168:171], v[104:107]
	v_mfma_f32_16x16x32_bf16 v[92:95], v[128:131], v[176:179], v[92:95]
	v_mfma_f32_16x16x32_bf16 v[88:91], v[136:139], v[176:179], v[88:91]
	v_mfma_f32_16x16x32_bf16 v[76:79], v[128:131], v[184:187], v[76:79]
	v_mfma_f32_16x16x32_bf16 v[72:75], v[136:139], v[184:187], v[72:75]
	v_mfma_f32_16x16x32_bf16 v[120:123], v[132:135], v[164:167], v[120:123]
	v_mfma_f32_16x16x32_bf16 v[124:127], v[140:143], v[164:167], v[124:127]
	v_mfma_f32_16x16x32_bf16 v[108:111], v[132:135], v[172:175], v[108:111]
	v_mfma_f32_16x16x32_bf16 v[104:107], v[140:143], v[172:175], v[104:107]
	v_mfma_f32_16x16x32_bf16 v[92:95], v[132:135], v[180:183], v[92:95]
	v_mfma_f32_16x16x32_bf16 v[88:91], v[140:143], v[180:183], v[88:91]
	v_mfma_f32_16x16x32_bf16 v[76:79], v[132:135], v[188:191], v[76:79]
	v_mfma_f32_16x16x32_bf16 v[72:75], v[140:143], v[188:191], v[72:75]
	v_mfma_f32_16x16x32_bf16 v[116:119], v[144:147], v[160:163], v[116:119]
	v_mfma_f32_16x16x32_bf16 v[112:115], v[152:155], v[160:163], v[112:115]
	v_mfma_f32_16x16x32_bf16 v[100:103], v[144:147], v[168:171], v[100:103]
	v_mfma_f32_16x16x32_bf16 v[96:99], v[152:155], v[168:171], v[96:99]
	v_mfma_f32_16x16x32_bf16 v[84:87], v[144:147], v[176:179], v[84:87]
	v_mfma_f32_16x16x32_bf16 v[80:83], v[152:155], v[176:179], v[80:83]
	v_mfma_f32_16x16x32_bf16 v[68:71], v[144:147], v[184:187], v[68:71]
	v_mfma_f32_16x16x32_bf16 v[64:67], v[152:155], v[184:187], v[64:67]
	v_mfma_f32_16x16x32_bf16 v[116:119], v[148:151], v[164:167], v[116:119]
	v_mfma_f32_16x16x32_bf16 v[112:115], v[156:159], v[164:167], v[112:115]
	v_mfma_f32_16x16x32_bf16 v[100:103], v[148:151], v[172:175], v[100:103]
	v_mfma_f32_16x16x32_bf16 v[96:99], v[156:159], v[172:175], v[96:99]
	v_mfma_f32_16x16x32_bf16 v[84:87], v[148:151], v[180:183], v[84:87]
	v_mfma_f32_16x16x32_bf16 v[80:83], v[156:159], v[180:183], v[80:83]
	v_mfma_f32_16x16x32_bf16 v[68:71], v[148:151], v[188:191], v[68:71]
	v_mfma_f32_16x16x32_bf16 v[64:67], v[156:159], v[188:191], v[64:67]
	s_setprio 0
	s_barrier
	s_add_i32 s78, s70, s3
	v_lshl_add_u64 v[208:209], s[76:77], 0, v[196:197]
	s_mov_b32 m0, s78
	ds_read_b128 v[160:163], v249 offset:16384
	ds_read_b128 v[164:167], v249 offset:17408
	ds_read_b128 v[168:171], v249 offset:18432
	ds_read_b128 v[172:175], v249 offset:19456
	ds_read_b128 v[176:179], v249 offset:20480
	ds_read_b128 v[180:183], v249 offset:21504
	ds_read_b128 v[184:187], v249 offset:22528
	ds_read_b128 v[188:191], v249 offset:23552
	global_load_lds_dwordx4 v[208:209], off
	s_add_i32 m0, s78, 0x2000
	v_lshl_add_u64 v[210:211], s[76:77], 0, v[200:201]
	s_add_u32 s76, s76, s14
	s_addc_u32 s77, s77, s15
	s_add_i32 s78, s71, s3
	global_load_lds_dwordx4 v[210:211], off
	v_lshl_add_u64 v[212:213], s[76:77], 0, v[196:197]
	s_mov_b32 m0, s78
	v_lshl_add_u64 v[214:215], s[76:77], 0, v[200:201]
	global_load_lds_dwordx4 v[212:213], off
	s_add_i32 m0, s78, 0x2000
	v_lshl_add_u64 v[216:217], s[58:59], 0, v[194:195]
	global_load_lds_dwordx4 v[214:215], off
	s_mov_b32 m0, s48
	v_lshl_add_u64 v[218:219], s[58:59], 0, v[198:199]
	global_load_lds_dwordx4 v[216:217], off
	s_mov_b32 m0, s49
	s_nop 0
	global_load_lds_dwordx4 v[218:219], off
	s_waitcnt vmcnt(8)
	s_waitcnt lgkmcnt(0)
	s_barrier
; #define PG8_STAGE(bufoff, gbase, voff) do { _Pragma("unroll") for (int _i = 0; _i < 2; ++_i) \
;         __builtin_amdgcn_global_load_lds((const unsigned*)((const char*)(gbase) + (voff)[_i]), (PG8_LAS unsigned*)(lds + (bufoff) + ldsw + _i * 8192), 16, 0, 0); } while (0)
; #define PG8_LDA(dst, b, h) do { _Pragma("unroll") for (int m = 0; m < 4; ++m) _Pragma("unroll") for (int k = 0; k < 2; ++k) dst[m][k] = *(const PG8_LAS bf16x8*)(lds + PG8_SA(b, h) + aoff + m * 2048 + k * 1024); } while (0)
; #define PG8_LDB(dst, b, h) do { _Pragma("unroll") for (int n = 0; n < 2; ++n) _Pragma("unroll") for (int k = 0; k < 2; ++k) dst[n][k] = *(const PG8_LAS bf16x8*)(lds + PG8_SB(b, h) + boff + n * 2048 + k * 1024); } while (0)
; #define PG8_MMA(ai, bj, At, Bt) do { __builtin_amdgcn_s_setprio(1); _Pragma("unroll") for (int m = 0; m < 4; ++m) _Pragma("unroll") for (int n = 0; n < 2; ++n) _Pragma("unroll") for (int k = 0; k < 2; ++k) \
;         acc[ai][bj][m][n] = __builtin_amdgcn_mfma_f32_16x16x32_bf16(Bt[n][k], At[m][k], acc[ai][bj][m][n], 0, 0, 0); __builtin_amdgcn_s_setprio(0); } while (0)
; #define PG8_WAIT_V(n) asm volatile("s_waitcnt vmcnt(" #n ")" ::: "memory")
; #define PG8_WAIT_L(n) asm volatile("s_waitcnt lgkmcnt(" #n ")" ::: "memory")
; #define PG8_BAR __builtin_amdgcn_s_barrier()
; #define PG8_SCHED __builtin_amdgcn_sched_barrier(0)
; template <class Epi, class Sched, bool ALIGN_EPI = false, bool SP2 = false>
; __device__ __forceinline__ void gemm_phase(PG8_LAS unsigned char* lds, const Gemm g, const Sched& S, const Epi& E) {
;     ...
;             PG8_WAIT_V(8); PG8_WAIT_L(0); PG8_BAR; PG8_MMA(1, 0, At, B0); PG8_MMA(1, 1, At, B1); PG8_BAR; PG8_SCHED;
;             PG8_LDB(B0, 1, 0); PG8_LDB(B1, 1, 1); PG8_SCHED; PG8_LDA(At, 1, 0); PG8_STAGE(PG8_SA(0, 1), a2 + hstep, voffA);
;             PG8_WAIT_V(8); PG8_WAIT_L(0); PG8_BAR; PG8_MMA(0, 0, At, B0); PG8_MMA(0, 1, At, B1); PG8_BAR; PG8_SCHED;
	s_setprio 1
	v_mfma_f32_16x16x32_bf16 v[60:63], v[128:131], v[160:163], v[60:63]
	v_mfma_f32_16x16x32_bf16 v[56:59], v[136:139], v[160:163], v[56:59]
	v_mfma_f32_16x16x32_bf16 v[44:47], v[128:131], v[168:171], v[44:47]
	v_mfma_f32_16x16x32_bf16 v[40:43], v[136:139], v[168:171], v[40:43]
	v_mfma_f32_16x16x32_bf16 v[28:31], v[128:131], v[176:179], v[28:31]
	v_mfma_f32_16x16x32_bf16 v[24:27], v[136:139], v[176:179], v[24:27]
	v_mfma_f32_16x16x32_bf16 v[12:15], v[128:131], v[184:187], v[12:15]
	v_mfma_f32_16x16x32_bf16 v[8:11], v[136:139], v[184:187], v[8:11]
	v_mfma_f32_16x16x32_bf16 v[60:63], v[132:135], v[164:167], v[60:63]
	v_mfma_f32_16x16x32_bf16 v[56:59], v[140:143], v[164:167], v[56:59]
	v_mfma_f32_16x16x32_bf16 v[44:47], v[132:135], v[172:175], v[44:47]
	v_mfma_f32_16x16x32_bf16 v[40:43], v[140:143], v[172:175], v[40:43]
	v_mfma_f32_16x16x32_bf16 v[28:31], v[132:135], v[180:183], v[28:31]
	v_mfma_f32_16x16x32_bf16 v[24:27], v[140:143], v[180:183], v[24:27]
	v_mfma_f32_16x16x32_bf16 v[12:15], v[132:135], v[188:191], v[12:15]
	v_mfma_f32_16x16x32_bf16 v[8:11], v[140:143], v[188:191], v[8:11]
	v_mfma_f32_16x16x32_bf16 v[52:55], v[144:147], v[160:163], v[52:55]
	v_mfma_f32_16x16x32_bf16 v[48:51], v[152:155], v[160:163], v[48:51]
	v_mfma_f32_16x16x32_bf16 v[36:39], v[144:147], v[168:171], v[36:39]
	v_mfma_f32_16x16x32_bf16 v[32:35], v[152:155], v[168:171], v[32:35]
	v_mfma_f32_16x16x32_bf16 v[20:23], v[144:147], v[176:179], v[20:23]
	v_mfma_f32_16x16x32_bf16 v[16:19], v[152:155], v[176:179], v[16:19]
	v_mfma_f32_16x16x32_bf16 v[4:7], v[144:147], v[184:187], v[4:7]
	v_mfma_f32_16x16x32_bf16 v[0:3], v[152:155], v[184:187], v[0:3]
	v_mfma_f32_16x16x32_bf16 v[52:55], v[148:151], v[164:167], v[52:55]
	v_mfma_f32_16x16x32_bf16 v[48:51], v[156:159], v[164:167], v[48:51]
	v_mfma_f32_16x16x32_bf16 v[36:39], v[148:151], v[172:175], v[36:39]
	v_mfma_f32_16x16x32_bf16 v[32:35], v[156:159], v[172:175], v[32:35]
	v_mfma_f32_16x16x32_bf16 v[20:23], v[148:151], v[180:183], v[20:23]
	v_mfma_f32_16x16x32_bf16 v[16:19], v[156:159], v[180:183], v[16:19]
	v_mfma_f32_16x16x32_bf16 v[4:7], v[148:151], v[188:191], v[4:7]
	v_mfma_f32_16x16x32_bf16 v[0:3], v[156:159], v[188:191], v[0:3]
	s_setprio 0
	s_barrier
	s_add_i32 s76, 0, 0x18000
	s_add_i32 s77, 0, 0x1c000
	v_add_u32_e32 v140, s76, v244
	v_add_u32_e32 v156, s77, v244
	ds_read_b128 v[128:131], v140
	ds_read_b128 v[132:135], v140 offset:1024
	ds_read_b128 v[136:139], v140 offset:2048
	ds_read_b128 v[140:143], v140 offset:3072
	ds_read_b128 v[144:147], v156
	ds_read_b128 v[148:151], v156 offset:1024
	ds_read_b128 v[152:155], v156 offset:2048
	ds_read_b128 v[156:159], v156 offset:3072
	s_add_u32 s58, s58, s14
	s_addc_u32 s59, s59, s15
	s_mov_b32 m0, s60
	v_lshl_add_u64 v[220:221], s[58:59], 0, v[194:195]
	ds_read_b128 v[160:163], v249 offset:32768
	ds_read_b128 v[164:167], v249 offset:33792
	ds_read_b128 v[168:171], v249 offset:34816
	ds_read_b128 v[172:175], v249 offset:35840
	ds_read_b128 v[176:179], v249 offset:36864
	ds_read_b128 v[180:183], v249 offset:37888
	ds_read_b128 v[184:187], v249 offset:38912
	ds_read_b128 v[188:191], v249 offset:39936
	global_load_lds_dwordx4 v[220:221], off
	v_lshl_add_u64 v[220:221], s[58:59], 0, v[198:199]
	s_mov_b32 m0, s61
	s_nop 0
	global_load_lds_dwordx4 v[220:221], off
	s_waitcnt vmcnt(8)
	s_waitcnt lgkmcnt(0)
	s_barrier
	s_setprio 1
	v_mfma_f32_16x16x32_bf16 v[120:123], v[128:131], v[160:163], v[120:123]
	v_mfma_f32_16x16x32_bf16 v[124:127], v[136:139], v[160:163], v[124:127]
	v_mfma_f32_16x16x32_bf16 v[108:111], v[128:131], v[168:171], v[108:111]
	v_mfma_f32_16x16x32_bf16 v[104:107], v[136:139], v[168:171], v[104:107]
	v_mfma_f32_16x16x32_bf16 v[92:95], v[128:131], v[176:179], v[92:95]
	v_mfma_f32_16x16x32_bf16 v[88:91], v[136:139], v[176:179], v[88:91]
	v_mfma_f32_16x16x32_bf16 v[76:79], v[128:131], v[184:187], v[76:79]
	v_mfma_f32_16x16x32_bf16 v[72:75], v[136:139], v[184:187], v[72:75]
	v_mfma_f32_16x16x32_bf16 v[120:123], v[132:135], v[164:167], v[120:123]
	v_mfma_f32_16x16x32_bf16 v[124:127], v[140:143], v[164:167], v[124:127]
	v_mfma_f32_16x16x32_bf16 v[108:111], v[132:135], v[172:175], v[108:111]
	v_mfma_f32_16x16x32_bf16 v[104:107], v[140:143], v[172:175], v[104:107]
	v_mfma_f32_16x16x32_bf16 v[92:95], v[132:135], v[180:183], v[92:95]
	v_mfma_f32_16x16x32_bf16 v[88:91], v[140:143], v[180:183], v[88:91]
	v_mfma_f32_16x16x32_bf16 v[76:79], v[132:135], v[188:191], v[76:79]
	v_mfma_f32_16x16x32_bf16 v[72:75], v[140:143], v[188:191], v[72:75]
	v_mfma_f32_16x16x32_bf16 v[116:119], v[144:147], v[160:163], v[116:119]
	v_mfma_f32_16x16x32_bf16 v[112:115], v[152:155], v[160:163], v[112:115]
	v_mfma_f32_16x16x32_bf16 v[100:103], v[144:147], v[168:171], v[100:103]
	v_mfma_f32_16x16x32_bf16 v[96:99], v[152:155], v[168:171], v[96:99]
	v_mfma_f32_16x16x32_bf16 v[84:87], v[144:147], v[176:179], v[84:87]
	v_mfma_f32_16x16x32_bf16 v[80:83], v[152:155], v[176:179], v[80:83]
	v_mfma_f32_16x16x32_bf16 v[68:71], v[144:147], v[184:187], v[68:71]
	v_mfma_f32_16x16x32_bf16 v[64:67], v[152:155], v[184:187], v[64:67]
	v_mfma_f32_16x16x32_bf16 v[116:119], v[148:151], v[164:167], v[116:119]
	v_mfma_f32_16x16x32_bf16 v[112:115], v[156:159], v[164:167], v[112:115]
	v_mfma_f32_16x16x32_bf16 v[100:103], v[148:151], v[172:175], v[100:103]
	v_mfma_f32_16x16x32_bf16 v[96:99], v[156:159], v[172:175], v[96:99]
	v_mfma_f32_16x16x32_bf16 v[84:87], v[148:151], v[180:183], v[84:87]
	v_mfma_f32_16x16x32_bf16 v[80:83], v[156:159], v[180:183], v[80:83]
	v_mfma_f32_16x16x32_bf16 v[68:71], v[148:151], v[188:191], v[68:71]
	v_mfma_f32_16x16x32_bf16 v[64:67], v[156:159], v[188:191], v[64:67]
	s_setprio 0
	s_barrier
; #define PG8_STAGE(bufoff, gbase, voff) do { _Pragma("unroll") for (int _i = 0; _i < 2; ++_i) \
;         __builtin_amdgcn_global_load_lds((const unsigned*)((const char*)(gbase) + (voff)[_i]), (PG8_LAS unsigned*)(lds + (bufoff) + ldsw + _i * 8192), 16, 0, 0); } while (0)
; #define PG8_LDA(dst, b, h) do { _Pragma("unroll") for (int m = 0; m < 4; ++m) _Pragma("unroll") for (int k = 0; k < 2; ++k) dst[m][k] = *(const PG8_LAS bf16x8*)(lds + PG8_SA(b, h) + aoff + m * 2048 + k * 1024); } while (0)
; #define PG8_MMA(ai, bj, At, Bt) do { __builtin_amdgcn_s_setprio(1); _Pragma("unroll") for (int m = 0; m < 4; ++m) _Pragma("unroll") for (int n = 0; n < 2; ++n) _Pragma("unroll") for (int k = 0; k < 2; ++k) \
;         acc[ai][bj][m][n] = __builtin_amdgcn_mfma_f32_16x16x32_bf16(Bt[n][k], At[m][k], acc[ai][bj][m][n], 0, 0, 0); __builtin_amdgcn_s_setprio(0); } while (0)
; #define PG8_WAIT_V(n) asm volatile("s_waitcnt vmcnt(" #n ")" ::: "memory")
; #define PG8_WAIT_L(n) asm volatile("s_waitcnt lgkmcnt(" #n ")" ::: "memory")
; #define PG8_BAR __builtin_amdgcn_s_barrier()
; #define PG8_SCHED __builtin_amdgcn_sched_barrier(0)
; template <class Epi, class Sched, bool ALIGN_EPI = false, bool SP2 = false>
; __device__ __forceinline__ void gemm_phase(PG8_LAS unsigned char* lds, const Gemm g, const Sched& S, const Epi& E) {
;     ...
;             PG8_LDA(At, 1, 1); PG8_STAGE(PG8_SB(1, 0), b3, voffB); PG8_STAGE(PG8_SB(1, 1), b3 + hstep, voffB); PG8_STAGE(PG8_SA(1, 0), a3, voffA);
;             PG8_WAIT_V(8); PG8_WAIT_L(0); PG8_BAR; PG8_MMA(1, 0, At, B0); PG8_MMA(1, 1, At, B1); PG8_BAR; PG8_SCHED;
	s_add_i32 s58, s76, s3
	v_lshl_add_u64 v[208:209], v[208:209], 0, s[22:23]
	s_mov_b32 m0, s58
	ds_read_b128 v[160:163], v249 offset:49152
	ds_read_b128 v[164:167], v249 offset:50176
	ds_read_b128 v[168:171], v249 offset:51200
	ds_read_b128 v[172:175], v249 offset:52224
	ds_read_b128 v[176:179], v249 offset:53248
	ds_read_b128 v[180:183], v249 offset:54272
	ds_read_b128 v[184:187], v249 offset:55296
	ds_read_b128 v[188:191], v249 offset:56320
	global_load_lds_dwordx4 v[208:209], off
	v_lshl_add_u64 v[208:209], v[210:211], 0, s[22:23]
	s_add_i32 m0, s58, 0x2000
	s_add_i32 s58, s77, s3
	global_load_lds_dwordx4 v[208:209], off
	v_lshl_add_u64 v[208:209], v[212:213], 0, s[22:23]
	s_mov_b32 m0, s58
	s_nop 0
	global_load_lds_dwordx4 v[208:209], off
	v_lshl_add_u64 v[208:209], v[214:215], 0, s[22:23]
	s_add_i32 m0, s58, 0x2000
	s_nop 0
	global_load_lds_dwordx4 v[208:209], off
	v_lshl_add_u64 v[208:209], v[216:217], 0, s[22:23]
	s_mov_b32 m0, s62
	s_nop 0
	global_load_lds_dwordx4 v[208:209], off
	v_lshl_add_u64 v[208:209], v[218:219], 0, s[22:23]
	s_mov_b32 m0, s63
	s_nop 0
	global_load_lds_dwordx4 v[208:209], off
	s_waitcnt vmcnt(8)
	s_waitcnt lgkmcnt(0)
	s_barrier
	s_setprio 1
	v_mfma_f32_16x16x32_bf16 v[60:63], v[128:131], v[160:163], v[60:63]
	v_mfma_f32_16x16x32_bf16 v[56:59], v[136:139], v[160:163], v[56:59]
	v_mfma_f32_16x16x32_bf16 v[44:47], v[128:131], v[168:171], v[44:47]
	v_mfma_f32_16x16x32_bf16 v[40:43], v[136:139], v[168:171], v[40:43]
	v_mfma_f32_16x16x32_bf16 v[28:31], v[128:131], v[176:179], v[28:31]
	v_mfma_f32_16x16x32_bf16 v[24:27], v[136:139], v[176:179], v[24:27]
	v_mfma_f32_16x16x32_bf16 v[12:15], v[128:131], v[184:187], v[12:15]
	v_mfma_f32_16x16x32_bf16 v[8:11], v[136:139], v[184:187], v[8:11]
	v_mfma_f32_16x16x32_bf16 v[60:63], v[132:135], v[164:167], v[60:63]
	v_mfma_f32_16x16x32_bf16 v[56:59], v[140:143], v[164:167], v[56:59]
	v_mfma_f32_16x16x32_bf16 v[44:47], v[132:135], v[172:175], v[44:47]
	v_mfma_f32_16x16x32_bf16 v[40:43], v[140:143], v[172:175], v[40:43]
	v_mfma_f32_16x16x32_bf16 v[28:31], v[132:135], v[180:183], v[28:31]
	v_mfma_f32_16x16x32_bf16 v[24:27], v[140:143], v[180:183], v[24:27]
	v_mfma_f32_16x16x32_bf16 v[12:15], v[132:135], v[188:191], v[12:15]
	v_mfma_f32_16x16x32_bf16 v[8:11], v[140:143], v[188:191], v[8:11]
	v_mfma_f32_16x16x32_bf16 v[52:55], v[144:147], v[160:163], v[52:55]
	v_mfma_f32_16x16x32_bf16 v[48:51], v[152:155], v[160:163], v[48:51]
	v_mfma_f32_16x16x32_bf16 v[36:39], v[144:147], v[168:171], v[36:39]
	v_mfma_f32_16x16x32_bf16 v[32:35], v[152:155], v[168:171], v[32:35]
	v_mfma_f32_16x16x32_bf16 v[20:23], v[144:147], v[176:179], v[20:23]
	v_mfma_f32_16x16x32_bf16 v[16:19], v[152:155], v[176:179], v[16:19]
	v_mfma_f32_16x16x32_bf16 v[4:7], v[144:147], v[184:187], v[4:7]
	v_mfma_f32_16x16x32_bf16 v[0:3], v[152:155], v[184:187], v[0:3]
	v_mfma_f32_16x16x32_bf16 v[52:55], v[148:151], v[164:167], v[52:55]
	v_mfma_f32_16x16x32_bf16 v[48:51], v[156:159], v[164:167], v[48:51]
	v_mfma_f32_16x16x32_bf16 v[36:39], v[148:151], v[172:175], v[36:39]
	v_mfma_f32_16x16x32_bf16 v[32:35], v[156:159], v[172:175], v[32:35]
	v_mfma_f32_16x16x32_bf16 v[20:23], v[148:151], v[180:183], v[20:23]
	v_mfma_f32_16x16x32_bf16 v[16:19], v[156:159], v[180:183], v[16:19]
	v_mfma_f32_16x16x32_bf16 v[4:7], v[148:151], v[188:191], v[4:7]
	v_mfma_f32_16x16x32_bf16 v[0:3], v[156:159], v[188:191], v[0:3]
	s_setprio 0
	s_barrier
	s_add_u32 s42, s42, 0x100
	s_addc_u32 s43, s43, 0
	s_add_u32 s5, s5, 0x100
	s_addc_u32 s33, s33, 0
	s_cmp_ge_i32 s75, s65
	s_mov_b32 s58, s75
	s_cbranch_scc0 .LBB0_921

; #define PG8_STAGE(bufoff, gbase, voff) do { _Pragma("unroll") for (int _i = 0; _i < 2; ++_i) \
;         __builtin_amdgcn_global_load_lds((const unsigned*)((const char*)(gbase) + (voff)[_i]), (PG8_LAS unsigned*)(lds + (bufoff) + ldsw + _i * 8192), 16, 0, 0); } while (0)
; #define PG8_LDA(dst, b, h) do { _Pragma("unroll") for (int m = 0; m < 4; ++m) _Pragma("unroll") for (int k = 0; k < 2; ++k) dst[m][k] = *(const PG8_LAS bf16x8*)(lds + PG8_SA(b, h) + aoff + m * 2048 + k * 1024); } while (0)
; #define PG8_LDB(dst, b, h) do { _Pragma("unroll") for (int n = 0; n < 2; ++n) _Pragma("unroll") for (int k = 0; k < 2; ++k) dst[n][k] = *(const PG8_LAS bf16x8*)(lds + PG8_SB(b, h) + boff + n * 2048 + k * 1024); } while (0)
; #define PG8_MMA(ai, bj, At, Bt) do { __builtin_amdgcn_s_setprio(1); _Pragma("unroll") for (int m = 0; m < 4; ++m) _Pragma("unroll") for (int n = 0; n < 2; ++n) _Pragma("unroll") for (int k = 0; k < 2; ++k) \
;         acc[ai][bj][m][n] = __builtin_amdgcn_mfma_f32_16x16x32_bf16(Bt[n][k], At[m][k], acc[ai][bj][m][n], 0, 0, 0); __builtin_amdgcn_s_setprio(0); } while (0)
; #define PG8_WAIT_V(n) asm volatile("s_waitcnt vmcnt(" #n ")" ::: "memory")
; #define PG8_BAR __builtin_amdgcn_s_barrier()
; template <class Epi, class Sched, bool ALIGN_EPI = false, bool SP2 = false>
; __device__ __forceinline__ void gemm_phase(PG8_LAS unsigned char* lds, const Gemm g, const Sched& S, const Epi& E) {
;     ...
;         for (int t = 0; t < nt; t += 2) {
;             const bool last = (t == nt - 2);
;             const char* a1 = cA + (size_t)(t + 1) * kstep;
;             const char* a2 = last ? nA : cA + (size_t)(t + 2) * kstep; const char* b2 = last ? nB : cB + (size_t)(t + 2) * kstep;
;             const char* a3 = a2 + kstep; const char* b3 = b2 + kstep;
;             if (last && has_next) S.a_ready(nxt);
;             if constexpr (SP2) {
;             PG8_LDB(B0, 0, 0); PG8_LDB(B1, 0, 1); PG8_SCHED; PG8_LDA(At, 0, 0); PG8_STAGE(PG8_SA(1, 1), a1 + hstep, voffA);
;             PG8_WAIT_V(8); PG8_WAIT_L(0); PG8_BAR; PG8_MMA(0, 0, At, B0); PG8_MMA(0, 1, At, B1); PG8_BAR; PG8_SCHED;
;             PG8_LDA(At, 0, 1); PG8_STAGE(PG8_SB(0, 0), b2, voffB); PG8_STAGE(PG8_SB(0, 1), b2 + hstep, voffB); PG8_STAGE(PG8_SA(0, 0), a2, voffA);
;             PG8_WAIT_V(8); PG8_WAIT_L(0); PG8_BAR; PG8_MMA(1, 0, At, B0); PG8_MMA(1, 1, At, B1); PG8_BAR; PG8_SCHED;
.LBB0_1014:
	ds_read_b128 v[146:149], v167
	ds_read_b128 v[150:153], v167 offset:1024
	ds_read_b128 v[154:157], v167 offset:2048
	ds_read_b128 v[158:161], v167 offset:3072
	ds_read_b128 v[172:175], v168
	ds_read_b128 v[176:179], v168 offset:1024
	ds_read_b128 v[180:183], v168 offset:2048
	ds_read_b128 v[184:187], v168 offset:3072
	s_add_i32 s71, s38, 2
	s_add_u32 s72, s36, 0x80
	s_addc_u32 s39, s37, 0
	s_cmp_eq_u32 s62, s38
	s_cselect_b32 s38, s6, s72
	s_cselect_b32 s39, s7, s39
	s_cselect_b32 s73, s23, s70
	s_cselect_b32 s72, s22, s33
	v_lshl_add_u64 v[162:163], s[36:37], 0, v[138:139]
	s_add_i32 m0, s48, 0xc000
	ds_read_b128 v[188:191], v169
	ds_read_b128 v[194:197], v169 offset:1024
	ds_read_b128 v[198:201], v169 offset:2048
	ds_read_b128 v[202:205], v169 offset:3072
	ds_read_b128 v[206:209], v169 offset:4096
	ds_read_b128 v[210:213], v169 offset:5120
	ds_read_b128 v[214:217], v169 offset:6144
	ds_read_b128 v[218:221], v169 offset:7168
	global_load_lds_dwordx4 v[162:163], off
	v_lshl_add_u64 v[162:163], s[36:37], 0, v[140:141]
	s_add_i32 m0, s48, 0xe000
	s_nop 0
	global_load_lds_dwordx4 v[162:163], off
	s_waitcnt vmcnt(8)
	s_waitcnt lgkmcnt(0)
	s_barrier
	s_setprio 1
	v_mfma_f32_16x16x32_bf16 v[120:123], v[146:149], v[188:191], v[120:123]
	v_mfma_f32_16x16x32_bf16 v[116:119], v[154:157], v[188:191], v[116:119]
	v_mfma_f32_16x16x32_bf16 v[108:111], v[146:149], v[198:201], v[108:111]
	v_mfma_f32_16x16x32_bf16 v[100:103], v[154:157], v[198:201], v[100:103]
	v_mfma_f32_16x16x32_bf16 v[92:95], v[146:149], v[206:209], v[92:95]
	v_mfma_f32_16x16x32_bf16 v[84:87], v[154:157], v[206:209], v[84:87]
	v_mfma_f32_16x16x32_bf16 v[76:79], v[146:149], v[214:217], v[76:79]
	v_mfma_f32_16x16x32_bf16 v[68:71], v[154:157], v[214:217], v[68:71]
	v_mfma_f32_16x16x32_bf16 v[120:123], v[150:153], v[194:197], v[120:123]
	v_mfma_f32_16x16x32_bf16 v[116:119], v[158:161], v[194:197], v[116:119]
	v_mfma_f32_16x16x32_bf16 v[108:111], v[150:153], v[202:205], v[108:111]
	v_mfma_f32_16x16x32_bf16 v[100:103], v[158:161], v[202:205], v[100:103]
	v_mfma_f32_16x16x32_bf16 v[92:95], v[150:153], v[210:213], v[92:95]
	v_mfma_f32_16x16x32_bf16 v[84:87], v[158:161], v[210:213], v[84:87]
	v_mfma_f32_16x16x32_bf16 v[76:79], v[150:153], v[218:221], v[76:79]
	v_mfma_f32_16x16x32_bf16 v[68:71], v[158:161], v[218:221], v[68:71]
	v_mfma_f32_16x16x32_bf16 v[124:127], v[172:175], v[188:191], v[124:127]
	v_mfma_f32_16x16x32_bf16 v[112:115], v[180:183], v[188:191], v[112:115]
	v_mfma_f32_16x16x32_bf16 v[104:107], v[172:175], v[198:201], v[104:107]
	v_mfma_f32_16x16x32_bf16 v[96:99], v[180:183], v[198:201], v[96:99]
	v_mfma_f32_16x16x32_bf16 v[88:91], v[172:175], v[206:209], v[88:91]
	v_mfma_f32_16x16x32_bf16 v[80:83], v[180:183], v[206:209], v[80:83]
	v_mfma_f32_16x16x32_bf16 v[72:75], v[172:175], v[214:217], v[72:75]
	v_mfma_f32_16x16x32_bf16 v[64:67], v[180:183], v[214:217], v[64:67]
	v_mfma_f32_16x16x32_bf16 v[124:127], v[176:179], v[194:197], v[124:127]
	v_mfma_f32_16x16x32_bf16 v[112:115], v[184:187], v[194:197], v[112:115]
	v_mfma_f32_16x16x32_bf16 v[104:107], v[176:179], v[202:205], v[104:107]
	v_mfma_f32_16x16x32_bf16 v[96:99], v[184:187], v[202:205], v[96:99]
	v_mfma_f32_16x16x32_bf16 v[88:91], v[176:179], v[210:213], v[88:91]
	v_mfma_f32_16x16x32_bf16 v[80:83], v[184:187], v[210:213], v[80:83]
	v_mfma_f32_16x16x32_bf16 v[72:75], v[176:179], v[218:221], v[72:75]
	v_mfma_f32_16x16x32_bf16 v[64:67], v[184:187], v[218:221], v[64:67]
	s_setprio 0
	s_barrier
	s_add_i32 s74, s65, s41
	v_lshl_add_u64 v[162:163], s[72:73], 0, v[132:133]
	s_mov_b32 m0, s74
	ds_read_b128 v[188:191], v169 offset:16384
	ds_read_b128 v[194:197], v169 offset:17408
	ds_read_b128 v[198:201], v169 offset:18432
	ds_read_b128 v[202:205], v169 offset:19456
	ds_read_b128 v[206:209], v169 offset:20480
	ds_read_b128 v[210:213], v169 offset:21504
	ds_read_b128 v[214:217], v169 offset:22528
	ds_read_b128 v[218:221], v169 offset:23552
	global_load_lds_dwordx4 v[162:163], off
	s_add_i32 m0, s74, 0x2000
	v_lshl_add_u64 v[222:223], s[72:73], 0, v[128:129]
	s_add_u32 s72, s72, s10
	s_addc_u32 s73, s73, s11
	s_add_i32 s74, s66, s41
	global_load_lds_dwordx4 v[222:223], off
	v_lshl_add_u64 v[224:225], s[72:73], 0, v[132:133]
	s_mov_b32 m0, s74
	v_lshl_add_u64 v[226:227], s[72:73], 0, v[128:129]
	global_load_lds_dwordx4 v[224:225], off
	s_add_i32 m0, s74, 0x2000
	v_lshl_add_u64 v[228:229], s[38:39], 0, v[134:135]
	global_load_lds_dwordx4 v[226:227], off
	s_mov_b32 m0, s48
	v_lshl_add_u64 v[230:231], s[38:39], 0, v[130:131]
	global_load_lds_dwordx4 v[228:229], off
	s_mov_b32 m0, s49
	s_nop 0
	global_load_lds_dwordx4 v[230:231], off
	s_cmp_lg_u32 s71, 2
	s_cbranch_scc1 .Lss_p6_skip
	s_lshl_b32 s84, s4, 14
	s_mov_b32 s85, 0
	s_add_i32 m0, s48, 0x20000
	v_lshl_add_u64 v[238:239], v[236:237], 0, s[84:85]
	s_add_u32 s84, s84, 0x2000
	global_load_lds_dwordx4 v[238:239], off
	s_add_i32 m0, s48, 0x22000
	v_lshl_add_u64 v[238:239], v[236:237], 0, s[84:85]
	global_load_lds_dwordx4 v[238:239], off
; #define PG8_STAGE(bufoff, gbase, voff) do { _Pragma("unroll") for (int _i = 0; _i < 2; ++_i) \
;         __builtin_amdgcn_global_load_lds((const unsigned*)((const char*)(gbase) + (voff)[_i]), (PG8_LAS unsigned*)(lds + (bufoff) + ldsw + _i * 8192), 16, 0, 0); } while (0)
; #define PG8_LDA(dst, b, h) do { _Pragma("unroll") for (int m = 0; m < 4; ++m) _Pragma("unroll") for (int k = 0; k < 2; ++k) dst[m][k] = *(const PG8_LAS bf16x8*)(lds + PG8_SA(b, h) + aoff + m * 2048 + k * 1024); } while (0)
; #define PG8_LDB(dst, b, h) do { _Pragma("unroll") for (int n = 0; n < 2; ++n) _Pragma("unroll") for (int k = 0; k < 2; ++k) dst[n][k] = *(const PG8_LAS bf16x8*)(lds + PG8_SB(b, h) + boff + n * 2048 + k * 1024); } while (0)
; #define PG8_MMA(ai, bj, At, Bt) do { __builtin_amdgcn_s_setprio(1); _Pragma("unroll") for (int m = 0; m < 4; ++m) _Pragma("unroll") for (int n = 0; n < 2; ++n) _Pragma("unroll") for (int k = 0; k < 2; ++k) \
;         acc[ai][bj][m][n] = __builtin_amdgcn_mfma_f32_16x16x32_bf16(Bt[n][k], At[m][k], acc[ai][bj][m][n], 0, 0, 0); __builtin_amdgcn_s_setprio(0); } while (0)
; #define PG8_WAIT_V(n) asm volatile("s_waitcnt vmcnt(" #n ")" ::: "memory")
; #define PG8_WAIT_L(n) asm volatile("s_waitcnt lgkmcnt(" #n ")" ::: "memory")
; #define PG8_BAR __builtin_amdgcn_s_barrier()
; #define PG8_SCHED __builtin_amdgcn_sched_barrier(0)
; template <class Epi, class Sched, bool ALIGN_EPI = false, bool SP2 = false>
; __device__ __forceinline__ void gemm_phase(PG8_LAS unsigned char* lds, const Gemm g, const Sched& S, const Epi& E) {
;     ...
;             PG8_WAIT_V(8); PG8_WAIT_L(0); PG8_BAR; PG8_MMA(1, 0, At, B0); PG8_MMA(1, 1, At, B1); PG8_BAR; PG8_SCHED;
;             PG8_LDB(B0, 1, 0); PG8_LDB(B1, 1, 1); PG8_SCHED; PG8_LDA(At, 1, 0); PG8_STAGE(PG8_SA(0, 1), a2 + hstep, voffA);
;             PG8_WAIT_V(8); PG8_WAIT_L(0); PG8_BAR; PG8_MMA(0, 0, At, B0); PG8_MMA(0, 1, At, B1); PG8_BAR; PG8_SCHED;
.Lss_p6_skip:
	s_waitcnt vmcnt(8)
	s_waitcnt lgkmcnt(0)
	s_barrier
	s_setprio 1
	v_mfma_f32_16x16x32_bf16 v[60:63], v[146:149], v[188:191], v[60:63]
	v_mfma_f32_16x16x32_bf16 v[52:55], v[154:157], v[188:191], v[52:55]
	v_mfma_f32_16x16x32_bf16 v[44:47], v[146:149], v[198:201], v[44:47]
	v_mfma_f32_16x16x32_bf16 v[36:39], v[154:157], v[198:201], v[36:39]
	v_mfma_f32_16x16x32_bf16 v[28:31], v[146:149], v[206:209], v[28:31]
	v_mfma_f32_16x16x32_bf16 v[20:23], v[154:157], v[206:209], v[20:23]
	v_mfma_f32_16x16x32_bf16 v[12:15], v[146:149], v[214:217], v[12:15]
	v_mfma_f32_16x16x32_bf16 v[4:7], v[154:157], v[214:217], v[4:7]
	v_mfma_f32_16x16x32_bf16 v[60:63], v[150:153], v[194:197], v[60:63]
	v_mfma_f32_16x16x32_bf16 v[52:55], v[158:161], v[194:197], v[52:55]
	v_mfma_f32_16x16x32_bf16 v[44:47], v[150:153], v[202:205], v[44:47]
	v_mfma_f32_16x16x32_bf16 v[36:39], v[158:161], v[202:205], v[36:39]
	v_mfma_f32_16x16x32_bf16 v[28:31], v[150:153], v[210:213], v[28:31]
	v_mfma_f32_16x16x32_bf16 v[20:23], v[158:161], v[210:213], v[20:23]
	v_mfma_f32_16x16x32_bf16 v[12:15], v[150:153], v[218:221], v[12:15]
	v_mfma_f32_16x16x32_bf16 v[4:7], v[158:161], v[218:221], v[4:7]
	v_mfma_f32_16x16x32_bf16 v[56:59], v[172:175], v[188:191], v[56:59]
	v_mfma_f32_16x16x32_bf16 v[48:51], v[180:183], v[188:191], v[48:51]
	v_mfma_f32_16x16x32_bf16 v[40:43], v[172:175], v[198:201], v[40:43]
	v_mfma_f32_16x16x32_bf16 v[32:35], v[180:183], v[198:201], v[32:35]
	v_mfma_f32_16x16x32_bf16 v[24:27], v[172:175], v[206:209], v[24:27]
	v_mfma_f32_16x16x32_bf16 v[16:19], v[180:183], v[206:209], v[16:19]
	v_mfma_f32_16x16x32_bf16 v[8:11], v[172:175], v[214:217], v[8:11]
	v_mfma_f32_16x16x32_bf16 v[0:3], v[180:183], v[214:217], v[0:3]
	v_mfma_f32_16x16x32_bf16 v[56:59], v[176:179], v[194:197], v[56:59]
	v_mfma_f32_16x16x32_bf16 v[48:51], v[184:187], v[194:197], v[48:51]
	v_mfma_f32_16x16x32_bf16 v[40:43], v[176:179], v[202:205], v[40:43]
	v_mfma_f32_16x16x32_bf16 v[32:35], v[184:187], v[202:205], v[32:35]
	v_mfma_f32_16x16x32_bf16 v[24:27], v[176:179], v[210:213], v[24:27]
	v_mfma_f32_16x16x32_bf16 v[16:19], v[184:187], v[210:213], v[16:19]
	v_mfma_f32_16x16x32_bf16 v[8:11], v[176:179], v[218:221], v[8:11]
	v_mfma_f32_16x16x32_bf16 v[0:3], v[184:187], v[218:221], v[0:3]
	s_setprio 0
	s_barrier
	s_add_i32 s72, 0, 0x18000
	s_add_i32 s73, 0, 0x1c000
	v_add_u32_e32 v158, s72, v165
	v_add_u32_e32 v184, s73, v165
	ds_read_b128 v[146:149], v158
	ds_read_b128 v[150:153], v158 offset:1024
	ds_read_b128 v[154:157], v158 offset:2048
	ds_read_b128 v[158:161], v158 offset:3072
	ds_read_b128 v[172:175], v184
	ds_read_b128 v[176:179], v184 offset:1024
	ds_read_b128 v[180:183], v184 offset:2048
	ds_read_b128 v[184:187], v184 offset:3072
	s_add_u32 s38, s38, s10
	s_addc_u32 s39, s39, s11
	s_mov_b32 m0, s56
	v_lshl_add_u64 v[232:233], s[38:39], 0, v[134:135]
	ds_read_b128 v[188:191], v169 offset:32768
	ds_read_b128 v[194:197], v169 offset:33792
	ds_read_b128 v[198:201], v169 offset:34816
	ds_read_b128 v[202:205], v169 offset:35840
	ds_read_b128 v[206:209], v169 offset:36864
	ds_read_b128 v[210:213], v169 offset:37888
	ds_read_b128 v[214:217], v169 offset:38912
	ds_read_b128 v[218:221], v169 offset:39936
	global_load_lds_dwordx4 v[232:233], off
	v_lshl_add_u64 v[232:233], s[38:39], 0, v[130:131]
	s_mov_b32 m0, s57
	s_nop 0
	global_load_lds_dwordx4 v[232:233], off
	s_waitcnt vmcnt(8)
	s_waitcnt lgkmcnt(0)
	s_barrier
	s_setprio 1
	v_mfma_f32_16x16x32_bf16 v[120:123], v[146:149], v[188:191], v[120:123]
	v_mfma_f32_16x16x32_bf16 v[116:119], v[154:157], v[188:191], v[116:119]
	v_mfma_f32_16x16x32_bf16 v[108:111], v[146:149], v[198:201], v[108:111]
	v_mfma_f32_16x16x32_bf16 v[100:103], v[154:157], v[198:201], v[100:103]
	v_mfma_f32_16x16x32_bf16 v[92:95], v[146:149], v[206:209], v[92:95]
	v_mfma_f32_16x16x32_bf16 v[84:87], v[154:157], v[206:209], v[84:87]
	v_mfma_f32_16x16x32_bf16 v[76:79], v[146:149], v[214:217], v[76:79]
	v_mfma_f32_16x16x32_bf16 v[68:71], v[154:157], v[214:217], v[68:71]
	v_mfma_f32_16x16x32_bf16 v[120:123], v[150:153], v[194:197], v[120:123]
	v_mfma_f32_16x16x32_bf16 v[116:119], v[158:161], v[194:197], v[116:119]
	v_mfma_f32_16x16x32_bf16 v[108:111], v[150:153], v[202:205], v[108:111]
	v_mfma_f32_16x16x32_bf16 v[100:103], v[158:161], v[202:205], v[100:103]
	v_mfma_f32_16x16x32_bf16 v[92:95], v[150:153], v[210:213], v[92:95]
	v_mfma_f32_16x16x32_bf16 v[84:87], v[158:161], v[210:213], v[84:87]
	v_mfma_f32_16x16x32_bf16 v[76:79], v[150:153], v[218:221], v[76:79]
	v_mfma_f32_16x16x32_bf16 v[68:71], v[158:161], v[218:221], v[68:71]
	v_mfma_f32_16x16x32_bf16 v[124:127], v[172:175], v[188:191], v[124:127]
	v_mfma_f32_16x16x32_bf16 v[112:115], v[180:183], v[188:191], v[112:115]
	v_mfma_f32_16x16x32_bf16 v[104:107], v[172:175], v[198:201], v[104:107]
	v_mfma_f32_16x16x32_bf16 v[96:99], v[180:183], v[198:201], v[96:99]
	v_mfma_f32_16x16x32_bf16 v[88:91], v[172:175], v[206:209], v[88:91]
	v_mfma_f32_16x16x32_bf16 v[80:83], v[180:183], v[206:209], v[80:83]
	v_mfma_f32_16x16x32_bf16 v[72:75], v[172:175], v[214:217], v[72:75]
	v_mfma_f32_16x16x32_bf16 v[64:67], v[180:183], v[214:217], v[64:67]
	v_mfma_f32_16x16x32_bf16 v[124:127], v[176:179], v[194:197], v[124:127]
	v_mfma_f32_16x16x32_bf16 v[112:115], v[184:187], v[194:197], v[112:115]
	v_mfma_f32_16x16x32_bf16 v[104:107], v[176:179], v[202:205], v[104:107]
	v_mfma_f32_16x16x32_bf16 v[96:99], v[184:187], v[202:205], v[96:99]
	v_mfma_f32_16x16x32_bf16 v[88:91], v[176:179], v[210:213], v[88:91]
	v_mfma_f32_16x16x32_bf16 v[80:83], v[184:187], v[210:213], v[80:83]
	v_mfma_f32_16x16x32_bf16 v[72:75], v[176:179], v[218:221], v[72:75]
	v_mfma_f32_16x16x32_bf16 v[64:67], v[184:187], v[218:221], v[64:67]
	s_setprio 0
	s_barrier
; #define PG8_STAGE(bufoff, gbase, voff) do { _Pragma("unroll") for (int _i = 0; _i < 2; ++_i) \
;         __builtin_amdgcn_global_load_lds((const unsigned*)((const char*)(gbase) + (voff)[_i]), (PG8_LAS unsigned*)(lds + (bufoff) + ldsw + _i * 8192), 16, 0, 0); } while (0)
; #define PG8_LDA(dst, b, h) do { _Pragma("unroll") for (int m = 0; m < 4; ++m) _Pragma("unroll") for (int k = 0; k < 2; ++k) dst[m][k] = *(const PG8_LAS bf16x8*)(lds + PG8_SA(b, h) + aoff + m * 2048 + k * 1024); } while (0)
; #define PG8_MMA(ai, bj, At, Bt) do { __builtin_amdgcn_s_setprio(1); _Pragma("unroll") for (int m = 0; m < 4; ++m) _Pragma("unroll") for (int n = 0; n < 2; ++n) _Pragma("unroll") for (int k = 0; k < 2; ++k) \
;         acc[ai][bj][m][n] = __builtin_amdgcn_mfma_f32_16x16x32_bf16(Bt[n][k], At[m][k], acc[ai][bj][m][n], 0, 0, 0); __builtin_amdgcn_s_setprio(0); } while (0)
; #define PG8_WAIT_V(n) asm volatile("s_waitcnt vmcnt(" #n ")" ::: "memory")
; #define PG8_WAIT_L(n) asm volatile("s_waitcnt lgkmcnt(" #n ")" ::: "memory")
; #define PG8_BAR __builtin_amdgcn_s_barrier()
; #define PG8_SCHED __builtin_amdgcn_sched_barrier(0)
; template <class Epi, class Sched, bool ALIGN_EPI = false, bool SP2 = false>
; __device__ __forceinline__ void gemm_phase(PG8_LAS unsigned char* lds, const Gemm g, const Sched& S, const Epi& E) {
;     ...
;             PG8_LDA(At, 1, 1); PG8_STAGE(PG8_SB(1, 0), b3, voffB); PG8_STAGE(PG8_SB(1, 1), b3 + hstep, voffB); PG8_STAGE(PG8_SA(1, 0), a3, voffA);
;             PG8_WAIT_V(8); PG8_WAIT_L(0); PG8_BAR; PG8_MMA(1, 0, At, B0); PG8_MMA(1, 1, At, B1); PG8_BAR; PG8_SCHED;
	s_add_i32 s38, s72, s41
	v_lshl_add_u64 v[162:163], v[162:163], 0, s[16:17]
	s_mov_b32 m0, s38
	ds_read_b128 v[188:191], v169 offset:49152
	ds_read_b128 v[194:197], v169 offset:50176
	ds_read_b128 v[198:201], v169 offset:51200
	ds_read_b128 v[202:205], v169 offset:52224
	ds_read_b128 v[206:209], v169 offset:53248
	ds_read_b128 v[210:213], v169 offset:54272
	ds_read_b128 v[214:217], v169 offset:55296
	ds_read_b128 v[218:221], v169 offset:56320
	global_load_lds_dwordx4 v[162:163], off
	v_lshl_add_u64 v[162:163], v[222:223], 0, s[16:17]
	s_add_i32 m0, s38, 0x2000
	s_add_i32 s38, s73, s41
	global_load_lds_dwordx4 v[162:163], off
	v_lshl_add_u64 v[162:163], v[224:225], 0, s[16:17]
	s_mov_b32 m0, s38
	s_nop 0
	global_load_lds_dwordx4 v[162:163], off
	v_lshl_add_u64 v[162:163], v[226:227], 0, s[16:17]
	s_add_i32 m0, s38, 0x2000
	s_nop 0
	global_load_lds_dwordx4 v[162:163], off
	v_lshl_add_u64 v[162:163], v[228:229], 0, s[16:17]
	s_mov_b32 m0, s59
	s_nop 0
	global_load_lds_dwordx4 v[162:163], off
	v_lshl_add_u64 v[162:163], v[230:231], 0, s[16:17]
	s_mov_b32 m0, s60
	s_nop 0
	global_load_lds_dwordx4 v[162:163], off
	s_waitcnt vmcnt(8)
	s_waitcnt lgkmcnt(0)
	s_barrier
	s_setprio 1
	v_mfma_f32_16x16x32_bf16 v[60:63], v[146:149], v[188:191], v[60:63]
	v_mfma_f32_16x16x32_bf16 v[52:55], v[154:157], v[188:191], v[52:55]
	v_mfma_f32_16x16x32_bf16 v[44:47], v[146:149], v[198:201], v[44:47]
	v_mfma_f32_16x16x32_bf16 v[36:39], v[154:157], v[198:201], v[36:39]
	v_mfma_f32_16x16x32_bf16 v[28:31], v[146:149], v[206:209], v[28:31]
	v_mfma_f32_16x16x32_bf16 v[20:23], v[154:157], v[206:209], v[20:23]
	v_mfma_f32_16x16x32_bf16 v[12:15], v[146:149], v[214:217], v[12:15]
	v_mfma_f32_16x16x32_bf16 v[4:7], v[154:157], v[214:217], v[4:7]
	v_mfma_f32_16x16x32_bf16 v[60:63], v[150:153], v[194:197], v[60:63]
	v_mfma_f32_16x16x32_bf16 v[52:55], v[158:161], v[194:197], v[52:55]
	v_mfma_f32_16x16x32_bf16 v[44:47], v[150:153], v[202:205], v[44:47]
	v_mfma_f32_16x16x32_bf16 v[36:39], v[158:161], v[202:205], v[36:39]
	v_mfma_f32_16x16x32_bf16 v[28:31], v[150:153], v[210:213], v[28:31]
	v_mfma_f32_16x16x32_bf16 v[20:23], v[158:161], v[210:213], v[20:23]
	v_mfma_f32_16x16x32_bf16 v[12:15], v[150:153], v[218:221], v[12:15]
	v_mfma_f32_16x16x32_bf16 v[4:7], v[158:161], v[218:221], v[4:7]
	v_mfma_f32_16x16x32_bf16 v[56:59], v[172:175], v[188:191], v[56:59]
	v_mfma_f32_16x16x32_bf16 v[48:51], v[180:183], v[188:191], v[48:51]
	v_mfma_f32_16x16x32_bf16 v[40:43], v[172:175], v[198:201], v[40:43]
	v_mfma_f32_16x16x32_bf16 v[32:35], v[180:183], v[198:201], v[32:35]
	v_mfma_f32_16x16x32_bf16 v[24:27], v[172:175], v[206:209], v[24:27]
	v_mfma_f32_16x16x32_bf16 v[16:19], v[180:183], v[206:209], v[16:19]
	v_mfma_f32_16x16x32_bf16 v[8:11], v[172:175], v[214:217], v[8:11]
	v_mfma_f32_16x16x32_bf16 v[0:3], v[180:183], v[214:217], v[0:3]
	v_mfma_f32_16x16x32_bf16 v[56:59], v[176:179], v[194:197], v[56:59]
	v_mfma_f32_16x16x32_bf16 v[48:51], v[184:187], v[194:197], v[48:51]
	v_mfma_f32_16x16x32_bf16 v[40:43], v[176:179], v[202:205], v[40:43]
	v_mfma_f32_16x16x32_bf16 v[32:35], v[184:187], v[202:205], v[32:35]
	v_mfma_f32_16x16x32_bf16 v[24:27], v[176:179], v[210:213], v[24:27]
	v_mfma_f32_16x16x32_bf16 v[16:19], v[184:187], v[210:213], v[16:19]
	v_mfma_f32_16x16x32_bf16 v[8:11], v[176:179], v[218:221], v[8:11]
	v_mfma_f32_16x16x32_bf16 v[0:3], v[184:187], v[218:221], v[0:3]
	s_setprio 0
	s_barrier
	s_add_u32 s36, s36, 0x100
	s_addc_u32 s37, s37, 0
	s_add_u32 s33, s33, 0x100
	s_addc_u32 s70, s70, 0
	s_cmp_ge_i32 s71, s61
	s_mov_b32 s38, s71
	s_cbranch_scc0 .LBB0_1014

; #define PG8_STAGE(bufoff, gbase, voff) do { _Pragma("unroll") for (int _i = 0; _i < 2; ++_i) \
;         __builtin_amdgcn_global_load_lds((const unsigned*)((const char*)(gbase) + (voff)[_i]), (PG8_LAS unsigned*)(lds + (bufoff) + ldsw + _i * 8192), 16, 0, 0); } while (0)
; #define PG8_LDA(dst, b, h) do { _Pragma("unroll") for (int m = 0; m < 4; ++m) _Pragma("unroll") for (int k = 0; k < 2; ++k) dst[m][k] = *(const PG8_LAS bf16x8*)(lds + PG8_SA(b, h) + aoff + m * 2048 + k * 1024); } while (0)
; #define PG8_LDB(dst, b, h) do { _Pragma("unroll") for (int n = 0; n < 2; ++n) _Pragma("unroll") for (int k = 0; k < 2; ++k) dst[n][k] = *(const PG8_LAS bf16x8*)(lds + PG8_SB(b, h) + boff + n * 2048 + k * 1024); } while (0)
; #define PG8_MMA(ai, bj, At, Bt) do { __builtin_amdgcn_s_setprio(1); _Pragma("unroll") for (int m = 0; m < 4; ++m) _Pragma("unroll") for (int n = 0; n < 2; ++n) _Pragma("unroll") for (int k = 0; k < 2; ++k) \
;         acc[ai][bj][m][n] = __builtin_amdgcn_mfma_f32_16x16x32_bf16(Bt[n][k], At[m][k], acc[ai][bj][m][n], 0, 0, 0); __builtin_amdgcn_s_setprio(0); } while (0)
; #define PG8_WAIT_V(n) asm volatile("s_waitcnt vmcnt(" #n ")" ::: "memory")
; #define PG8_BAR __builtin_amdgcn_s_barrier()
; template <class Epi, class Sched, bool ALIGN_EPI = false, bool SP2 = false>
; __device__ __forceinline__ void gemm_phase(PG8_LAS unsigned char* lds, const Gemm g, const Sched& S, const Epi& E) {
;     ...
;         for (int t = 0; t < nt; t += 2) {
;             const bool last = (t == nt - 2);
;             const char* a1 = cA + (size_t)(t + 1) * kstep;
;             const char* a2 = last ? nA : cA + (size_t)(t + 2) * kstep; const char* b2 = last ? nB : cB + (size_t)(t + 2) * kstep;
;             const char* a3 = a2 + kstep; const char* b3 = b2 + kstep;
;             if (last && has_next) S.a_ready(nxt);
;             if constexpr (SP2) {
;             PG8_LDB(B0, 0, 0); PG8_LDB(B1, 0, 1); PG8_SCHED; PG8_LDA(At, 0, 0); PG8_STAGE(PG8_SA(1, 1), a1 + hstep, voffA);
;             PG8_WAIT_V(8); PG8_WAIT_L(0); PG8_BAR; PG8_MMA(0, 0, At, B0); PG8_MMA(0, 1, At, B1); PG8_BAR; PG8_SCHED;
;             PG8_LDA(At, 0, 1); PG8_STAGE(PG8_SB(0, 0), b2, voffB); PG8_STAGE(PG8_SB(0, 1), b2 + hstep, voffB); PG8_STAGE(PG8_SA(0, 0), a2, voffA);
;             PG8_WAIT_V(8); PG8_WAIT_L(0); PG8_BAR; PG8_MMA(1, 0, At, B0); PG8_MMA(1, 1, At, B1); PG8_BAR; PG8_SCHED;
.LBB0_1034:
	ds_read_b128 v[150:153], v143
	ds_read_b128 v[154:157], v143 offset:1024
	ds_read_b128 v[158:161], v143 offset:2048
	ds_read_b128 v[162:165], v143 offset:3072
	ds_read_b128 v[166:169], v144
	ds_read_b128 v[170:173], v144 offset:1024
	ds_read_b128 v[174:177], v144 offset:2048
	ds_read_b128 v[178:181], v144 offset:3072
	s_add_i32 s86, s56, 2
	s_add_u32 s87, s54, 0x80
	s_addc_u32 s57, s55, 0
	s_cmp_eq_u32 s69, s56
	s_cselect_b32 s56, s40, s87
	s_cselect_b32 s57, s41, s57
	s_cselect_b32 s89, s43, s85
	s_cselect_b32 s88, s42, s33
	s_mov_b32 m0, s70
	v_lshl_add_u64 v[190:191], s[54:55], 0, v[138:139]
	ds_read_b128 v[182:185], v145
	ds_read_b128 v[186:189], v145 offset:1024
	ds_read_b128 v[194:197], v145 offset:2048
	ds_read_b128 v[198:201], v145 offset:3072
	ds_read_b128 v[202:205], v145 offset:4096
	ds_read_b128 v[206:209], v145 offset:5120
	ds_read_b128 v[210:213], v145 offset:6144
	ds_read_b128 v[214:217], v145 offset:7168
	global_load_lds_dwordx4 v[190:191], off
	v_lshl_add_u64 v[190:191], s[54:55], 0, v[140:141]
	s_mov_b32 m0, s71
	s_nop 0
	global_load_lds_dwordx4 v[190:191], off
	s_waitcnt vmcnt(8)
	s_waitcnt lgkmcnt(0)
	s_barrier
	s_setprio 1
	v_mfma_f32_16x16x32_bf16 v[124:127], v[150:153], v[182:185], v[124:127]
	v_mfma_f32_16x16x32_bf16 v[120:123], v[158:161], v[182:185], v[120:123]
	v_mfma_f32_16x16x32_bf16 v[108:111], v[150:153], v[194:197], v[108:111]
	v_mfma_f32_16x16x32_bf16 v[104:107], v[158:161], v[194:197], v[104:107]
	v_mfma_f32_16x16x32_bf16 v[92:95], v[150:153], v[202:205], v[92:95]
	v_mfma_f32_16x16x32_bf16 v[88:91], v[158:161], v[202:205], v[88:91]
	v_mfma_f32_16x16x32_bf16 v[76:79], v[150:153], v[210:213], v[76:79]
	v_mfma_f32_16x16x32_bf16 v[72:75], v[158:161], v[210:213], v[72:75]
	v_mfma_f32_16x16x32_bf16 v[124:127], v[154:157], v[186:189], v[124:127]
	v_mfma_f32_16x16x32_bf16 v[120:123], v[162:165], v[186:189], v[120:123]
	v_mfma_f32_16x16x32_bf16 v[108:111], v[154:157], v[198:201], v[108:111]
	v_mfma_f32_16x16x32_bf16 v[104:107], v[162:165], v[198:201], v[104:107]
	v_mfma_f32_16x16x32_bf16 v[92:95], v[154:157], v[206:209], v[92:95]
	v_mfma_f32_16x16x32_bf16 v[88:91], v[162:165], v[206:209], v[88:91]
	v_mfma_f32_16x16x32_bf16 v[76:79], v[154:157], v[214:217], v[76:79]
	v_mfma_f32_16x16x32_bf16 v[72:75], v[162:165], v[214:217], v[72:75]
	v_mfma_f32_16x16x32_bf16 v[116:119], v[166:169], v[182:185], v[116:119]
	v_mfma_f32_16x16x32_bf16 v[112:115], v[174:177], v[182:185], v[112:115]
	v_mfma_f32_16x16x32_bf16 v[100:103], v[166:169], v[194:197], v[100:103]
	v_mfma_f32_16x16x32_bf16 v[96:99], v[174:177], v[194:197], v[96:99]
	v_mfma_f32_16x16x32_bf16 v[84:87], v[166:169], v[202:205], v[84:87]
	v_mfma_f32_16x16x32_bf16 v[80:83], v[174:177], v[202:205], v[80:83]
	v_mfma_f32_16x16x32_bf16 v[68:71], v[166:169], v[210:213], v[68:71]
	v_mfma_f32_16x16x32_bf16 v[64:67], v[174:177], v[210:213], v[64:67]
	v_mfma_f32_16x16x32_bf16 v[116:119], v[170:173], v[186:189], v[116:119]
	v_mfma_f32_16x16x32_bf16 v[112:115], v[178:181], v[186:189], v[112:115]
	v_mfma_f32_16x16x32_bf16 v[100:103], v[170:173], v[198:201], v[100:103]
	v_mfma_f32_16x16x32_bf16 v[96:99], v[178:181], v[198:201], v[96:99]
	v_mfma_f32_16x16x32_bf16 v[84:87], v[170:173], v[206:209], v[84:87]
	v_mfma_f32_16x16x32_bf16 v[80:83], v[178:181], v[206:209], v[80:83]
	v_mfma_f32_16x16x32_bf16 v[68:71], v[170:173], v[214:217], v[68:71]
	v_mfma_f32_16x16x32_bf16 v[64:67], v[178:181], v[214:217], v[64:67]
	s_setprio 0
	s_barrier
	s_mov_b32 m0, s72
	v_lshl_add_u64 v[190:191], s[88:89], 0, v[132:133]
	v_lshl_add_u64 v[218:219], s[88:89], 0, v[128:129]
	s_add_u32 s88, s88, s10
	ds_read_b128 v[182:185], v145 offset:16384
	ds_read_b128 v[186:189], v145 offset:17408
	ds_read_b128 v[194:197], v145 offset:18432
	ds_read_b128 v[198:201], v145 offset:19456
	ds_read_b128 v[202:205], v145 offset:20480
	ds_read_b128 v[206:209], v145 offset:21504
	ds_read_b128 v[210:213], v145 offset:22528
	ds_read_b128 v[214:217], v145 offset:23552
	global_load_lds_dwordx4 v[190:191], off
	s_mov_b32 m0, s73
	s_addc_u32 s89, s89, s11
	global_load_lds_dwordx4 v[218:219], off
	v_lshl_add_u64 v[220:221], s[88:89], 0, v[132:133]
	s_mov_b32 m0, s74
	v_lshl_add_u64 v[222:223], s[88:89], 0, v[128:129]
	global_load_lds_dwordx4 v[220:221], off
	s_mov_b32 m0, s75
	v_lshl_add_u64 v[224:225], s[56:57], 0, v[134:135]
	global_load_lds_dwordx4 v[222:223], off
	s_mov_b32 m0, s4
	v_lshl_add_u64 v[226:227], s[56:57], 0, v[130:131]
	global_load_lds_dwordx4 v[224:225], off
	s_mov_b32 m0, s5
	s_nop 0
	global_load_lds_dwordx4 v[226:227], off
	s_waitcnt vmcnt(8)
	s_waitcnt lgkmcnt(0)
	s_barrier
; #define PG8_STAGE(bufoff, gbase, voff) do { _Pragma("unroll") for (int _i = 0; _i < 2; ++_i) \
;         __builtin_amdgcn_global_load_lds((const unsigned*)((const char*)(gbase) + (voff)[_i]), (PG8_LAS unsigned*)(lds + (bufoff) + ldsw + _i * 8192), 16, 0, 0); } while (0)
; #define PG8_LDA(dst, b, h) do { _Pragma("unroll") for (int m = 0; m < 4; ++m) _Pragma("unroll") for (int k = 0; k < 2; ++k) dst[m][k] = *(const PG8_LAS bf16x8*)(lds + PG8_SA(b, h) + aoff + m * 2048 + k * 1024); } while (0)
; #define PG8_LDB(dst, b, h) do { _Pragma("unroll") for (int n = 0; n < 2; ++n) _Pragma("unroll") for (int k = 0; k < 2; ++k) dst[n][k] = *(const PG8_LAS bf16x8*)(lds + PG8_SB(b, h) + boff + n * 2048 + k * 1024); } while (0)
; #define PG8_MMA(ai, bj, At, Bt) do { __builtin_amdgcn_s_setprio(1); _Pragma("unroll") for (int m = 0; m < 4; ++m) _Pragma("unroll") for (int n = 0; n < 2; ++n) _Pragma("unroll") for (int k = 0; k < 2; ++k) \
;         acc[ai][bj][m][n] = __builtin_amdgcn_mfma_f32_16x16x32_bf16(Bt[n][k], At[m][k], acc[ai][bj][m][n], 0, 0, 0); __builtin_amdgcn_s_setprio(0); } while (0)
; #define PG8_WAIT_V(n) asm volatile("s_waitcnt vmcnt(" #n ")" ::: "memory")
; #define PG8_WAIT_L(n) asm volatile("s_waitcnt lgkmcnt(" #n ")" ::: "memory")
; #define PG8_BAR __builtin_amdgcn_s_barrier()
; #define PG8_SCHED __builtin_amdgcn_sched_barrier(0)
; template <class Epi, class Sched, bool ALIGN_EPI = false, bool SP2 = false>
; __device__ __forceinline__ void gemm_phase(PG8_LAS unsigned char* lds, const Gemm g, const Sched& S, const Epi& E) {
;     ...
;             PG8_WAIT_V(8); PG8_WAIT_L(0); PG8_BAR; PG8_MMA(1, 0, At, B0); PG8_MMA(1, 1, At, B1); PG8_BAR; PG8_SCHED;
;             PG8_LDB(B0, 1, 0); PG8_LDB(B1, 1, 1); PG8_SCHED; PG8_LDA(At, 1, 0); PG8_STAGE(PG8_SA(0, 1), a2 + hstep, voffA);
;             PG8_WAIT_V(8); PG8_WAIT_L(0); PG8_BAR; PG8_MMA(0, 0, At, B0); PG8_MMA(0, 1, At, B1); PG8_BAR; PG8_SCHED;
	s_setprio 1
	v_mfma_f32_16x16x32_bf16 v[60:63], v[150:153], v[182:185], v[60:63]
	v_mfma_f32_16x16x32_bf16 v[56:59], v[158:161], v[182:185], v[56:59]
	v_mfma_f32_16x16x32_bf16 v[44:47], v[150:153], v[194:197], v[44:47]
	v_mfma_f32_16x16x32_bf16 v[40:43], v[158:161], v[194:197], v[40:43]
	v_mfma_f32_16x16x32_bf16 v[28:31], v[150:153], v[202:205], v[28:31]
	v_mfma_f32_16x16x32_bf16 v[24:27], v[158:161], v[202:205], v[24:27]
	v_mfma_f32_16x16x32_bf16 v[12:15], v[150:153], v[210:213], v[12:15]
	v_mfma_f32_16x16x32_bf16 v[8:11], v[158:161], v[210:213], v[8:11]
	v_mfma_f32_16x16x32_bf16 v[60:63], v[154:157], v[186:189], v[60:63]
	v_mfma_f32_16x16x32_bf16 v[56:59], v[162:165], v[186:189], v[56:59]
	v_mfma_f32_16x16x32_bf16 v[44:47], v[154:157], v[198:201], v[44:47]
	v_mfma_f32_16x16x32_bf16 v[40:43], v[162:165], v[198:201], v[40:43]
	v_mfma_f32_16x16x32_bf16 v[28:31], v[154:157], v[206:209], v[28:31]
	v_mfma_f32_16x16x32_bf16 v[24:27], v[162:165], v[206:209], v[24:27]
	v_mfma_f32_16x16x32_bf16 v[12:15], v[154:157], v[214:217], v[12:15]
	v_mfma_f32_16x16x32_bf16 v[8:11], v[162:165], v[214:217], v[8:11]
	v_mfma_f32_16x16x32_bf16 v[52:55], v[166:169], v[182:185], v[52:55]
	v_mfma_f32_16x16x32_bf16 v[48:51], v[174:177], v[182:185], v[48:51]
	v_mfma_f32_16x16x32_bf16 v[36:39], v[166:169], v[194:197], v[36:39]
	v_mfma_f32_16x16x32_bf16 v[32:35], v[174:177], v[194:197], v[32:35]
	v_mfma_f32_16x16x32_bf16 v[20:23], v[166:169], v[202:205], v[20:23]
	v_mfma_f32_16x16x32_bf16 v[16:19], v[174:177], v[202:205], v[16:19]
	v_mfma_f32_16x16x32_bf16 v[4:7], v[166:169], v[210:213], v[4:7]
	v_mfma_f32_16x16x32_bf16 v[0:3], v[174:177], v[210:213], v[0:3]
	v_mfma_f32_16x16x32_bf16 v[52:55], v[170:173], v[186:189], v[52:55]
	v_mfma_f32_16x16x32_bf16 v[48:51], v[178:181], v[186:189], v[48:51]
	v_mfma_f32_16x16x32_bf16 v[36:39], v[170:173], v[198:201], v[36:39]
	v_mfma_f32_16x16x32_bf16 v[32:35], v[178:181], v[198:201], v[32:35]
	v_mfma_f32_16x16x32_bf16 v[20:23], v[170:173], v[206:209], v[20:23]
	v_mfma_f32_16x16x32_bf16 v[16:19], v[178:181], v[206:209], v[16:19]
	v_mfma_f32_16x16x32_bf16 v[4:7], v[170:173], v[214:217], v[4:7]
	v_mfma_f32_16x16x32_bf16 v[0:3], v[178:181], v[214:217], v[0:3]
	s_setprio 0
	s_barrier
	ds_read_b128 v[150:153], v146
	ds_read_b128 v[154:157], v146 offset:1024
	ds_read_b128 v[158:161], v146 offset:2048
	ds_read_b128 v[162:165], v146 offset:3072
	ds_read_b128 v[166:169], v147
	ds_read_b128 v[170:173], v147 offset:1024
	ds_read_b128 v[174:177], v147 offset:2048
	ds_read_b128 v[178:181], v147 offset:3072
	s_add_u32 s56, s56, s10
	s_addc_u32 s57, s57, s11
	s_mov_b32 m0, s60
	v_lshl_add_u64 v[228:229], s[56:57], 0, v[134:135]
	ds_read_b128 v[182:185], v145 offset:32768
	ds_read_b128 v[186:189], v145 offset:33792
	ds_read_b128 v[194:197], v145 offset:34816
	ds_read_b128 v[198:201], v145 offset:35840
	ds_read_b128 v[202:205], v145 offset:36864
	ds_read_b128 v[206:209], v145 offset:37888
	ds_read_b128 v[210:213], v145 offset:38912
	ds_read_b128 v[214:217], v145 offset:39936
	global_load_lds_dwordx4 v[228:229], off
	v_lshl_add_u64 v[228:229], s[56:57], 0, v[130:131]
	s_mov_b32 m0, s61
	s_nop 0
	global_load_lds_dwordx4 v[228:229], off
	s_waitcnt vmcnt(8)
	s_waitcnt lgkmcnt(0)
	s_barrier
	s_setprio 1
	v_mfma_f32_16x16x32_bf16 v[124:127], v[150:153], v[182:185], v[124:127]
	v_mfma_f32_16x16x32_bf16 v[120:123], v[158:161], v[182:185], v[120:123]
	v_mfma_f32_16x16x32_bf16 v[108:111], v[150:153], v[194:197], v[108:111]
	v_mfma_f32_16x16x32_bf16 v[104:107], v[158:161], v[194:197], v[104:107]
	v_mfma_f32_16x16x32_bf16 v[92:95], v[150:153], v[202:205], v[92:95]
	v_mfma_f32_16x16x32_bf16 v[88:91], v[158:161], v[202:205], v[88:91]
	v_mfma_f32_16x16x32_bf16 v[76:79], v[150:153], v[210:213], v[76:79]
	v_mfma_f32_16x16x32_bf16 v[72:75], v[158:161], v[210:213], v[72:75]
	v_mfma_f32_16x16x32_bf16 v[124:127], v[154:157], v[186:189], v[124:127]
	v_mfma_f32_16x16x32_bf16 v[120:123], v[162:165], v[186:189], v[120:123]
	v_mfma_f32_16x16x32_bf16 v[108:111], v[154:157], v[198:201], v[108:111]
	v_mfma_f32_16x16x32_bf16 v[104:107], v[162:165], v[198:201], v[104:107]
	v_mfma_f32_16x16x32_bf16 v[92:95], v[154:157], v[206:209], v[92:95]
	v_mfma_f32_16x16x32_bf16 v[88:91], v[162:165], v[206:209], v[88:91]
	v_mfma_f32_16x16x32_bf16 v[76:79], v[154:157], v[214:217], v[76:79]
	v_mfma_f32_16x16x32_bf16 v[72:75], v[162:165], v[214:217], v[72:75]
	v_mfma_f32_16x16x32_bf16 v[116:119], v[166:169], v[182:185], v[116:119]
	v_mfma_f32_16x16x32_bf16 v[112:115], v[174:177], v[182:185], v[112:115]
	v_mfma_f32_16x16x32_bf16 v[100:103], v[166:169], v[194:197], v[100:103]
	v_mfma_f32_16x16x32_bf16 v[96:99], v[174:177], v[194:197], v[96:99]
	v_mfma_f32_16x16x32_bf16 v[84:87], v[166:169], v[202:205], v[84:87]
	v_mfma_f32_16x16x32_bf16 v[80:83], v[174:177], v[202:205], v[80:83]
	v_mfma_f32_16x16x32_bf16 v[68:71], v[166:169], v[210:213], v[68:71]
	v_mfma_f32_16x16x32_bf16 v[64:67], v[174:177], v[210:213], v[64:67]
	v_mfma_f32_16x16x32_bf16 v[116:119], v[170:173], v[186:189], v[116:119]
	v_mfma_f32_16x16x32_bf16 v[112:115], v[178:181], v[186:189], v[112:115]
	v_mfma_f32_16x16x32_bf16 v[100:103], v[170:173], v[198:201], v[100:103]
	v_mfma_f32_16x16x32_bf16 v[96:99], v[178:181], v[198:201], v[96:99]
	v_mfma_f32_16x16x32_bf16 v[84:87], v[170:173], v[206:209], v[84:87]
	v_mfma_f32_16x16x32_bf16 v[80:83], v[178:181], v[206:209], v[80:83]
	v_mfma_f32_16x16x32_bf16 v[68:71], v[170:173], v[214:217], v[68:71]
	v_mfma_f32_16x16x32_bf16 v[64:67], v[178:181], v[214:217], v[64:67]
	s_setprio 0
	s_barrier
; #define PG8_STAGE(bufoff, gbase, voff) do { _Pragma("unroll") for (int _i = 0; _i < 2; ++_i) \
;         __builtin_amdgcn_global_load_lds((const unsigned*)((const char*)(gbase) + (voff)[_i]), (PG8_LAS unsigned*)(lds + (bufoff) + ldsw + _i * 8192), 16, 0, 0); } while (0)
; #define PG8_LDA(dst, b, h) do { _Pragma("unroll") for (int m = 0; m < 4; ++m) _Pragma("unroll") for (int k = 0; k < 2; ++k) dst[m][k] = *(const PG8_LAS bf16x8*)(lds + PG8_SA(b, h) + aoff + m * 2048 + k * 1024); } while (0)
; #define PG8_MMA(ai, bj, At, Bt) do { __builtin_amdgcn_s_setprio(1); _Pragma("unroll") for (int m = 0; m < 4; ++m) _Pragma("unroll") for (int n = 0; n < 2; ++n) _Pragma("unroll") for (int k = 0; k < 2; ++k) \
;         acc[ai][bj][m][n] = __builtin_amdgcn_mfma_f32_16x16x32_bf16(Bt[n][k], At[m][k], acc[ai][bj][m][n], 0, 0, 0); __builtin_amdgcn_s_setprio(0); } while (0)
; #define PG8_WAIT_V(n) asm volatile("s_waitcnt vmcnt(" #n ")" ::: "memory")
; #define PG8_WAIT_L(n) asm volatile("s_waitcnt lgkmcnt(" #n ")" ::: "memory")
; #define PG8_BAR __builtin_amdgcn_s_barrier()
; #define PG8_SCHED __builtin_amdgcn_sched_barrier(0)
; template <class Epi, class Sched, bool ALIGN_EPI = false, bool SP2 = false>
; __device__ __forceinline__ void gemm_phase(PG8_LAS unsigned char* lds, const Gemm g, const Sched& S, const Epi& E) {
;     ...
;             PG8_LDA(At, 1, 1); PG8_STAGE(PG8_SB(1, 0), b3, voffB); PG8_STAGE(PG8_SB(1, 1), b3 + hstep, voffB); PG8_STAGE(PG8_SA(1, 0), a3, voffA);
;             PG8_WAIT_V(8); PG8_WAIT_L(0); PG8_BAR; PG8_MMA(1, 0, At, B0); PG8_MMA(1, 1, At, B1); PG8_BAR; PG8_SCHED;
	s_mov_b32 m0, s79
	v_lshl_add_u64 v[190:191], v[190:191], 0, s[16:17]
	ds_read_b128 v[182:185], v145 offset:49152
	ds_read_b128 v[186:189], v145 offset:50176
	ds_read_b128 v[194:197], v145 offset:51200
	ds_read_b128 v[198:201], v145 offset:52224
	ds_read_b128 v[202:205], v145 offset:53248
	ds_read_b128 v[206:209], v145 offset:54272
	ds_read_b128 v[210:213], v145 offset:55296
	ds_read_b128 v[214:217], v145 offset:56320
	global_load_lds_dwordx4 v[190:191], off
	v_lshl_add_u64 v[190:191], v[218:219], 0, s[16:17]
	s_mov_b32 m0, s80
	s_nop 0
	global_load_lds_dwordx4 v[190:191], off
	v_lshl_add_u64 v[190:191], v[220:221], 0, s[16:17]
	s_mov_b32 m0, s81
	s_nop 0
	global_load_lds_dwordx4 v[190:191], off
	v_lshl_add_u64 v[190:191], v[222:223], 0, s[16:17]
	s_mov_b32 m0, s82
	s_nop 0
	global_load_lds_dwordx4 v[190:191], off
	v_lshl_add_u64 v[190:191], v[224:225], 0, s[16:17]
	s_mov_b32 m0, s64
	s_nop 0
	global_load_lds_dwordx4 v[190:191], off
	v_lshl_add_u64 v[190:191], v[226:227], 0, s[16:17]
	s_mov_b32 m0, s65
	s_nop 0
	global_load_lds_dwordx4 v[190:191], off
	s_waitcnt vmcnt(8)
	s_waitcnt lgkmcnt(0)
	s_barrier
	s_setprio 1
	v_mfma_f32_16x16x32_bf16 v[60:63], v[150:153], v[182:185], v[60:63]
	v_mfma_f32_16x16x32_bf16 v[56:59], v[158:161], v[182:185], v[56:59]
	v_mfma_f32_16x16x32_bf16 v[44:47], v[150:153], v[194:197], v[44:47]
	v_mfma_f32_16x16x32_bf16 v[40:43], v[158:161], v[194:197], v[40:43]
	v_mfma_f32_16x16x32_bf16 v[28:31], v[150:153], v[202:205], v[28:31]
	v_mfma_f32_16x16x32_bf16 v[24:27], v[158:161], v[202:205], v[24:27]
	v_mfma_f32_16x16x32_bf16 v[12:15], v[150:153], v[210:213], v[12:15]
	v_mfma_f32_16x16x32_bf16 v[8:11], v[158:161], v[210:213], v[8:11]
	v_mfma_f32_16x16x32_bf16 v[60:63], v[154:157], v[186:189], v[60:63]
	v_mfma_f32_16x16x32_bf16 v[56:59], v[162:165], v[186:189], v[56:59]
	v_mfma_f32_16x16x32_bf16 v[44:47], v[154:157], v[198:201], v[44:47]
	v_mfma_f32_16x16x32_bf16 v[40:43], v[162:165], v[198:201], v[40:43]
	v_mfma_f32_16x16x32_bf16 v[28:31], v[154:157], v[206:209], v[28:31]
	v_mfma_f32_16x16x32_bf16 v[24:27], v[162:165], v[206:209], v[24:27]
	v_mfma_f32_16x16x32_bf16 v[12:15], v[154:157], v[214:217], v[12:15]
	v_mfma_f32_16x16x32_bf16 v[8:11], v[162:165], v[214:217], v[8:11]
	v_mfma_f32_16x16x32_bf16 v[52:55], v[166:169], v[182:185], v[52:55]
	v_mfma_f32_16x16x32_bf16 v[48:51], v[174:177], v[182:185], v[48:51]
	v_mfma_f32_16x16x32_bf16 v[36:39], v[166:169], v[194:197], v[36:39]
	v_mfma_f32_16x16x32_bf16 v[32:35], v[174:177], v[194:197], v[32:35]
	v_mfma_f32_16x16x32_bf16 v[20:23], v[166:169], v[202:205], v[20:23]
	v_mfma_f32_16x16x32_bf16 v[16:19], v[174:177], v[202:205], v[16:19]
	v_mfma_f32_16x16x32_bf16 v[4:7], v[166:169], v[210:213], v[4:7]
	v_mfma_f32_16x16x32_bf16 v[0:3], v[174:177], v[210:213], v[0:3]
	v_mfma_f32_16x16x32_bf16 v[52:55], v[170:173], v[186:189], v[52:55]
	v_mfma_f32_16x16x32_bf16 v[48:51], v[178:181], v[186:189], v[48:51]
	v_mfma_f32_16x16x32_bf16 v[36:39], v[170:173], v[198:201], v[36:39]
	v_mfma_f32_16x16x32_bf16 v[32:35], v[178:181], v[198:201], v[32:35]
	v_mfma_f32_16x16x32_bf16 v[20:23], v[170:173], v[206:209], v[20:23]
	v_mfma_f32_16x16x32_bf16 v[16:19], v[178:181], v[206:209], v[16:19]
	v_mfma_f32_16x16x32_bf16 v[4:7], v[170:173], v[214:217], v[4:7]
	v_mfma_f32_16x16x32_bf16 v[0:3], v[178:181], v[214:217], v[0:3]
	s_setprio 0
	s_barrier
	s_add_u32 s54, s54, 0x100
	s_addc_u32 s55, s55, 0
	s_add_u32 s33, s33, 0x100
	s_addc_u32 s85, s85, 0
	s_cmp_ge_i32 s86, s67
	s_mov_b32 s56, s86
	s_cbranch_scc0 .LBB0_1034

; #define PG8_STAGE(bufoff, gbase, voff) do { _Pragma("unroll") for (int _i = 0; _i < 2; ++_i) \
;         __builtin_amdgcn_global_load_lds((const unsigned*)((const char*)(gbase) + (voff)[_i]), (PG8_LAS unsigned*)(lds + (bufoff) + ldsw + _i * 8192), 16, 0, 0); } while (0)
; #define PG8_LDA(dst, b, h) do { _Pragma("unroll") for (int m = 0; m < 4; ++m) _Pragma("unroll") for (int k = 0; k < 2; ++k) dst[m][k] = *(const PG8_LAS bf16x8*)(lds + PG8_SA(b, h) + aoff + m * 2048 + k * 1024); } while (0)
; #define PG8_LDB(dst, b, h) do { _Pragma("unroll") for (int n = 0; n < 2; ++n) _Pragma("unroll") for (int k = 0; k < 2; ++k) dst[n][k] = *(const PG8_LAS bf16x8*)(lds + PG8_SB(b, h) + boff + n * 2048 + k * 1024); } while (0)
; #define PG8_MMA(ai, bj, At, Bt) do { __builtin_amdgcn_s_setprio(1); _Pragma("unroll") for (int m = 0; m < 4; ++m) _Pragma("unroll") for (int n = 0; n < 2; ++n) _Pragma("unroll") for (int k = 0; k < 2; ++k) \
;         acc[ai][bj][m][n] = __builtin_amdgcn_mfma_f32_16x16x32_bf16(Bt[n][k], At[m][k], acc[ai][bj][m][n], 0, 0, 0); __builtin_amdgcn_s_setprio(0); } while (0)
; #define PG8_WAIT_V(n) asm volatile("s_waitcnt vmcnt(" #n ")" ::: "memory")
; #define PG8_BAR __builtin_amdgcn_s_barrier()
; template <class Epi, class Sched, bool ALIGN_EPI = false, bool SP2 = false>
; __device__ __forceinline__ void gemm_phase(PG8_LAS unsigned char* lds, const Gemm g, const Sched& S, const Epi& E) {
;     ...
;         for (int t = 0; t < nt; t += 2) {
;             const bool last = (t == nt - 2);
;             const char* a1 = cA + (size_t)(t + 1) * kstep;
;             const char* a2 = last ? nA : cA + (size_t)(t + 2) * kstep; const char* b2 = last ? nB : cB + (size_t)(t + 2) * kstep;
;             const char* a3 = a2 + kstep; const char* b3 = b2 + kstep;
;             if (last && has_next) S.a_ready(nxt);
;             if constexpr (SP2) {
;             PG8_LDB(B0, 0, 0); PG8_LDB(B1, 0, 1); PG8_SCHED; PG8_LDA(At, 0, 0); PG8_STAGE(PG8_SA(1, 1), a1 + hstep, voffA);
;             PG8_WAIT_V(8); PG8_WAIT_L(0); PG8_BAR; PG8_MMA(0, 0, At, B0); PG8_MMA(0, 1, At, B1); PG8_BAR; PG8_SCHED;
;             PG8_LDA(At, 0, 1); PG8_STAGE(PG8_SB(0, 0), b2, voffB); PG8_STAGE(PG8_SB(0, 1), b2 + hstep, voffB); PG8_STAGE(PG8_SA(0, 0), a2, voffA);
;             PG8_WAIT_V(8); PG8_WAIT_L(0); PG8_BAR; PG8_MMA(1, 0, At, B0); PG8_MMA(1, 1, At, B1); PG8_BAR; PG8_SCHED;
.LBB0_1118:
	ds_read_b128 v[142:145], v247
	ds_read_b128 v[146:149], v247 offset:1024
	ds_read_b128 v[150:153], v247 offset:2048
	ds_read_b128 v[154:157], v247 offset:3072
	ds_read_b128 v[158:161], v248
	ds_read_b128 v[162:165], v248 offset:1024
	ds_read_b128 v[166:169], v248 offset:2048
	ds_read_b128 v[170:173], v248 offset:3072
	s_add_i32 s72, s33, 2
	s_add_u32 s54, s42, 0x80
	s_addc_u32 s55, s43, 0
	s_cmp_eq_u32 s62, s33
	s_cselect_b32 s55, s9, s55
	s_cselect_b32 s54, s8, s54
	s_cselect_b32 s75, s41, s5
	s_cselect_b32 s74, s40, s4
	v_lshl_add_u64 v[190:191], s[42:43], 0, v[136:137]
	s_add_i32 m0, s48, 0xc000
	ds_read_b128 v[174:177], v249
	ds_read_b128 v[178:181], v249 offset:1024
	ds_read_b128 v[182:185], v249 offset:2048
	ds_read_b128 v[186:189], v249 offset:3072
	ds_read_b128 v[194:197], v249 offset:4096
	ds_read_b128 v[198:201], v249 offset:5120
	ds_read_b128 v[202:205], v249 offset:6144
	ds_read_b128 v[206:209], v249 offset:7168
	global_load_lds_dwordx4 v[190:191], off
	v_lshl_add_u64 v[190:191], s[42:43], 0, v[138:139]
	s_add_i32 m0, s48, 0xe000
	s_nop 0
	global_load_lds_dwordx4 v[190:191], off
	s_waitcnt vmcnt(8)
	s_waitcnt lgkmcnt(0)
	s_barrier
	s_setprio 1
	v_mfma_f32_16x16x32_bf16 v[124:127], v[142:145], v[174:177], v[124:127]
	v_mfma_f32_16x16x32_bf16 v[120:123], v[150:153], v[174:177], v[120:123]
	v_mfma_f32_16x16x32_bf16 v[116:119], v[142:145], v[182:185], v[116:119]
	v_mfma_f32_16x16x32_bf16 v[112:115], v[150:153], v[182:185], v[112:115]
	v_mfma_f32_16x16x32_bf16 v[104:107], v[142:145], v[194:197], v[104:107]
	v_mfma_f32_16x16x32_bf16 v[96:99], v[150:153], v[194:197], v[96:99]
	v_mfma_f32_16x16x32_bf16 v[88:91], v[142:145], v[202:205], v[88:91]
	v_mfma_f32_16x16x32_bf16 v[80:83], v[150:153], v[202:205], v[80:83]
	v_mfma_f32_16x16x32_bf16 v[124:127], v[146:149], v[178:181], v[124:127]
	v_mfma_f32_16x16x32_bf16 v[120:123], v[154:157], v[178:181], v[120:123]
	v_mfma_f32_16x16x32_bf16 v[116:119], v[146:149], v[186:189], v[116:119]
	v_mfma_f32_16x16x32_bf16 v[112:115], v[154:157], v[186:189], v[112:115]
	v_mfma_f32_16x16x32_bf16 v[104:107], v[146:149], v[198:201], v[104:107]
	v_mfma_f32_16x16x32_bf16 v[96:99], v[154:157], v[198:201], v[96:99]
	v_mfma_f32_16x16x32_bf16 v[88:91], v[146:149], v[206:209], v[88:91]
	v_mfma_f32_16x16x32_bf16 v[80:83], v[154:157], v[206:209], v[80:83]
	v_mfma_f32_16x16x32_bf16 v[108:111], v[158:161], v[174:177], v[108:111]
	v_mfma_f32_16x16x32_bf16 v[100:103], v[166:169], v[174:177], v[100:103]
	v_mfma_f32_16x16x32_bf16 v[92:95], v[158:161], v[182:185], v[92:95]
	v_mfma_f32_16x16x32_bf16 v[84:87], v[166:169], v[182:185], v[84:87]
	v_mfma_f32_16x16x32_bf16 v[76:79], v[158:161], v[194:197], v[76:79]
	v_mfma_f32_16x16x32_bf16 v[72:75], v[166:169], v[194:197], v[72:75]
	v_mfma_f32_16x16x32_bf16 v[68:71], v[158:161], v[202:205], v[68:71]
	v_mfma_f32_16x16x32_bf16 v[64:67], v[166:169], v[202:205], v[64:67]
	v_mfma_f32_16x16x32_bf16 v[108:111], v[162:165], v[178:181], v[108:111]
	v_mfma_f32_16x16x32_bf16 v[100:103], v[170:173], v[178:181], v[100:103]
	v_mfma_f32_16x16x32_bf16 v[92:95], v[162:165], v[186:189], v[92:95]
	v_mfma_f32_16x16x32_bf16 v[84:87], v[170:173], v[186:189], v[84:87]
	v_mfma_f32_16x16x32_bf16 v[76:79], v[162:165], v[198:201], v[76:79]
	v_mfma_f32_16x16x32_bf16 v[72:75], v[170:173], v[198:201], v[72:75]
	v_mfma_f32_16x16x32_bf16 v[68:71], v[162:165], v[206:209], v[68:71]
	v_mfma_f32_16x16x32_bf16 v[64:67], v[170:173], v[206:209], v[64:67]
	s_setprio 0
	s_barrier
	s_add_i32 s33, s66, s3
	v_lshl_add_u64 v[190:191], s[74:75], 0, v[130:131]
	s_mov_b32 m0, s33
	ds_read_b128 v[174:177], v249 offset:16384
	ds_read_b128 v[178:181], v249 offset:17408
	ds_read_b128 v[182:185], v249 offset:18432
	ds_read_b128 v[186:189], v249 offset:19456
	ds_read_b128 v[194:197], v249 offset:20480
	ds_read_b128 v[198:201], v249 offset:21504
	ds_read_b128 v[202:205], v249 offset:22528
	ds_read_b128 v[206:209], v249 offset:23552
	global_load_lds_dwordx4 v[190:191], off
	s_add_i32 m0, s33, 0x2000
	v_lshl_add_u64 v[210:211], s[74:75], 0, v[134:135]
	s_add_u32 s74, s74, s14
	s_addc_u32 s75, s75, s15
	s_add_i32 s33, s67, s3
	global_load_lds_dwordx4 v[210:211], off
	v_lshl_add_u64 v[212:213], s[74:75], 0, v[130:131]
	s_mov_b32 m0, s33
	v_lshl_add_u64 v[214:215], s[74:75], 0, v[134:135]
	global_load_lds_dwordx4 v[212:213], off
	s_add_i32 m0, s33, 0x2000
	v_lshl_add_u64 v[216:217], s[54:55], 0, v[128:129]
	global_load_lds_dwordx4 v[214:215], off
	s_mov_b32 m0, s48
	v_lshl_add_u64 v[218:219], s[54:55], 0, v[132:133]
	global_load_lds_dwordx4 v[216:217], off
	s_mov_b32 m0, s49
	s_nop 0
	global_load_lds_dwordx4 v[218:219], off
	s_waitcnt vmcnt(8)
	s_waitcnt lgkmcnt(0)
	s_barrier
; #define PG8_STAGE(bufoff, gbase, voff) do { _Pragma("unroll") for (int _i = 0; _i < 2; ++_i) \
;         __builtin_amdgcn_global_load_lds((const unsigned*)((const char*)(gbase) + (voff)[_i]), (PG8_LAS unsigned*)(lds + (bufoff) + ldsw + _i * 8192), 16, 0, 0); } while (0)
; #define PG8_LDA(dst, b, h) do { _Pragma("unroll") for (int m = 0; m < 4; ++m) _Pragma("unroll") for (int k = 0; k < 2; ++k) dst[m][k] = *(const PG8_LAS bf16x8*)(lds + PG8_SA(b, h) + aoff + m * 2048 + k * 1024); } while (0)
; #define PG8_LDB(dst, b, h) do { _Pragma("unroll") for (int n = 0; n < 2; ++n) _Pragma("unroll") for (int k = 0; k < 2; ++k) dst[n][k] = *(const PG8_LAS bf16x8*)(lds + PG8_SB(b, h) + boff + n * 2048 + k * 1024); } while (0)
; #define PG8_MMA(ai, bj, At, Bt) do { __builtin_amdgcn_s_setprio(1); _Pragma("unroll") for (int m = 0; m < 4; ++m) _Pragma("unroll") for (int n = 0; n < 2; ++n) _Pragma("unroll") for (int k = 0; k < 2; ++k) \
;         acc[ai][bj][m][n] = __builtin_amdgcn_mfma_f32_16x16x32_bf16(Bt[n][k], At[m][k], acc[ai][bj][m][n], 0, 0, 0); __builtin_amdgcn_s_setprio(0); } while (0)
; #define PG8_WAIT_V(n) asm volatile("s_waitcnt vmcnt(" #n ")" ::: "memory")
; #define PG8_WAIT_L(n) asm volatile("s_waitcnt lgkmcnt(" #n ")" ::: "memory")
; #define PG8_BAR __builtin_amdgcn_s_barrier()
; #define PG8_SCHED __builtin_amdgcn_sched_barrier(0)
; template <class Epi, class Sched, bool ALIGN_EPI = false, bool SP2 = false>
; __device__ __forceinline__ void gemm_phase(PG8_LAS unsigned char* lds, const Gemm g, const Sched& S, const Epi& E) {
;     ...
;             PG8_WAIT_V(8); PG8_WAIT_L(0); PG8_BAR; PG8_MMA(1, 0, At, B0); PG8_MMA(1, 1, At, B1); PG8_BAR; PG8_SCHED;
;             PG8_LDB(B0, 1, 0); PG8_LDB(B1, 1, 1); PG8_SCHED; PG8_LDA(At, 1, 0); PG8_STAGE(PG8_SA(0, 1), a2 + hstep, voffA);
;             PG8_WAIT_V(8); PG8_WAIT_L(0); PG8_BAR; PG8_MMA(0, 0, At, B0); PG8_MMA(0, 1, At, B1); PG8_BAR; PG8_SCHED;
	s_setprio 1
	v_mfma_f32_16x16x32_bf16 v[60:63], v[142:145], v[174:177], v[60:63]
	v_mfma_f32_16x16x32_bf16 v[56:59], v[150:153], v[174:177], v[56:59]
	v_mfma_f32_16x16x32_bf16 v[52:55], v[142:145], v[182:185], v[52:55]
	v_mfma_f32_16x16x32_bf16 v[48:51], v[150:153], v[182:185], v[48:51]
	v_mfma_f32_16x16x32_bf16 v[40:43], v[142:145], v[194:197], v[40:43]
	v_mfma_f32_16x16x32_bf16 v[32:35], v[150:153], v[194:197], v[32:35]
	v_mfma_f32_16x16x32_bf16 v[24:27], v[142:145], v[202:205], v[24:27]
	v_mfma_f32_16x16x32_bf16 v[16:19], v[150:153], v[202:205], v[16:19]
	v_mfma_f32_16x16x32_bf16 v[60:63], v[146:149], v[178:181], v[60:63]
	v_mfma_f32_16x16x32_bf16 v[56:59], v[154:157], v[178:181], v[56:59]
	v_mfma_f32_16x16x32_bf16 v[52:55], v[146:149], v[186:189], v[52:55]
	v_mfma_f32_16x16x32_bf16 v[48:51], v[154:157], v[186:189], v[48:51]
	v_mfma_f32_16x16x32_bf16 v[40:43], v[146:149], v[198:201], v[40:43]
	v_mfma_f32_16x16x32_bf16 v[32:35], v[154:157], v[198:201], v[32:35]
	v_mfma_f32_16x16x32_bf16 v[24:27], v[146:149], v[206:209], v[24:27]
	v_mfma_f32_16x16x32_bf16 v[16:19], v[154:157], v[206:209], v[16:19]
	v_mfma_f32_16x16x32_bf16 v[44:47], v[158:161], v[174:177], v[44:47]
	v_mfma_f32_16x16x32_bf16 v[36:39], v[166:169], v[174:177], v[36:39]
	v_mfma_f32_16x16x32_bf16 v[28:31], v[158:161], v[182:185], v[28:31]
	v_mfma_f32_16x16x32_bf16 v[20:23], v[166:169], v[182:185], v[20:23]
	v_mfma_f32_16x16x32_bf16 v[12:15], v[158:161], v[194:197], v[12:15]
	v_mfma_f32_16x16x32_bf16 v[8:11], v[166:169], v[194:197], v[8:11]
	v_mfma_f32_16x16x32_bf16 v[4:7], v[158:161], v[202:205], v[4:7]
	v_mfma_f32_16x16x32_bf16 v[0:3], v[166:169], v[202:205], v[0:3]
	v_mfma_f32_16x16x32_bf16 v[44:47], v[162:165], v[178:181], v[44:47]
	v_mfma_f32_16x16x32_bf16 v[36:39], v[170:173], v[178:181], v[36:39]
	v_mfma_f32_16x16x32_bf16 v[28:31], v[162:165], v[186:189], v[28:31]
	v_mfma_f32_16x16x32_bf16 v[20:23], v[170:173], v[186:189], v[20:23]
	v_mfma_f32_16x16x32_bf16 v[12:15], v[162:165], v[198:201], v[12:15]
	v_mfma_f32_16x16x32_bf16 v[8:11], v[170:173], v[198:201], v[8:11]
	v_mfma_f32_16x16x32_bf16 v[4:7], v[162:165], v[206:209], v[4:7]
	v_mfma_f32_16x16x32_bf16 v[0:3], v[170:173], v[206:209], v[0:3]
	s_setprio 0
	s_barrier
	s_add_i32 s33, 0, 0x18000
	s_add_i32 s73, 0, 0x1c000
	v_add_u32_e32 v154, s33, v244
	v_add_u32_e32 v170, s73, v244
	ds_read_b128 v[142:145], v154
	ds_read_b128 v[146:149], v154 offset:1024
	ds_read_b128 v[150:153], v154 offset:2048
	ds_read_b128 v[154:157], v154 offset:3072
	ds_read_b128 v[158:161], v170
	ds_read_b128 v[162:165], v170 offset:1024
	ds_read_b128 v[166:169], v170 offset:2048
	ds_read_b128 v[170:173], v170 offset:3072
	s_add_u32 s54, s54, s14
	s_addc_u32 s55, s55, s15
	s_mov_b32 m0, s56
	v_lshl_add_u64 v[220:221], s[54:55], 0, v[128:129]
	ds_read_b128 v[174:177], v249 offset:32768
	ds_read_b128 v[178:181], v249 offset:33792
	ds_read_b128 v[182:185], v249 offset:34816
	ds_read_b128 v[186:189], v249 offset:35840
	ds_read_b128 v[194:197], v249 offset:36864
	ds_read_b128 v[198:201], v249 offset:37888
	ds_read_b128 v[202:205], v249 offset:38912
	ds_read_b128 v[206:209], v249 offset:39936
	global_load_lds_dwordx4 v[220:221], off
	v_lshl_add_u64 v[220:221], s[54:55], 0, v[132:133]
	s_mov_b32 m0, s57
	s_nop 0
	global_load_lds_dwordx4 v[220:221], off
	s_waitcnt vmcnt(8)
	s_waitcnt lgkmcnt(0)
	s_barrier
	s_setprio 1
	v_mfma_f32_16x16x32_bf16 v[124:127], v[142:145], v[174:177], v[124:127]
	v_mfma_f32_16x16x32_bf16 v[120:123], v[150:153], v[174:177], v[120:123]
	v_mfma_f32_16x16x32_bf16 v[116:119], v[142:145], v[182:185], v[116:119]
	v_mfma_f32_16x16x32_bf16 v[112:115], v[150:153], v[182:185], v[112:115]
	v_mfma_f32_16x16x32_bf16 v[104:107], v[142:145], v[194:197], v[104:107]
	v_mfma_f32_16x16x32_bf16 v[96:99], v[150:153], v[194:197], v[96:99]
	v_mfma_f32_16x16x32_bf16 v[88:91], v[142:145], v[202:205], v[88:91]
	v_mfma_f32_16x16x32_bf16 v[80:83], v[150:153], v[202:205], v[80:83]
	v_mfma_f32_16x16x32_bf16 v[124:127], v[146:149], v[178:181], v[124:127]
	v_mfma_f32_16x16x32_bf16 v[120:123], v[154:157], v[178:181], v[120:123]
	v_mfma_f32_16x16x32_bf16 v[116:119], v[146:149], v[186:189], v[116:119]
	v_mfma_f32_16x16x32_bf16 v[112:115], v[154:157], v[186:189], v[112:115]
	v_mfma_f32_16x16x32_bf16 v[104:107], v[146:149], v[198:201], v[104:107]
	v_mfma_f32_16x16x32_bf16 v[96:99], v[154:157], v[198:201], v[96:99]
	v_mfma_f32_16x16x32_bf16 v[88:91], v[146:149], v[206:209], v[88:91]
	v_mfma_f32_16x16x32_bf16 v[80:83], v[154:157], v[206:209], v[80:83]
	v_mfma_f32_16x16x32_bf16 v[108:111], v[158:161], v[174:177], v[108:111]
	v_mfma_f32_16x16x32_bf16 v[100:103], v[166:169], v[174:177], v[100:103]
	v_mfma_f32_16x16x32_bf16 v[92:95], v[158:161], v[182:185], v[92:95]
	v_mfma_f32_16x16x32_bf16 v[84:87], v[166:169], v[182:185], v[84:87]
	v_mfma_f32_16x16x32_bf16 v[76:79], v[158:161], v[194:197], v[76:79]
	v_mfma_f32_16x16x32_bf16 v[72:75], v[166:169], v[194:197], v[72:75]
	v_mfma_f32_16x16x32_bf16 v[68:71], v[158:161], v[202:205], v[68:71]
	v_mfma_f32_16x16x32_bf16 v[64:67], v[166:169], v[202:205], v[64:67]
	v_mfma_f32_16x16x32_bf16 v[108:111], v[162:165], v[178:181], v[108:111]
	v_mfma_f32_16x16x32_bf16 v[100:103], v[170:173], v[178:181], v[100:103]
	v_mfma_f32_16x16x32_bf16 v[92:95], v[162:165], v[186:189], v[92:95]
	v_mfma_f32_16x16x32_bf16 v[84:87], v[170:173], v[186:189], v[84:87]
	v_mfma_f32_16x16x32_bf16 v[76:79], v[162:165], v[198:201], v[76:79]
	v_mfma_f32_16x16x32_bf16 v[72:75], v[170:173], v[198:201], v[72:75]
	v_mfma_f32_16x16x32_bf16 v[68:71], v[162:165], v[206:209], v[68:71]
	v_mfma_f32_16x16x32_bf16 v[64:67], v[170:173], v[206:209], v[64:67]
	s_setprio 0
	s_barrier
; #define PG8_STAGE(bufoff, gbase, voff) do { _Pragma("unroll") for (int _i = 0; _i < 2; ++_i) \
;         __builtin_amdgcn_global_load_lds((const unsigned*)((const char*)(gbase) + (voff)[_i]), (PG8_LAS unsigned*)(lds + (bufoff) + ldsw + _i * 8192), 16, 0, 0); } while (0)
; #define PG8_LDA(dst, b, h) do { _Pragma("unroll") for (int m = 0; m < 4; ++m) _Pragma("unroll") for (int k = 0; k < 2; ++k) dst[m][k] = *(const PG8_LAS bf16x8*)(lds + PG8_SA(b, h) + aoff + m * 2048 + k * 1024); } while (0)
; #define PG8_MMA(ai, bj, At, Bt) do { __builtin_amdgcn_s_setprio(1); _Pragma("unroll") for (int m = 0; m < 4; ++m) _Pragma("unroll") for (int n = 0; n < 2; ++n) _Pragma("unroll") for (int k = 0; k < 2; ++k) \
;         acc[ai][bj][m][n] = __builtin_amdgcn_mfma_f32_16x16x32_bf16(Bt[n][k], At[m][k], acc[ai][bj][m][n], 0, 0, 0); __builtin_amdgcn_s_setprio(0); } while (0)
; #define PG8_WAIT_V(n) asm volatile("s_waitcnt vmcnt(" #n ")" ::: "memory")
; #define PG8_WAIT_L(n) asm volatile("s_waitcnt lgkmcnt(" #n ")" ::: "memory")
; #define PG8_BAR __builtin_amdgcn_s_barrier()
; #define PG8_SCHED __builtin_amdgcn_sched_barrier(0)
; template <class Epi, class Sched, bool ALIGN_EPI = false, bool SP2 = false>
; __device__ __forceinline__ void gemm_phase(PG8_LAS unsigned char* lds, const Gemm g, const Sched& S, const Epi& E) {
;     ...
;             PG8_LDA(At, 1, 1); PG8_STAGE(PG8_SB(1, 0), b3, voffB); PG8_STAGE(PG8_SB(1, 1), b3 + hstep, voffB); PG8_STAGE(PG8_SA(1, 0), a3, voffA);
;             PG8_WAIT_V(8); PG8_WAIT_L(0); PG8_BAR; PG8_MMA(1, 0, At, B0); PG8_MMA(1, 1, At, B1); PG8_BAR; PG8_SCHED;
	s_add_i32 s33, s33, s3
	v_lshl_add_u64 v[190:191], v[190:191], 0, s[22:23]
	s_mov_b32 m0, s33
	ds_read_b128 v[174:177], v249 offset:49152
	ds_read_b128 v[178:181], v249 offset:50176
	ds_read_b128 v[182:185], v249 offset:51200
	ds_read_b128 v[186:189], v249 offset:52224
	ds_read_b128 v[194:197], v249 offset:53248
	ds_read_b128 v[198:201], v249 offset:54272
	ds_read_b128 v[202:205], v249 offset:55296
	ds_read_b128 v[206:209], v249 offset:56320
	global_load_lds_dwordx4 v[190:191], off
	v_lshl_add_u64 v[190:191], v[210:211], 0, s[22:23]
	s_add_i32 m0, s33, 0x2000
	s_add_i32 s33, s73, s3
	global_load_lds_dwordx4 v[190:191], off
	v_lshl_add_u64 v[190:191], v[212:213], 0, s[22:23]
	s_mov_b32 m0, s33
	s_nop 0
	global_load_lds_dwordx4 v[190:191], off
	v_lshl_add_u64 v[190:191], v[214:215], 0, s[22:23]
	s_add_i32 m0, s33, 0x2000
	s_nop 0
	global_load_lds_dwordx4 v[190:191], off
	v_lshl_add_u64 v[190:191], v[216:217], 0, s[22:23]
	s_mov_b32 m0, s58
	s_nop 0
	global_load_lds_dwordx4 v[190:191], off
	v_lshl_add_u64 v[190:191], v[218:219], 0, s[22:23]
	s_mov_b32 m0, s59
	s_nop 0
	global_load_lds_dwordx4 v[190:191], off
	s_waitcnt vmcnt(8)
	s_waitcnt lgkmcnt(0)
	s_barrier
	s_setprio 1
	v_mfma_f32_16x16x32_bf16 v[60:63], v[142:145], v[174:177], v[60:63]
	v_mfma_f32_16x16x32_bf16 v[56:59], v[150:153], v[174:177], v[56:59]
	v_mfma_f32_16x16x32_bf16 v[52:55], v[142:145], v[182:185], v[52:55]
	v_mfma_f32_16x16x32_bf16 v[48:51], v[150:153], v[182:185], v[48:51]
	v_mfma_f32_16x16x32_bf16 v[40:43], v[142:145], v[194:197], v[40:43]
	v_mfma_f32_16x16x32_bf16 v[32:35], v[150:153], v[194:197], v[32:35]
	v_mfma_f32_16x16x32_bf16 v[24:27], v[142:145], v[202:205], v[24:27]
	v_mfma_f32_16x16x32_bf16 v[16:19], v[150:153], v[202:205], v[16:19]
	v_mfma_f32_16x16x32_bf16 v[60:63], v[146:149], v[178:181], v[60:63]
	v_mfma_f32_16x16x32_bf16 v[56:59], v[154:157], v[178:181], v[56:59]
	v_mfma_f32_16x16x32_bf16 v[52:55], v[146:149], v[186:189], v[52:55]
	v_mfma_f32_16x16x32_bf16 v[48:51], v[154:157], v[186:189], v[48:51]
	v_mfma_f32_16x16x32_bf16 v[40:43], v[146:149], v[198:201], v[40:43]
	v_mfma_f32_16x16x32_bf16 v[32:35], v[154:157], v[198:201], v[32:35]
	v_mfma_f32_16x16x32_bf16 v[24:27], v[146:149], v[206:209], v[24:27]
	v_mfma_f32_16x16x32_bf16 v[16:19], v[154:157], v[206:209], v[16:19]
	v_mfma_f32_16x16x32_bf16 v[44:47], v[158:161], v[174:177], v[44:47]
	v_mfma_f32_16x16x32_bf16 v[36:39], v[166:169], v[174:177], v[36:39]
	v_mfma_f32_16x16x32_bf16 v[28:31], v[158:161], v[182:185], v[28:31]
	v_mfma_f32_16x16x32_bf16 v[20:23], v[166:169], v[182:185], v[20:23]
	v_mfma_f32_16x16x32_bf16 v[12:15], v[158:161], v[194:197], v[12:15]
	v_mfma_f32_16x16x32_bf16 v[8:11], v[166:169], v[194:197], v[8:11]
	v_mfma_f32_16x16x32_bf16 v[4:7], v[158:161], v[202:205], v[4:7]
	v_mfma_f32_16x16x32_bf16 v[0:3], v[166:169], v[202:205], v[0:3]
	v_mfma_f32_16x16x32_bf16 v[44:47], v[162:165], v[178:181], v[44:47]
	v_mfma_f32_16x16x32_bf16 v[36:39], v[170:173], v[178:181], v[36:39]
	v_mfma_f32_16x16x32_bf16 v[28:31], v[162:165], v[186:189], v[28:31]
	v_mfma_f32_16x16x32_bf16 v[20:23], v[170:173], v[186:189], v[20:23]
	v_mfma_f32_16x16x32_bf16 v[12:15], v[162:165], v[198:201], v[12:15]
	v_mfma_f32_16x16x32_bf16 v[8:11], v[170:173], v[198:201], v[8:11]
	v_mfma_f32_16x16x32_bf16 v[4:7], v[162:165], v[206:209], v[4:7]
	v_mfma_f32_16x16x32_bf16 v[0:3], v[170:173], v[206:209], v[0:3]
	s_setprio 0
	s_barrier
	s_add_u32 s42, s42, 0x100
	s_addc_u32 s43, s43, 0
	s_add_u32 s4, s4, 0x100
	s_addc_u32 s5, s5, 0
	s_cmp_ge_i32 s72, s61
	s_mov_b32 s33, s72
	s_cbranch_scc0 .LBB0_1118
;     __device__ __forceinline__ void operator()(const f32x4 (&acc)[2][2][4][2], const Unit& u, int wr, int wc, int fr, int fq) const {
;     ...
;                 const u32x4 b0 = rb[ai][m][0], b1 = rb[ai][m][1];
;                 float ss = 0.f;
; #pragma unroll
;                 for (int bj = 0; bj < 2; ++bj) {
;                     const u32x4 b = bj ? b1 : b0;
;                     f32x4 v0, v1;
;                     v0[0] = __uint_as_float(b.x << 16); v0[1] = __uint_as_float(b.x & 0xffff0000u); v0[2] = __uint_as_float(b.y << 16); v0[3] = __uint_as_float(b.y & 0xffff0000u);
;                     v1[0] = __uint_as_float(b.z << 16); v1[1] = __uint_as_float(b.z & 0xffff0000u); v1[2] = __uint_as_float(b.w << 16); v1[3] = __uint_as_float(b.w & 0xffff0000u);
;                     v0 += acc[ai][bj][m][0] * alpha; v1 += acc[ai][bj][m][1] * alpha;
	v_pk_mul_f32 v[220:221], v[126:127], 0.5 op_sel_hi:[1,0]
	v_pk_mul_f32 v[222:223], v[124:125], 0.5 op_sel_hi:[1,0]
	v_pk_mul_f32 v[224:225], v[122:123], 0.5 op_sel_hi:[1,0]
	v_pk_mul_f32 v[226:227], v[120:121], 0.5 op_sel_hi:[1,0]
	v_pk_mul_f32 v[214:215], v[110:111], 0.5 op_sel_hi:[1,0]
	v_pk_mul_f32 v[212:213], v[108:109], 0.5 op_sel_hi:[1,0]
	v_pk_mul_f32 v[210:211], v[102:103], 0.5 op_sel_hi:[1,0]
	v_pk_mul_f32 v[206:207], v[100:101], 0.5 op_sel_hi:[1,0]
	v_pk_mul_f32 v[198:199], v[118:119], 0.5 op_sel_hi:[1,0]
	v_pk_mul_f32 v[196:197], v[116:117], 0.5 op_sel_hi:[1,0]
	v_pk_mul_f32 v[194:195], v[114:115], 0.5 op_sel_hi:[1,0]
	v_pk_mul_f32 v[190:191], v[112:113], 0.5 op_sel_hi:[1,0]
	v_pk_mul_f32 v[188:189], v[94:95], 0.5 op_sel_hi:[1,0]
	v_pk_mul_f32 v[186:187], v[92:93], 0.5 op_sel_hi:[1,0]
	v_pk_mul_f32 v[184:185], v[86:87], 0.5 op_sel_hi:[1,0]
	v_pk_mul_f32 v[182:183], v[84:85], 0.5 op_sel_hi:[1,0]
	v_pk_mul_f32 v[176:177], v[106:107], 0.5 op_sel_hi:[1,0]
	v_pk_mul_f32 v[174:175], v[104:105], 0.5 op_sel_hi:[1,0]
	v_pk_mul_f32 v[172:173], v[98:99], 0.5 op_sel_hi:[1,0]
	v_pk_mul_f32 v[170:171], v[96:97], 0.5 op_sel_hi:[1,0]
	v_pk_mul_f32 v[168:169], v[78:79], 0.5 op_sel_hi:[1,0]
	v_pk_mul_f32 v[166:167], v[76:77], 0.5 op_sel_hi:[1,0]
	v_pk_mul_f32 v[164:165], v[74:75], 0.5 op_sel_hi:[1,0]
	v_pk_mul_f32 v[162:163], v[72:73], 0.5 op_sel_hi:[1,0]
	v_pk_mul_f32 v[158:159], v[90:91], 0.5 op_sel_hi:[1,0]
	v_pk_mul_f32 v[156:157], v[88:89], 0.5 op_sel_hi:[1,0]
	v_pk_mul_f32 v[154:155], v[82:83], 0.5 op_sel_hi:[1,0]
	v_pk_mul_f32 v[152:153], v[80:81], 0.5 op_sel_hi:[1,0]
	v_pk_mul_f32 v[148:149], v[70:71], 0.5 op_sel_hi:[1,0]
	v_pk_mul_f32 v[146:147], v[68:69], 0.5 op_sel_hi:[1,0]
	v_pk_mul_f32 v[144:145], v[66:67], 0.5 op_sel_hi:[1,0]
	v_pk_mul_f32 v[142:143], v[64:65], 0.5 op_sel_hi:[1,0]
	v_pk_mul_f32 v[126:127], v[62:63], 0.5 op_sel_hi:[1,0]
	v_pk_mul_f32 v[124:125], v[60:61], 0.5 op_sel_hi:[1,0]
	v_pk_mul_f32 v[122:123], v[58:59], 0.5 op_sel_hi:[1,0]
	v_pk_mul_f32 v[120:121], v[56:57], 0.5 op_sel_hi:[1,0]
	v_pk_mul_f32 v[118:119], v[46:47], 0.5 op_sel_hi:[1,0]
	v_pk_mul_f32 v[116:117], v[44:45], 0.5 op_sel_hi:[1,0]
	v_pk_mul_f32 v[114:115], v[38:39], 0.5 op_sel_hi:[1,0]
	v_pk_mul_f32 v[112:113], v[36:37], 0.5 op_sel_hi:[1,0]
	v_pk_mul_f32 v[110:111], v[54:55], 0.5 op_sel_hi:[1,0]
	v_pk_mul_f32 v[108:109], v[52:53], 0.5 op_sel_hi:[1,0]
	v_pk_mul_f32 v[106:107], v[50:51], 0.5 op_sel_hi:[1,0]
	v_pk_mul_f32 v[104:105], v[48:49], 0.5 op_sel_hi:[1,0]
	v_pk_mul_f32 v[102:103], v[30:31], 0.5 op_sel_hi:[1,0]
	v_pk_mul_f32 v[100:101], v[28:29], 0.5 op_sel_hi:[1,0]
	v_pk_mul_f32 v[98:99], v[22:23], 0.5 op_sel_hi:[1,0]
	v_pk_mul_f32 v[96:97], v[20:21], 0.5 op_sel_hi:[1,0]
	v_pk_mul_f32 v[94:95], v[42:43], 0.5 op_sel_hi:[1,0]
	v_pk_mul_f32 v[92:93], v[40:41], 0.5 op_sel_hi:[1,0]
	v_pk_mul_f32 v[90:91], v[34:35], 0.5 op_sel_hi:[1,0]
	v_pk_mul_f32 v[88:89], v[32:33], 0.5 op_sel_hi:[1,0]
	v_pk_mul_f32 v[86:87], v[14:15], 0.5 op_sel_hi:[1,0]
	v_pk_mul_f32 v[84:85], v[12:13], 0.5 op_sel_hi:[1,0]
	v_pk_mul_f32 v[82:83], v[10:11], 0.5 op_sel_hi:[1,0]
	v_pk_mul_f32 v[80:81], v[8:9], 0.5 op_sel_hi:[1,0]
	v_pk_mul_f32 v[78:79], v[26:27], 0.5 op_sel_hi:[1,0]
	v_pk_mul_f32 v[76:77], v[24:25], 0.5 op_sel_hi:[1,0]
	v_pk_mul_f32 v[74:75], v[18:19], 0.5 op_sel_hi:[1,0]
	v_pk_mul_f32 v[72:73], v[16:17], 0.5 op_sel_hi:[1,0]
	v_pk_mul_f32 v[70:71], v[6:7], 0.5 op_sel_hi:[1,0]
	v_pk_mul_f32 v[68:69], v[4:5], 0.5 op_sel_hi:[1,0]
	v_pk_mul_f32 v[66:67], v[2:3], 0.5 op_sel_hi:[1,0]
	v_pk_mul_f32 v[64:65], v[0:1], 0.5 op_sel_hi:[1,0]

; #define PG8_STAGE(bufoff, gbase, voff) do { _Pragma("unroll") for (int _i = 0; _i < 2; ++_i) \
;         __builtin_amdgcn_global_load_lds((const unsigned*)((const char*)(gbase) + (voff)[_i]), (PG8_LAS unsigned*)(lds + (bufoff) + ldsw + _i * 8192), 16, 0, 0); } while (0)
; #define PG8_LDA(dst, b, h) do { _Pragma("unroll") for (int m = 0; m < 4; ++m) _Pragma("unroll") for (int k = 0; k < 2; ++k) dst[m][k] = *(const PG8_LAS bf16x8*)(lds + PG8_SA(b, h) + aoff + m * 2048 + k * 1024); } while (0)
; #define PG8_LDB(dst, b, h) do { _Pragma("unroll") for (int n = 0; n < 2; ++n) _Pragma("unroll") for (int k = 0; k < 2; ++k) dst[n][k] = *(const PG8_LAS bf16x8*)(lds + PG8_SB(b, h) + boff + n * 2048 + k * 1024); } while (0)
; #define PG8_MMA(ai, bj, At, Bt) do { __builtin_amdgcn_s_setprio(1); _Pragma("unroll") for (int m = 0; m < 4; ++m) _Pragma("unroll") for (int n = 0; n < 2; ++n) _Pragma("unroll") for (int k = 0; k < 2; ++k) \
;         acc[ai][bj][m][n] = __builtin_amdgcn_mfma_f32_16x16x32_bf16(Bt[n][k], At[m][k], acc[ai][bj][m][n], 0, 0, 0); __builtin_amdgcn_s_setprio(0); } while (0)
; #define PG8_WAIT_V(n) asm volatile("s_waitcnt vmcnt(" #n ")" ::: "memory")
; #define PG8_BAR __builtin_amdgcn_s_barrier()
; template <class Epi, class Sched, bool ALIGN_EPI = false, bool SP2 = false>
; __device__ __forceinline__ void gemm_phase(PG8_LAS unsigned char* lds, const Gemm g, const Sched& S, const Epi& E) {
;     ...
;         for (int t = 0; t < nt; t += 2) {
;             const bool last = (t == nt - 2);
;             const char* a1 = cA + (size_t)(t + 1) * kstep;
;             const char* a2 = last ? nA : cA + (size_t)(t + 2) * kstep; const char* b2 = last ? nB : cB + (size_t)(t + 2) * kstep;
;             const char* a3 = a2 + kstep; const char* b3 = b2 + kstep;
;             if (last && has_next) S.a_ready(nxt);
;             if constexpr (SP2) {
;             PG8_LDB(B0, 0, 0); PG8_LDB(B1, 0, 1); PG8_SCHED; PG8_LDA(At, 0, 0); PG8_STAGE(PG8_SA(1, 1), a1 + hstep, voffA);
;             PG8_WAIT_V(8); PG8_WAIT_L(0); PG8_BAR; PG8_MMA(0, 0, At, B0); PG8_MMA(0, 1, At, B1); PG8_BAR; PG8_SCHED;
;             PG8_LDA(At, 0, 1); PG8_STAGE(PG8_SB(0, 0), b2, voffB); PG8_STAGE(PG8_SB(0, 1), b2 + hstep, voffB); PG8_STAGE(PG8_SA(0, 0), a2, voffA);
;             PG8_WAIT_V(8); PG8_WAIT_L(0); PG8_BAR; PG8_MMA(1, 0, At, B0); PG8_MMA(1, 1, At, B1); PG8_BAR; PG8_SCHED;
.LBB0_1221:
	ds_read_b128 v[150:153], v147
	ds_read_b128 v[154:157], v147 offset:1024
	ds_read_b128 v[158:161], v147 offset:2048
	ds_read_b128 v[162:165], v147 offset:3072
	ds_read_b128 v[166:169], v148
	ds_read_b128 v[170:173], v148 offset:1024
	ds_read_b128 v[174:177], v148 offset:2048
	ds_read_b128 v[178:181], v148 offset:3072
	s_add_i32 s70, s48, 2
	s_add_u32 s71, s42, 0x80
	s_addc_u32 s49, s43, 0
	s_cmp_eq_u32 s57, s48
	s_cselect_b32 s48, s4, s71
	s_cselect_b32 s49, s5, s49
	s_cselect_b32 s73, s41, s69
	s_cselect_b32 s72, s40, s68
	v_lshl_add_u64 v[190:191], s[42:43], 0, v[136:137]
	s_add_i32 m0, s33, 0xc000
	ds_read_b128 v[182:185], v149
	ds_read_b128 v[186:189], v149 offset:1024
	ds_read_b128 v[194:197], v149 offset:2048
	ds_read_b128 v[198:201], v149 offset:3072
	ds_read_b128 v[202:205], v149 offset:4096
	ds_read_b128 v[206:209], v149 offset:5120
	ds_read_b128 v[210:213], v149 offset:6144
	ds_read_b128 v[214:217], v149 offset:7168
	global_load_lds_dwordx4 v[190:191], off
	v_lshl_add_u64 v[190:191], s[42:43], 0, v[138:139]
	s_add_i32 m0, s33, 0xe000
	s_nop 0
	global_load_lds_dwordx4 v[190:191], off
	s_waitcnt vmcnt(8)
	s_waitcnt lgkmcnt(0)
	s_barrier
	s_setprio 1
	v_mfma_f32_16x16x32_bf16 v[120:123], v[150:153], v[182:185], v[120:123]
	v_mfma_f32_16x16x32_bf16 v[124:127], v[158:161], v[182:185], v[124:127]
	v_mfma_f32_16x16x32_bf16 v[108:111], v[150:153], v[194:197], v[108:111]
	v_mfma_f32_16x16x32_bf16 v[104:107], v[158:161], v[194:197], v[104:107]
	v_mfma_f32_16x16x32_bf16 v[92:95], v[150:153], v[202:205], v[92:95]
	v_mfma_f32_16x16x32_bf16 v[88:91], v[158:161], v[202:205], v[88:91]
	v_mfma_f32_16x16x32_bf16 v[76:79], v[150:153], v[210:213], v[76:79]
	v_mfma_f32_16x16x32_bf16 v[72:75], v[158:161], v[210:213], v[72:75]
	v_mfma_f32_16x16x32_bf16 v[120:123], v[154:157], v[186:189], v[120:123]
	v_mfma_f32_16x16x32_bf16 v[124:127], v[162:165], v[186:189], v[124:127]
	v_mfma_f32_16x16x32_bf16 v[108:111], v[154:157], v[198:201], v[108:111]
	v_mfma_f32_16x16x32_bf16 v[104:107], v[162:165], v[198:201], v[104:107]
	v_mfma_f32_16x16x32_bf16 v[92:95], v[154:157], v[206:209], v[92:95]
	v_mfma_f32_16x16x32_bf16 v[88:91], v[162:165], v[206:209], v[88:91]
	v_mfma_f32_16x16x32_bf16 v[76:79], v[154:157], v[214:217], v[76:79]
	v_mfma_f32_16x16x32_bf16 v[72:75], v[162:165], v[214:217], v[72:75]
	v_mfma_f32_16x16x32_bf16 v[116:119], v[166:169], v[182:185], v[116:119]
	v_mfma_f32_16x16x32_bf16 v[112:115], v[174:177], v[182:185], v[112:115]
	v_mfma_f32_16x16x32_bf16 v[100:103], v[166:169], v[194:197], v[100:103]
	v_mfma_f32_16x16x32_bf16 v[96:99], v[174:177], v[194:197], v[96:99]
	v_mfma_f32_16x16x32_bf16 v[84:87], v[166:169], v[202:205], v[84:87]
	v_mfma_f32_16x16x32_bf16 v[80:83], v[174:177], v[202:205], v[80:83]
	v_mfma_f32_16x16x32_bf16 v[68:71], v[166:169], v[210:213], v[68:71]
	v_mfma_f32_16x16x32_bf16 v[64:67], v[174:177], v[210:213], v[64:67]
	v_mfma_f32_16x16x32_bf16 v[116:119], v[170:173], v[186:189], v[116:119]
	v_mfma_f32_16x16x32_bf16 v[112:115], v[178:181], v[186:189], v[112:115]
	v_mfma_f32_16x16x32_bf16 v[100:103], v[170:173], v[198:201], v[100:103]
	v_mfma_f32_16x16x32_bf16 v[96:99], v[178:181], v[198:201], v[96:99]
	v_mfma_f32_16x16x32_bf16 v[84:87], v[170:173], v[206:209], v[84:87]
	v_mfma_f32_16x16x32_bf16 v[80:83], v[178:181], v[206:209], v[80:83]
	v_mfma_f32_16x16x32_bf16 v[68:71], v[170:173], v[214:217], v[68:71]
	v_mfma_f32_16x16x32_bf16 v[64:67], v[178:181], v[214:217], v[64:67]
	s_setprio 0
	s_barrier
	s_add_i32 s71, s59, s31
	v_lshl_add_u64 v[190:191], s[72:73], 0, v[130:131]
	s_mov_b32 m0, s71
	ds_read_b128 v[182:185], v149 offset:16384
	ds_read_b128 v[186:189], v149 offset:17408
	ds_read_b128 v[194:197], v149 offset:18432
	ds_read_b128 v[198:201], v149 offset:19456
	ds_read_b128 v[202:205], v149 offset:20480
	ds_read_b128 v[206:209], v149 offset:21504
	ds_read_b128 v[210:213], v149 offset:22528
	ds_read_b128 v[214:217], v149 offset:23552
	global_load_lds_dwordx4 v[190:191], off
	s_add_i32 m0, s71, 0x2000
	v_lshl_add_u64 v[218:219], s[72:73], 0, v[134:135]
	s_add_u32 s72, s72, s10
	s_addc_u32 s73, s73, s11
	s_add_i32 s71, s60, s31
	global_load_lds_dwordx4 v[218:219], off
	v_lshl_add_u64 v[220:221], s[72:73], 0, v[130:131]
	s_mov_b32 m0, s71
	v_lshl_add_u64 v[222:223], s[72:73], 0, v[134:135]
	global_load_lds_dwordx4 v[220:221], off
	s_add_i32 m0, s71, 0x2000
	v_lshl_add_u64 v[224:225], s[48:49], 0, v[128:129]
	global_load_lds_dwordx4 v[222:223], off
	s_mov_b32 m0, s33
	v_lshl_add_u64 v[226:227], s[48:49], 0, v[132:133]
	global_load_lds_dwordx4 v[224:225], off
	s_mov_b32 m0, s50
	s_nop 0
	global_load_lds_dwordx4 v[226:227], off
	s_waitcnt vmcnt(8)
	s_waitcnt lgkmcnt(0)
	s_barrier
; #define PG8_STAGE(bufoff, gbase, voff) do { _Pragma("unroll") for (int _i = 0; _i < 2; ++_i) \
;         __builtin_amdgcn_global_load_lds((const unsigned*)((const char*)(gbase) + (voff)[_i]), (PG8_LAS unsigned*)(lds + (bufoff) + ldsw + _i * 8192), 16, 0, 0); } while (0)
; #define PG8_LDA(dst, b, h) do { _Pragma("unroll") for (int m = 0; m < 4; ++m) _Pragma("unroll") for (int k = 0; k < 2; ++k) dst[m][k] = *(const PG8_LAS bf16x8*)(lds + PG8_SA(b, h) + aoff + m * 2048 + k * 1024); } while (0)
; #define PG8_LDB(dst, b, h) do { _Pragma("unroll") for (int n = 0; n < 2; ++n) _Pragma("unroll") for (int k = 0; k < 2; ++k) dst[n][k] = *(const PG8_LAS bf16x8*)(lds + PG8_SB(b, h) + boff + n * 2048 + k * 1024); } while (0)
; #define PG8_MMA(ai, bj, At, Bt) do { __builtin_amdgcn_s_setprio(1); _Pragma("unroll") for (int m = 0; m < 4; ++m) _Pragma("unroll") for (int n = 0; n < 2; ++n) _Pragma("unroll") for (int k = 0; k < 2; ++k) \
;         acc[ai][bj][m][n] = __builtin_amdgcn_mfma_f32_16x16x32_bf16(Bt[n][k], At[m][k], acc[ai][bj][m][n], 0, 0, 0); __builtin_amdgcn_s_setprio(0); } while (0)
; #define PG8_WAIT_V(n) asm volatile("s_waitcnt vmcnt(" #n ")" ::: "memory")
; #define PG8_WAIT_L(n) asm volatile("s_waitcnt lgkmcnt(" #n ")" ::: "memory")
; #define PG8_BAR __builtin_amdgcn_s_barrier()
; #define PG8_SCHED __builtin_amdgcn_sched_barrier(0)
; template <class Epi, class Sched, bool ALIGN_EPI = false, bool SP2 = false>
; __device__ __forceinline__ void gemm_phase(PG8_LAS unsigned char* lds, const Gemm g, const Sched& S, const Epi& E) {
;     ...
;             PG8_WAIT_V(8); PG8_WAIT_L(0); PG8_BAR; PG8_MMA(1, 0, At, B0); PG8_MMA(1, 1, At, B1); PG8_BAR; PG8_SCHED;
;             PG8_LDB(B0, 1, 0); PG8_LDB(B1, 1, 1); PG8_SCHED; PG8_LDA(At, 1, 0); PG8_STAGE(PG8_SA(0, 1), a2 + hstep, voffA);
;             PG8_WAIT_V(8); PG8_WAIT_L(0); PG8_BAR; PG8_MMA(0, 0, At, B0); PG8_MMA(0, 1, At, B1); PG8_BAR; PG8_SCHED;
	s_setprio 1
	v_mfma_f32_16x16x32_bf16 v[60:63], v[150:153], v[182:185], v[60:63]
	v_mfma_f32_16x16x32_bf16 v[56:59], v[158:161], v[182:185], v[56:59]
	v_mfma_f32_16x16x32_bf16 v[44:47], v[150:153], v[194:197], v[44:47]
	v_mfma_f32_16x16x32_bf16 v[40:43], v[158:161], v[194:197], v[40:43]
	v_mfma_f32_16x16x32_bf16 v[28:31], v[150:153], v[202:205], v[28:31]
	v_mfma_f32_16x16x32_bf16 v[24:27], v[158:161], v[202:205], v[24:27]
	v_mfma_f32_16x16x32_bf16 v[12:15], v[150:153], v[210:213], v[12:15]
	v_mfma_f32_16x16x32_bf16 v[8:11], v[158:161], v[210:213], v[8:11]
	v_mfma_f32_16x16x32_bf16 v[60:63], v[154:157], v[186:189], v[60:63]
	v_mfma_f32_16x16x32_bf16 v[56:59], v[162:165], v[186:189], v[56:59]
	v_mfma_f32_16x16x32_bf16 v[44:47], v[154:157], v[198:201], v[44:47]
	v_mfma_f32_16x16x32_bf16 v[40:43], v[162:165], v[198:201], v[40:43]
	v_mfma_f32_16x16x32_bf16 v[28:31], v[154:157], v[206:209], v[28:31]
	v_mfma_f32_16x16x32_bf16 v[24:27], v[162:165], v[206:209], v[24:27]
	v_mfma_f32_16x16x32_bf16 v[12:15], v[154:157], v[214:217], v[12:15]
	v_mfma_f32_16x16x32_bf16 v[8:11], v[162:165], v[214:217], v[8:11]
	v_mfma_f32_16x16x32_bf16 v[52:55], v[166:169], v[182:185], v[52:55]
	v_mfma_f32_16x16x32_bf16 v[48:51], v[174:177], v[182:185], v[48:51]
	v_mfma_f32_16x16x32_bf16 v[36:39], v[166:169], v[194:197], v[36:39]
	v_mfma_f32_16x16x32_bf16 v[32:35], v[174:177], v[194:197], v[32:35]
	v_mfma_f32_16x16x32_bf16 v[20:23], v[166:169], v[202:205], v[20:23]
	v_mfma_f32_16x16x32_bf16 v[16:19], v[174:177], v[202:205], v[16:19]
	v_mfma_f32_16x16x32_bf16 v[4:7], v[166:169], v[210:213], v[4:7]
	v_mfma_f32_16x16x32_bf16 v[0:3], v[174:177], v[210:213], v[0:3]
	v_mfma_f32_16x16x32_bf16 v[52:55], v[170:173], v[186:189], v[52:55]
	v_mfma_f32_16x16x32_bf16 v[48:51], v[178:181], v[186:189], v[48:51]
	v_mfma_f32_16x16x32_bf16 v[36:39], v[170:173], v[198:201], v[36:39]
	v_mfma_f32_16x16x32_bf16 v[32:35], v[178:181], v[198:201], v[32:35]
	v_mfma_f32_16x16x32_bf16 v[20:23], v[170:173], v[206:209], v[20:23]
	v_mfma_f32_16x16x32_bf16 v[16:19], v[178:181], v[206:209], v[16:19]
	v_mfma_f32_16x16x32_bf16 v[4:7], v[170:173], v[214:217], v[4:7]
	v_mfma_f32_16x16x32_bf16 v[0:3], v[178:181], v[214:217], v[0:3]
	s_setprio 0
	s_barrier
	s_add_i32 s71, 0, 0x18000
	s_add_i32 s72, 0, 0x1c000
	v_add_u32_e32 v162, s71, v145
	v_add_u32_e32 v178, s72, v145
	ds_read_b128 v[150:153], v162
	ds_read_b128 v[154:157], v162 offset:1024
	ds_read_b128 v[158:161], v162 offset:2048
	ds_read_b128 v[162:165], v162 offset:3072
	ds_read_b128 v[166:169], v178
	ds_read_b128 v[170:173], v178 offset:1024
	ds_read_b128 v[174:177], v178 offset:2048
	ds_read_b128 v[178:181], v178 offset:3072
	s_add_u32 s48, s48, s10
	s_addc_u32 s49, s49, s11
	s_mov_b32 m0, s51
	v_lshl_add_u64 v[228:229], s[48:49], 0, v[128:129]
	ds_read_b128 v[182:185], v149 offset:32768
	ds_read_b128 v[186:189], v149 offset:33792
	ds_read_b128 v[194:197], v149 offset:34816
	ds_read_b128 v[198:201], v149 offset:35840
	ds_read_b128 v[202:205], v149 offset:36864
	ds_read_b128 v[206:209], v149 offset:37888
	ds_read_b128 v[210:213], v149 offset:38912
	ds_read_b128 v[214:217], v149 offset:39936
	global_load_lds_dwordx4 v[228:229], off
	v_lshl_add_u64 v[228:229], s[48:49], 0, v[132:133]
	s_mov_b32 m0, s52
	s_nop 0
	global_load_lds_dwordx4 v[228:229], off
	s_waitcnt vmcnt(8)
	s_waitcnt lgkmcnt(0)
	s_barrier
	s_setprio 1
	v_mfma_f32_16x16x32_bf16 v[120:123], v[150:153], v[182:185], v[120:123]
	v_mfma_f32_16x16x32_bf16 v[124:127], v[158:161], v[182:185], v[124:127]
	v_mfma_f32_16x16x32_bf16 v[108:111], v[150:153], v[194:197], v[108:111]
	v_mfma_f32_16x16x32_bf16 v[104:107], v[158:161], v[194:197], v[104:107]
	v_mfma_f32_16x16x32_bf16 v[92:95], v[150:153], v[202:205], v[92:95]
	v_mfma_f32_16x16x32_bf16 v[88:91], v[158:161], v[202:205], v[88:91]
	v_mfma_f32_16x16x32_bf16 v[76:79], v[150:153], v[210:213], v[76:79]
	v_mfma_f32_16x16x32_bf16 v[72:75], v[158:161], v[210:213], v[72:75]
	v_mfma_f32_16x16x32_bf16 v[120:123], v[154:157], v[186:189], v[120:123]
	v_mfma_f32_16x16x32_bf16 v[124:127], v[162:165], v[186:189], v[124:127]
	v_mfma_f32_16x16x32_bf16 v[108:111], v[154:157], v[198:201], v[108:111]
	v_mfma_f32_16x16x32_bf16 v[104:107], v[162:165], v[198:201], v[104:107]
	v_mfma_f32_16x16x32_bf16 v[92:95], v[154:157], v[206:209], v[92:95]
	v_mfma_f32_16x16x32_bf16 v[88:91], v[162:165], v[206:209], v[88:91]
	v_mfma_f32_16x16x32_bf16 v[76:79], v[154:157], v[214:217], v[76:79]
	v_mfma_f32_16x16x32_bf16 v[72:75], v[162:165], v[214:217], v[72:75]
	v_mfma_f32_16x16x32_bf16 v[116:119], v[166:169], v[182:185], v[116:119]
	v_mfma_f32_16x16x32_bf16 v[112:115], v[174:177], v[182:185], v[112:115]
	v_mfma_f32_16x16x32_bf16 v[100:103], v[166:169], v[194:197], v[100:103]
	v_mfma_f32_16x16x32_bf16 v[96:99], v[174:177], v[194:197], v[96:99]
	v_mfma_f32_16x16x32_bf16 v[84:87], v[166:169], v[202:205], v[84:87]
	v_mfma_f32_16x16x32_bf16 v[80:83], v[174:177], v[202:205], v[80:83]
	v_mfma_f32_16x16x32_bf16 v[68:71], v[166:169], v[210:213], v[68:71]
	v_mfma_f32_16x16x32_bf16 v[64:67], v[174:177], v[210:213], v[64:67]
	v_mfma_f32_16x16x32_bf16 v[116:119], v[170:173], v[186:189], v[116:119]
	v_mfma_f32_16x16x32_bf16 v[112:115], v[178:181], v[186:189], v[112:115]
	v_mfma_f32_16x16x32_bf16 v[100:103], v[170:173], v[198:201], v[100:103]
	v_mfma_f32_16x16x32_bf16 v[96:99], v[178:181], v[198:201], v[96:99]
	v_mfma_f32_16x16x32_bf16 v[84:87], v[170:173], v[206:209], v[84:87]
	v_mfma_f32_16x16x32_bf16 v[80:83], v[178:181], v[206:209], v[80:83]
	v_mfma_f32_16x16x32_bf16 v[68:71], v[170:173], v[214:217], v[68:71]
	v_mfma_f32_16x16x32_bf16 v[64:67], v[178:181], v[214:217], v[64:67]
	s_setprio 0
	s_barrier
; #define PG8_STAGE(bufoff, gbase, voff) do { _Pragma("unroll") for (int _i = 0; _i < 2; ++_i) \
;         __builtin_amdgcn_global_load_lds((const unsigned*)((const char*)(gbase) + (voff)[_i]), (PG8_LAS unsigned*)(lds + (bufoff) + ldsw + _i * 8192), 16, 0, 0); } while (0)
; #define PG8_LDA(dst, b, h) do { _Pragma("unroll") for (int m = 0; m < 4; ++m) _Pragma("unroll") for (int k = 0; k < 2; ++k) dst[m][k] = *(const PG8_LAS bf16x8*)(lds + PG8_SA(b, h) + aoff + m * 2048 + k * 1024); } while (0)
; #define PG8_MMA(ai, bj, At, Bt) do { __builtin_amdgcn_s_setprio(1); _Pragma("unroll") for (int m = 0; m < 4; ++m) _Pragma("unroll") for (int n = 0; n < 2; ++n) _Pragma("unroll") for (int k = 0; k < 2; ++k) \
;         acc[ai][bj][m][n] = __builtin_amdgcn_mfma_f32_16x16x32_bf16(Bt[n][k], At[m][k], acc[ai][bj][m][n], 0, 0, 0); __builtin_amdgcn_s_setprio(0); } while (0)
; #define PG8_WAIT_V(n) asm volatile("s_waitcnt vmcnt(" #n ")" ::: "memory")
; #define PG8_WAIT_L(n) asm volatile("s_waitcnt lgkmcnt(" #n ")" ::: "memory")
; #define PG8_BAR __builtin_amdgcn_s_barrier()
; #define PG8_SCHED __builtin_amdgcn_sched_barrier(0)
; template <class Epi, class Sched, bool ALIGN_EPI = false, bool SP2 = false>
; __device__ __forceinline__ void gemm_phase(PG8_LAS unsigned char* lds, const Gemm g, const Sched& S, const Epi& E) {
;     ...
;             PG8_LDA(At, 1, 1); PG8_STAGE(PG8_SB(1, 0), b3, voffB); PG8_STAGE(PG8_SB(1, 1), b3 + hstep, voffB); PG8_STAGE(PG8_SA(1, 0), a3, voffA);
;             PG8_WAIT_V(8); PG8_WAIT_L(0); PG8_BAR; PG8_MMA(1, 0, At, B0); PG8_MMA(1, 1, At, B1); PG8_BAR; PG8_SCHED;
	s_add_i32 s48, s71, s31
	v_lshl_add_u64 v[190:191], v[190:191], 0, s[16:17]
	s_mov_b32 m0, s48
	ds_read_b128 v[182:185], v149 offset:49152
	ds_read_b128 v[186:189], v149 offset:50176
	ds_read_b128 v[194:197], v149 offset:51200
	ds_read_b128 v[198:201], v149 offset:52224
	ds_read_b128 v[202:205], v149 offset:53248
	ds_read_b128 v[206:209], v149 offset:54272
	ds_read_b128 v[210:213], v149 offset:55296
	ds_read_b128 v[214:217], v149 offset:56320
	global_load_lds_dwordx4 v[190:191], off
	v_lshl_add_u64 v[190:191], v[218:219], 0, s[16:17]
	s_add_i32 m0, s48, 0x2000
	s_add_i32 s48, s72, s31
	global_load_lds_dwordx4 v[190:191], off
	v_lshl_add_u64 v[190:191], v[220:221], 0, s[16:17]
	s_mov_b32 m0, s48
	s_nop 0
	global_load_lds_dwordx4 v[190:191], off
	v_lshl_add_u64 v[190:191], v[222:223], 0, s[16:17]
	s_add_i32 m0, s48, 0x2000
	s_nop 0
	global_load_lds_dwordx4 v[190:191], off
	v_lshl_add_u64 v[190:191], v[224:225], 0, s[16:17]
	s_mov_b32 m0, s54
	s_nop 0
	global_load_lds_dwordx4 v[190:191], off
	v_lshl_add_u64 v[190:191], v[226:227], 0, s[16:17]
	s_mov_b32 m0, s55
	s_nop 0
	global_load_lds_dwordx4 v[190:191], off
	s_waitcnt vmcnt(8)
	s_waitcnt lgkmcnt(0)
	s_barrier
	s_setprio 1
	v_mfma_f32_16x16x32_bf16 v[60:63], v[150:153], v[182:185], v[60:63]
	v_mfma_f32_16x16x32_bf16 v[56:59], v[158:161], v[182:185], v[56:59]
	v_mfma_f32_16x16x32_bf16 v[44:47], v[150:153], v[194:197], v[44:47]
	v_mfma_f32_16x16x32_bf16 v[40:43], v[158:161], v[194:197], v[40:43]
	v_mfma_f32_16x16x32_bf16 v[28:31], v[150:153], v[202:205], v[28:31]
	v_mfma_f32_16x16x32_bf16 v[24:27], v[158:161], v[202:205], v[24:27]
	v_mfma_f32_16x16x32_bf16 v[12:15], v[150:153], v[210:213], v[12:15]
	v_mfma_f32_16x16x32_bf16 v[8:11], v[158:161], v[210:213], v[8:11]
	v_mfma_f32_16x16x32_bf16 v[60:63], v[154:157], v[186:189], v[60:63]
	v_mfma_f32_16x16x32_bf16 v[56:59], v[162:165], v[186:189], v[56:59]
	v_mfma_f32_16x16x32_bf16 v[44:47], v[154:157], v[198:201], v[44:47]
	v_mfma_f32_16x16x32_bf16 v[40:43], v[162:165], v[198:201], v[40:43]
	v_mfma_f32_16x16x32_bf16 v[28:31], v[154:157], v[206:209], v[28:31]
	v_mfma_f32_16x16x32_bf16 v[24:27], v[162:165], v[206:209], v[24:27]
	v_mfma_f32_16x16x32_bf16 v[12:15], v[154:157], v[214:217], v[12:15]
	v_mfma_f32_16x16x32_bf16 v[8:11], v[162:165], v[214:217], v[8:11]
	v_mfma_f32_16x16x32_bf16 v[52:55], v[166:169], v[182:185], v[52:55]
	v_mfma_f32_16x16x32_bf16 v[48:51], v[174:177], v[182:185], v[48:51]
	v_mfma_f32_16x16x32_bf16 v[36:39], v[166:169], v[194:197], v[36:39]
	v_mfma_f32_16x16x32_bf16 v[32:35], v[174:177], v[194:197], v[32:35]
	v_mfma_f32_16x16x32_bf16 v[20:23], v[166:169], v[202:205], v[20:23]
	v_mfma_f32_16x16x32_bf16 v[16:19], v[174:177], v[202:205], v[16:19]
	v_mfma_f32_16x16x32_bf16 v[4:7], v[166:169], v[210:213], v[4:7]
	v_mfma_f32_16x16x32_bf16 v[0:3], v[174:177], v[210:213], v[0:3]
	v_mfma_f32_16x16x32_bf16 v[52:55], v[170:173], v[186:189], v[52:55]
	v_mfma_f32_16x16x32_bf16 v[48:51], v[178:181], v[186:189], v[48:51]
	v_mfma_f32_16x16x32_bf16 v[36:39], v[170:173], v[198:201], v[36:39]
	v_mfma_f32_16x16x32_bf16 v[32:35], v[178:181], v[198:201], v[32:35]
	v_mfma_f32_16x16x32_bf16 v[20:23], v[170:173], v[206:209], v[20:23]
	v_mfma_f32_16x16x32_bf16 v[16:19], v[178:181], v[206:209], v[16:19]
	v_mfma_f32_16x16x32_bf16 v[4:7], v[170:173], v[214:217], v[4:7]
	v_mfma_f32_16x16x32_bf16 v[0:3], v[178:181], v[214:217], v[0:3]
	s_setprio 0
	s_barrier
	s_add_u32 s42, s42, 0x100
	s_addc_u32 s43, s43, 0
	s_add_u32 s68, s68, 0x100
	s_addc_u32 s69, s69, 0
	s_cmp_ge_i32 s70, s56
	s_mov_b32 s48, s70
	s_cbranch_scc0 .LBB0_1221

; #define PG8_STAGE(bufoff, gbase, voff) do { _Pragma("unroll") for (int _i = 0; _i < 2; ++_i) \
;         __builtin_amdgcn_global_load_lds((const unsigned*)((const char*)(gbase) + (voff)[_i]), (PG8_LAS unsigned*)(lds + (bufoff) + ldsw + _i * 8192), 16, 0, 0); } while (0)
; #define PG8_LDA(dst, b, h) do { _Pragma("unroll") for (int m = 0; m < 4; ++m) _Pragma("unroll") for (int k = 0; k < 2; ++k) dst[m][k] = *(const PG8_LAS bf16x8*)(lds + PG8_SA(b, h) + aoff + m * 2048 + k * 1024); } while (0)
; #define PG8_LDB(dst, b, h) do { _Pragma("unroll") for (int n = 0; n < 2; ++n) _Pragma("unroll") for (int k = 0; k < 2; ++k) dst[n][k] = *(const PG8_LAS bf16x8*)(lds + PG8_SB(b, h) + boff + n * 2048 + k * 1024); } while (0)
; #define PG8_MMA(ai, bj, At, Bt) do { __builtin_amdgcn_s_setprio(1); _Pragma("unroll") for (int m = 0; m < 4; ++m) _Pragma("unroll") for (int n = 0; n < 2; ++n) _Pragma("unroll") for (int k = 0; k < 2; ++k) \
;         acc[ai][bj][m][n] = __builtin_amdgcn_mfma_f32_16x16x32_bf16(Bt[n][k], At[m][k], acc[ai][bj][m][n], 0, 0, 0); __builtin_amdgcn_s_setprio(0); } while (0)
; #define PG8_WAIT_V(n) asm volatile("s_waitcnt vmcnt(" #n ")" ::: "memory")
; #define PG8_WAIT_L(n) asm volatile("s_waitcnt lgkmcnt(" #n ")" ::: "memory")
; #define PG8_BAR __builtin_amdgcn_s_barrier()
; #define PG8_SCHED __builtin_amdgcn_sched_barrier(0)
; template <class Epi, class Sched, bool ALIGN_EPI = false, bool SP2 = false>
; __device__ __forceinline__ void gemm_phase(PG8_LAS unsigned char* lds, const Gemm g, const Sched& S, const Epi& E) {
;     ...
;             PG8_LDB(B0, 0, 0); PG8_LDB(B1, 0, 1); PG8_SCHED; PG8_LDA(At, 0, 0); PG8_STAGE(PG8_SA(1, 1), a1 + hstep, voffA);
;             PG8_WAIT_V(8); PG8_WAIT_L(0); PG8_BAR; PG8_MMA(0, 0, At, B0); PG8_MMA(0, 1, At, B1); PG8_BAR; PG8_SCHED;
;             PG8_LDA(At, 0, 1); PG8_STAGE(PG8_SB(0, 0), b2, voffB); PG8_STAGE(PG8_SB(0, 1), b2 + hstep, voffB); PG8_STAGE(PG8_SA(0, 0), a2, voffA);
;             PG8_WAIT_V(8); PG8_WAIT_L(0); PG8_BAR; PG8_MMA(1, 0, At, B0); PG8_MMA(1, 1, At, B1); PG8_BAR; PG8_SCHED;
.LBB0_1253:
	ds_read_b128 v[124:127], v214
	ds_read_b128 v[132:135], v214 offset:1024
	ds_read_b128 v[136:139], v214 offset:2048
	ds_read_b128 v[140:143], v214 offset:3072
	ds_read_b128 v[144:147], v215
	ds_read_b128 v[148:151], v215 offset:1024
	ds_read_b128 v[152:155], v215 offset:2048
	ds_read_b128 v[156:159], v215 offset:3072
	s_add_i32 s55, s26, 2
	s_add_u32 s56, s22, 0x80
	s_addc_u32 s27, s23, 0
	s_cmp_eq_u32 s41, s26
	s_cselect_b32 s26, s4, s56
	s_cselect_b32 s27, s5, s27
	s_cselect_b32 s57, s21, s54
	s_cselect_b32 s56, s20, s53
	v_lshl_add_u64 v[220:221], s[22:23], 0, v[186:187]
	s_add_i32 m0, s29, 0xc000
	ds_read_b128 v[160:163], v216
	ds_read_b128 v[164:167], v216 offset:1024
	ds_read_b128 v[168:171], v216 offset:2048
	ds_read_b128 v[172:175], v216 offset:3072
	ds_read_b128 v[196:199], v216 offset:4096
	ds_read_b128 v[200:203], v216 offset:5120
	ds_read_b128 v[204:207], v216 offset:6144
	ds_read_b128 v[208:211], v216 offset:7168
	global_load_lds_dwordx4 v[220:221], off
	v_lshl_add_u64 v[220:221], s[22:23], 0, v[188:189]
	s_add_i32 m0, s29, 0xe000
	s_nop 0
	global_load_lds_dwordx4 v[220:221], off
	s_waitcnt vmcnt(8)
	s_waitcnt lgkmcnt(0)
	s_barrier
	s_setprio 1
	v_mfma_f32_16x16x32_bf16 v[128:131], v[124:127], v[160:163], v[128:131]
	v_mfma_f32_16x16x32_bf16 v[120:123], v[136:139], v[160:163], v[120:123]
	v_mfma_f32_16x16x32_bf16 v[108:111], v[124:127], v[168:171], v[108:111]
	v_mfma_f32_16x16x32_bf16 v[104:107], v[136:139], v[168:171], v[104:107]
	v_mfma_f32_16x16x32_bf16 v[92:95], v[124:127], v[196:199], v[92:95]
	v_mfma_f32_16x16x32_bf16 v[88:91], v[136:139], v[196:199], v[88:91]
	v_mfma_f32_16x16x32_bf16 v[76:79], v[124:127], v[204:207], v[76:79]
	v_mfma_f32_16x16x32_bf16 v[72:75], v[136:139], v[204:207], v[72:75]
	v_mfma_f32_16x16x32_bf16 v[128:131], v[132:135], v[164:167], v[128:131]
	v_mfma_f32_16x16x32_bf16 v[120:123], v[140:143], v[164:167], v[120:123]
	v_mfma_f32_16x16x32_bf16 v[108:111], v[132:135], v[172:175], v[108:111]
	v_mfma_f32_16x16x32_bf16 v[104:107], v[140:143], v[172:175], v[104:107]
	v_mfma_f32_16x16x32_bf16 v[92:95], v[132:135], v[200:203], v[92:95]
	v_mfma_f32_16x16x32_bf16 v[88:91], v[140:143], v[200:203], v[88:91]
	v_mfma_f32_16x16x32_bf16 v[76:79], v[132:135], v[208:211], v[76:79]
	v_mfma_f32_16x16x32_bf16 v[72:75], v[140:143], v[208:211], v[72:75]
	v_mfma_f32_16x16x32_bf16 v[116:119], v[144:147], v[160:163], v[116:119]
	v_mfma_f32_16x16x32_bf16 v[112:115], v[152:155], v[160:163], v[112:115]
	v_mfma_f32_16x16x32_bf16 v[100:103], v[144:147], v[168:171], v[100:103]
	v_mfma_f32_16x16x32_bf16 v[96:99], v[152:155], v[168:171], v[96:99]
	v_mfma_f32_16x16x32_bf16 v[84:87], v[144:147], v[196:199], v[84:87]
	v_mfma_f32_16x16x32_bf16 v[80:83], v[152:155], v[196:199], v[80:83]
	v_mfma_f32_16x16x32_bf16 v[68:71], v[144:147], v[204:207], v[68:71]
	v_mfma_f32_16x16x32_bf16 v[64:67], v[152:155], v[204:207], v[64:67]
	v_mfma_f32_16x16x32_bf16 v[116:119], v[148:151], v[164:167], v[116:119]
	v_mfma_f32_16x16x32_bf16 v[112:115], v[156:159], v[164:167], v[112:115]
	v_mfma_f32_16x16x32_bf16 v[100:103], v[148:151], v[172:175], v[100:103]
	v_mfma_f32_16x16x32_bf16 v[96:99], v[156:159], v[172:175], v[96:99]
	v_mfma_f32_16x16x32_bf16 v[84:87], v[148:151], v[200:203], v[84:87]
	v_mfma_f32_16x16x32_bf16 v[80:83], v[156:159], v[200:203], v[80:83]
	v_mfma_f32_16x16x32_bf16 v[68:71], v[148:151], v[208:211], v[68:71]
	v_mfma_f32_16x16x32_bf16 v[64:67], v[156:159], v[208:211], v[64:67]
	s_setprio 0
	s_barrier
	s_add_i32 s58, s43, s28
	v_lshl_add_u64 v[220:221], s[56:57], 0, v[178:179]
	s_mov_b32 m0, s58
	ds_read_b128 v[160:163], v216 offset:16384
	ds_read_b128 v[164:167], v216 offset:17408
	ds_read_b128 v[168:171], v216 offset:18432
	ds_read_b128 v[172:175], v216 offset:19456
	ds_read_b128 v[196:199], v216 offset:20480
	ds_read_b128 v[200:203], v216 offset:21504
	ds_read_b128 v[204:207], v216 offset:22528
	ds_read_b128 v[208:211], v216 offset:23552
	global_load_lds_dwordx4 v[220:221], off
	s_add_i32 m0, s58, 0x2000
	v_lshl_add_u64 v[222:223], s[56:57], 0, v[182:183]
	s_add_u32 s56, s56, s8
	s_addc_u32 s57, s57, s9
	s_add_i32 s58, s48, s28
	global_load_lds_dwordx4 v[222:223], off
	v_lshl_add_u64 v[224:225], s[56:57], 0, v[178:179]
	s_mov_b32 m0, s58
	v_lshl_add_u64 v[226:227], s[56:57], 0, v[182:183]
	global_load_lds_dwordx4 v[224:225], off
	s_add_i32 m0, s58, 0x2000
	v_lshl_add_u64 v[228:229], s[26:27], 0, v[176:177]
	global_load_lds_dwordx4 v[226:227], off
	s_mov_b32 m0, s29
	v_lshl_add_u64 v[230:231], s[26:27], 0, v[180:181]
	global_load_lds_dwordx4 v[228:229], off
	s_mov_b32 m0, s31
	s_nop 0
	global_load_lds_dwordx4 v[230:231], off
	s_waitcnt vmcnt(8)
	s_waitcnt lgkmcnt(0)
	s_barrier
; #define PG8_STAGE(bufoff, gbase, voff) do { _Pragma("unroll") for (int _i = 0; _i < 2; ++_i) \
;         __builtin_amdgcn_global_load_lds((const unsigned*)((const char*)(gbase) + (voff)[_i]), (PG8_LAS unsigned*)(lds + (bufoff) + ldsw + _i * 8192), 16, 0, 0); } while (0)
; #define PG8_LDA(dst, b, h) do { _Pragma("unroll") for (int m = 0; m < 4; ++m) _Pragma("unroll") for (int k = 0; k < 2; ++k) dst[m][k] = *(const PG8_LAS bf16x8*)(lds + PG8_SA(b, h) + aoff + m * 2048 + k * 1024); } while (0)
; #define PG8_LDB(dst, b, h) do { _Pragma("unroll") for (int n = 0; n < 2; ++n) _Pragma("unroll") for (int k = 0; k < 2; ++k) dst[n][k] = *(const PG8_LAS bf16x8*)(lds + PG8_SB(b, h) + boff + n * 2048 + k * 1024); } while (0)
; #define PG8_MMA(ai, bj, At, Bt) do { __builtin_amdgcn_s_setprio(1); _Pragma("unroll") for (int m = 0; m < 4; ++m) _Pragma("unroll") for (int n = 0; n < 2; ++n) _Pragma("unroll") for (int k = 0; k < 2; ++k) \
;         acc[ai][bj][m][n] = __builtin_amdgcn_mfma_f32_16x16x32_bf16(Bt[n][k], At[m][k], acc[ai][bj][m][n], 0, 0, 0); __builtin_amdgcn_s_setprio(0); } while (0)
; #define PG8_WAIT_V(n) asm volatile("s_waitcnt vmcnt(" #n ")" ::: "memory")
; #define PG8_WAIT_L(n) asm volatile("s_waitcnt lgkmcnt(" #n ")" ::: "memory")
; #define PG8_BAR __builtin_amdgcn_s_barrier()
; #define PG8_SCHED __builtin_amdgcn_sched_barrier(0)
; template <class Epi, class Sched, bool ALIGN_EPI = false, bool SP2 = false>
; __device__ __forceinline__ void gemm_phase(PG8_LAS unsigned char* lds, const Gemm g, const Sched& S, const Epi& E) {
;     ...
;             PG8_WAIT_V(8); PG8_WAIT_L(0); PG8_BAR; PG8_MMA(1, 0, At, B0); PG8_MMA(1, 1, At, B1); PG8_BAR; PG8_SCHED;
;             PG8_LDB(B0, 1, 0); PG8_LDB(B1, 1, 1); PG8_SCHED; PG8_LDA(At, 1, 0); PG8_STAGE(PG8_SA(0, 1), a2 + hstep, voffA);
;             PG8_WAIT_V(8); PG8_WAIT_L(0); PG8_BAR; PG8_MMA(0, 0, At, B0); PG8_MMA(0, 1, At, B1); PG8_BAR; PG8_SCHED;
	s_setprio 1
	v_mfma_f32_16x16x32_bf16 v[60:63], v[124:127], v[160:163], v[60:63]
	v_mfma_f32_16x16x32_bf16 v[56:59], v[136:139], v[160:163], v[56:59]
	v_mfma_f32_16x16x32_bf16 v[44:47], v[124:127], v[168:171], v[44:47]
	v_mfma_f32_16x16x32_bf16 v[40:43], v[136:139], v[168:171], v[40:43]
	v_mfma_f32_16x16x32_bf16 v[28:31], v[124:127], v[196:199], v[28:31]
	v_mfma_f32_16x16x32_bf16 v[24:27], v[136:139], v[196:199], v[24:27]
	v_mfma_f32_16x16x32_bf16 v[12:15], v[124:127], v[204:207], v[12:15]
	v_mfma_f32_16x16x32_bf16 v[8:11], v[136:139], v[204:207], v[8:11]
	v_mfma_f32_16x16x32_bf16 v[60:63], v[132:135], v[164:167], v[60:63]
	v_mfma_f32_16x16x32_bf16 v[56:59], v[140:143], v[164:167], v[56:59]
	v_mfma_f32_16x16x32_bf16 v[44:47], v[132:135], v[172:175], v[44:47]
	v_mfma_f32_16x16x32_bf16 v[40:43], v[140:143], v[172:175], v[40:43]
	v_mfma_f32_16x16x32_bf16 v[28:31], v[132:135], v[200:203], v[28:31]
	v_mfma_f32_16x16x32_bf16 v[24:27], v[140:143], v[200:203], v[24:27]
	v_mfma_f32_16x16x32_bf16 v[12:15], v[132:135], v[208:211], v[12:15]
	v_mfma_f32_16x16x32_bf16 v[8:11], v[140:143], v[208:211], v[8:11]
	v_mfma_f32_16x16x32_bf16 v[52:55], v[144:147], v[160:163], v[52:55]
	v_mfma_f32_16x16x32_bf16 v[48:51], v[152:155], v[160:163], v[48:51]
	v_mfma_f32_16x16x32_bf16 v[36:39], v[144:147], v[168:171], v[36:39]
	v_mfma_f32_16x16x32_bf16 v[32:35], v[152:155], v[168:171], v[32:35]
	v_mfma_f32_16x16x32_bf16 v[20:23], v[144:147], v[196:199], v[20:23]
	v_mfma_f32_16x16x32_bf16 v[16:19], v[152:155], v[196:199], v[16:19]
	v_mfma_f32_16x16x32_bf16 v[4:7], v[144:147], v[204:207], v[4:7]
	v_mfma_f32_16x16x32_bf16 v[0:3], v[152:155], v[204:207], v[0:3]
	v_mfma_f32_16x16x32_bf16 v[52:55], v[148:151], v[164:167], v[52:55]
	v_mfma_f32_16x16x32_bf16 v[48:51], v[156:159], v[164:167], v[48:51]
	v_mfma_f32_16x16x32_bf16 v[36:39], v[148:151], v[172:175], v[36:39]
	v_mfma_f32_16x16x32_bf16 v[32:35], v[156:159], v[172:175], v[32:35]
	v_mfma_f32_16x16x32_bf16 v[20:23], v[148:151], v[200:203], v[20:23]
	v_mfma_f32_16x16x32_bf16 v[16:19], v[156:159], v[200:203], v[16:19]
	v_mfma_f32_16x16x32_bf16 v[4:7], v[148:151], v[208:211], v[4:7]
	v_mfma_f32_16x16x32_bf16 v[0:3], v[156:159], v[208:211], v[0:3]
	s_setprio 0
	s_barrier
	s_add_i32 s56, 0, 0x18000
	s_add_i32 s57, 0, 0x1c000
	v_add_u32_e32 v140, s56, v212
	v_add_u32_e32 v156, s57, v212
	ds_read_b128 v[124:127], v140
	ds_read_b128 v[132:135], v140 offset:1024
	ds_read_b128 v[136:139], v140 offset:2048
	ds_read_b128 v[140:143], v140 offset:3072
	ds_read_b128 v[144:147], v156
	ds_read_b128 v[148:151], v156 offset:1024
	ds_read_b128 v[152:155], v156 offset:2048
	ds_read_b128 v[156:159], v156 offset:3072
	s_add_u32 s26, s26, s8
	s_addc_u32 s27, s27, s9
	s_mov_b32 m0, s33
	v_lshl_add_u64 v[232:233], s[26:27], 0, v[176:177]
	ds_read_b128 v[160:163], v216 offset:32768
	ds_read_b128 v[164:167], v216 offset:33792
	ds_read_b128 v[168:171], v216 offset:34816
	ds_read_b128 v[172:175], v216 offset:35840
	ds_read_b128 v[196:199], v216 offset:36864
	ds_read_b128 v[200:203], v216 offset:37888
	ds_read_b128 v[204:207], v216 offset:38912
	ds_read_b128 v[208:211], v216 offset:39936
	global_load_lds_dwordx4 v[232:233], off
	v_lshl_add_u64 v[232:233], s[26:27], 0, v[180:181]
	s_mov_b32 m0, s36
	s_nop 0
	global_load_lds_dwordx4 v[232:233], off
	s_waitcnt vmcnt(8)
	s_waitcnt lgkmcnt(0)
	s_barrier
	s_setprio 1
	v_mfma_f32_16x16x32_bf16 v[128:131], v[124:127], v[160:163], v[128:131]
	v_mfma_f32_16x16x32_bf16 v[120:123], v[136:139], v[160:163], v[120:123]
	v_mfma_f32_16x16x32_bf16 v[108:111], v[124:127], v[168:171], v[108:111]
	v_mfma_f32_16x16x32_bf16 v[104:107], v[136:139], v[168:171], v[104:107]
	v_mfma_f32_16x16x32_bf16 v[92:95], v[124:127], v[196:199], v[92:95]
	v_mfma_f32_16x16x32_bf16 v[88:91], v[136:139], v[196:199], v[88:91]
	v_mfma_f32_16x16x32_bf16 v[76:79], v[124:127], v[204:207], v[76:79]
	v_mfma_f32_16x16x32_bf16 v[72:75], v[136:139], v[204:207], v[72:75]
	v_mfma_f32_16x16x32_bf16 v[128:131], v[132:135], v[164:167], v[128:131]
	v_mfma_f32_16x16x32_bf16 v[120:123], v[140:143], v[164:167], v[120:123]
	v_mfma_f32_16x16x32_bf16 v[108:111], v[132:135], v[172:175], v[108:111]
	v_mfma_f32_16x16x32_bf16 v[104:107], v[140:143], v[172:175], v[104:107]
	v_mfma_f32_16x16x32_bf16 v[92:95], v[132:135], v[200:203], v[92:95]
	v_mfma_f32_16x16x32_bf16 v[88:91], v[140:143], v[200:203], v[88:91]
	v_mfma_f32_16x16x32_bf16 v[76:79], v[132:135], v[208:211], v[76:79]
	v_mfma_f32_16x16x32_bf16 v[72:75], v[140:143], v[208:211], v[72:75]
	v_mfma_f32_16x16x32_bf16 v[116:119], v[144:147], v[160:163], v[116:119]
	v_mfma_f32_16x16x32_bf16 v[112:115], v[152:155], v[160:163], v[112:115]
	v_mfma_f32_16x16x32_bf16 v[100:103], v[144:147], v[168:171], v[100:103]
	v_mfma_f32_16x16x32_bf16 v[96:99], v[152:155], v[168:171], v[96:99]
	v_mfma_f32_16x16x32_bf16 v[84:87], v[144:147], v[196:199], v[84:87]
	v_mfma_f32_16x16x32_bf16 v[80:83], v[152:155], v[196:199], v[80:83]
	v_mfma_f32_16x16x32_bf16 v[68:71], v[144:147], v[204:207], v[68:71]
	v_mfma_f32_16x16x32_bf16 v[64:67], v[152:155], v[204:207], v[64:67]
	v_mfma_f32_16x16x32_bf16 v[116:119], v[148:151], v[164:167], v[116:119]
	v_mfma_f32_16x16x32_bf16 v[112:115], v[156:159], v[164:167], v[112:115]
	v_mfma_f32_16x16x32_bf16 v[100:103], v[148:151], v[172:175], v[100:103]
	v_mfma_f32_16x16x32_bf16 v[96:99], v[156:159], v[172:175], v[96:99]
	v_mfma_f32_16x16x32_bf16 v[84:87], v[148:151], v[200:203], v[84:87]
	v_mfma_f32_16x16x32_bf16 v[80:83], v[156:159], v[200:203], v[80:83]
	v_mfma_f32_16x16x32_bf16 v[68:71], v[148:151], v[208:211], v[68:71]
	v_mfma_f32_16x16x32_bf16 v[64:67], v[156:159], v[208:211], v[64:67]
	s_setprio 0
	s_barrier
; #define PG8_STAGE(bufoff, gbase, voff) do { _Pragma("unroll") for (int _i = 0; _i < 2; ++_i) \
;         __builtin_amdgcn_global_load_lds((const unsigned*)((const char*)(gbase) + (voff)[_i]), (PG8_LAS unsigned*)(lds + (bufoff) + ldsw + _i * 8192), 16, 0, 0); } while (0)
; #define PG8_LDA(dst, b, h) do { _Pragma("unroll") for (int m = 0; m < 4; ++m) _Pragma("unroll") for (int k = 0; k < 2; ++k) dst[m][k] = *(const PG8_LAS bf16x8*)(lds + PG8_SA(b, h) + aoff + m * 2048 + k * 1024); } while (0)
; #define PG8_MMA(ai, bj, At, Bt) do { __builtin_amdgcn_s_setprio(1); _Pragma("unroll") for (int m = 0; m < 4; ++m) _Pragma("unroll") for (int n = 0; n < 2; ++n) _Pragma("unroll") for (int k = 0; k < 2; ++k) \
;         acc[ai][bj][m][n] = __builtin_amdgcn_mfma_f32_16x16x32_bf16(Bt[n][k], At[m][k], acc[ai][bj][m][n], 0, 0, 0); __builtin_amdgcn_s_setprio(0); } while (0)
; #define PG8_WAIT_V(n) asm volatile("s_waitcnt vmcnt(" #n ")" ::: "memory")
; #define PG8_WAIT_L(n) asm volatile("s_waitcnt lgkmcnt(" #n ")" ::: "memory")
; #define PG8_BAR __builtin_amdgcn_s_barrier()
; #define PG8_SCHED __builtin_amdgcn_sched_barrier(0)
; template <class Epi, class Sched, bool ALIGN_EPI = false, bool SP2 = false>
; __device__ __forceinline__ void gemm_phase(PG8_LAS unsigned char* lds, const Gemm g, const Sched& S, const Epi& E) {
;     ...
;             PG8_LDA(At, 1, 1); PG8_STAGE(PG8_SB(1, 0), b3, voffB); PG8_STAGE(PG8_SB(1, 1), b3 + hstep, voffB); PG8_STAGE(PG8_SA(1, 0), a3, voffA);
;             PG8_WAIT_V(8); PG8_WAIT_L(0); PG8_BAR; PG8_MMA(1, 0, At, B0); PG8_MMA(1, 1, At, B1); PG8_BAR; PG8_SCHED;
	s_add_i32 s26, s56, s28
	v_lshl_add_u64 v[220:221], v[220:221], 0, s[14:15]
	s_mov_b32 m0, s26
	ds_read_b128 v[160:163], v216 offset:49152
	ds_read_b128 v[164:167], v216 offset:50176
	ds_read_b128 v[168:171], v216 offset:51200
	ds_read_b128 v[172:175], v216 offset:52224
	ds_read_b128 v[196:199], v216 offset:53248
	ds_read_b128 v[200:203], v216 offset:54272
	ds_read_b128 v[204:207], v216 offset:55296
	ds_read_b128 v[208:211], v216 offset:56320
	global_load_lds_dwordx4 v[220:221], off
	v_lshl_add_u64 v[220:221], v[222:223], 0, s[14:15]
	s_add_i32 m0, s26, 0x2000
	s_add_i32 s26, s57, s28
	global_load_lds_dwordx4 v[220:221], off
	v_lshl_add_u64 v[220:221], v[224:225], 0, s[14:15]
	s_mov_b32 m0, s26
	s_nop 0
	global_load_lds_dwordx4 v[220:221], off
	v_lshl_add_u64 v[220:221], v[226:227], 0, s[14:15]
	s_add_i32 m0, s26, 0x2000
	s_nop 0
	global_load_lds_dwordx4 v[220:221], off
	v_lshl_add_u64 v[220:221], v[228:229], 0, s[14:15]
	s_mov_b32 m0, s38
	s_nop 0
	global_load_lds_dwordx4 v[220:221], off
	v_lshl_add_u64 v[220:221], v[230:231], 0, s[14:15]
	s_mov_b32 m0, s39
	s_nop 0
	global_load_lds_dwordx4 v[220:221], off
	s_waitcnt vmcnt(8)
	s_waitcnt lgkmcnt(0)
	s_barrier
	s_setprio 1
	v_mfma_f32_16x16x32_bf16 v[60:63], v[124:127], v[160:163], v[60:63]
	v_mfma_f32_16x16x32_bf16 v[56:59], v[136:139], v[160:163], v[56:59]
	v_mfma_f32_16x16x32_bf16 v[44:47], v[124:127], v[168:171], v[44:47]
	v_mfma_f32_16x16x32_bf16 v[40:43], v[136:139], v[168:171], v[40:43]
	v_mfma_f32_16x16x32_bf16 v[28:31], v[124:127], v[196:199], v[28:31]
	v_mfma_f32_16x16x32_bf16 v[24:27], v[136:139], v[196:199], v[24:27]
	v_mfma_f32_16x16x32_bf16 v[12:15], v[124:127], v[204:207], v[12:15]
	v_mfma_f32_16x16x32_bf16 v[8:11], v[136:139], v[204:207], v[8:11]
	v_mfma_f32_16x16x32_bf16 v[60:63], v[132:135], v[164:167], v[60:63]
	v_mfma_f32_16x16x32_bf16 v[56:59], v[140:143], v[164:167], v[56:59]
	v_mfma_f32_16x16x32_bf16 v[44:47], v[132:135], v[172:175], v[44:47]
	v_mfma_f32_16x16x32_bf16 v[40:43], v[140:143], v[172:175], v[40:43]
	v_mfma_f32_16x16x32_bf16 v[28:31], v[132:135], v[200:203], v[28:31]
	v_mfma_f32_16x16x32_bf16 v[24:27], v[140:143], v[200:203], v[24:27]
	v_mfma_f32_16x16x32_bf16 v[12:15], v[132:135], v[208:211], v[12:15]
	v_mfma_f32_16x16x32_bf16 v[8:11], v[140:143], v[208:211], v[8:11]
	v_mfma_f32_16x16x32_bf16 v[52:55], v[144:147], v[160:163], v[52:55]
	v_mfma_f32_16x16x32_bf16 v[48:51], v[152:155], v[160:163], v[48:51]
	v_mfma_f32_16x16x32_bf16 v[36:39], v[144:147], v[168:171], v[36:39]
	v_mfma_f32_16x16x32_bf16 v[32:35], v[152:155], v[168:171], v[32:35]
	v_mfma_f32_16x16x32_bf16 v[20:23], v[144:147], v[196:199], v[20:23]
	v_mfma_f32_16x16x32_bf16 v[16:19], v[152:155], v[196:199], v[16:19]
	v_mfma_f32_16x16x32_bf16 v[4:7], v[144:147], v[204:207], v[4:7]
	v_mfma_f32_16x16x32_bf16 v[0:3], v[152:155], v[204:207], v[0:3]
	v_mfma_f32_16x16x32_bf16 v[52:55], v[148:151], v[164:167], v[52:55]
	v_mfma_f32_16x16x32_bf16 v[48:51], v[156:159], v[164:167], v[48:51]
	v_mfma_f32_16x16x32_bf16 v[36:39], v[148:151], v[172:175], v[36:39]
	v_mfma_f32_16x16x32_bf16 v[32:35], v[156:159], v[172:175], v[32:35]
	v_mfma_f32_16x16x32_bf16 v[20:23], v[148:151], v[200:203], v[20:23]
	v_mfma_f32_16x16x32_bf16 v[16:19], v[156:159], v[200:203], v[16:19]
	v_mfma_f32_16x16x32_bf16 v[4:7], v[148:151], v[208:211], v[4:7]
	v_mfma_f32_16x16x32_bf16 v[0:3], v[156:159], v[208:211], v[0:3]
	s_setprio 0
	s_barrier
	s_add_u32 s22, s22, 0x100
	s_addc_u32 s23, s23, 0
	s_add_u32 s53, s53, 0x100
	s_addc_u32 s54, s54, 0
	s_cmp_ge_i32 s55, s40
	s_mov_b32 s26, s55
	s_cbranch_scc0 .LBB0_1253
